# attention: one workgroup barrier per two KV tiles (two tiles staged per barrier on the same 4+4-slot LDS ring)
# baseline (speedup 1.0000x reference)
; __device__ __forceinline__ int v_st(int k, int c) { const int kk = (k & ~0xC) | ((k & 4) << 1) | ((k & 8) >> 1); return ((kk >> 3) * 4 + (c >> 5)) * 512 + ((kk & 7) * 32 + (c & 31)) * 2; }
; __device__ __forceinline__ int v_rd_base(int lane) { return ((lane & 3) << 3) | (((lane >> 2) & 3) << 6) | (((lane >> 4) & 1) << 5) | (((lane >> 5) & 1) << 8); }
; #define SLOAD(i, k0) do { sr_[i].vs0 = St::ld8(&Vh[(long)((k0) + sr) * LDK + sc]); sr_[i].vs1 = St::ld8(&Vh[(long)((k0) + 32 + sr) * LDK + sc]); \
;     sr_[i].ks0 = St::ld8(&Kh[(long)((k0) + sr) * LDK + sc]); sr_[i].ks1 = St::ld8(&Kh[(long)((k0) + 32 + sr) * LDK + sc]); } while (0)
; template <typename TQ> ...
;     ...
;   const int tid = tid_, wid = __builtin_amdgcn_readfirstlane(tid >> 6), lane = tid & 63, r32 = lane & 31, hi = lane >> 5;
;   bf16* V_lds = (bf16*)lds; bf16* K_lds = (bf16*)(lds + 2 * SHM_V);
;   float* ws = (float*)(lds + 2 * SHM_V + 2 * SHM_K) + wid * 64; float* li_l = ws;
;   float l_reg = 0; f32x16 o[4] = {}; bf16x8 qr[8];
;   const TQ* Qw = Qb + (long)(wid * QBLK + r32) * LDQ + hi * 8;
; #pragma unroll
;   for (int d0 = 0; d0 < 8; ++d0) qr[d0] = SQ::tobf(SQ::ld8(Qw + d0 * 16));
;   const int sr = tid >> 4, sc = (tid & 15) * 8, vst0 = v_st(sr, sc), vst1 = v_st(32 + sr, sc);
;   const int vb0 = (int)(uintptr_t)V_lds + v_rd_base(lane);
;   struct { typename St::T vs0, vs1, ks0, ks1; } sr_[SDEPTH];
;     ...
;   constexpr int SE = 0, SO = SDEPTH - 1;
;   SLOAD(SE, 0);
; __global__ void __launch_bounds__(NTHR, 2) fwd_megakernel(KArgs a) {
;     ...
;         for (int i = 0; i < upb; ++i) {
;             const int unit = vcu * upb + i; if (unit >= 512) break;
;             const int grp = unit >> 7, rem = unit & 127, gq = rem >> 5, qb = rem & 31, b = grp >> 1, kvh = grp & 1, h = kvh * 4 + gq;
;             const size_t qoff = ((size_t)(b * SEQ + qb * 256)) * DM + h * 128, koff = (size_t)b * SKV * 256 + kvh * 128;
;             att::attn_dense_body<att::bf16>(Q + qoff, Kb + koff, Vb + koff, O + qoff, SKV, (char*)lds_raw, mC, a.g_q, (const float*)(ws + WS_ROPE), (const float*)(ws + WS_ROPE) + 4096, qb * 256);
.LBB0_819:
	s_add_i32 s12, s74, s73
	s_cmpk_gt_i32 s12, 0x1ff
	s_mov_b64 s[0:1], -1
	s_cbranch_scc1 .LBB0_818
	s_lshl_b32 s0, s94, 1
	s_ashr_i32 s96, s12, 8
	s_lshl_b32 s1, s12, 8
	s_and_b32 s95, s0, 0x100
	s_lshl_b32 s0, s96, 13
	s_and_b32 s33, s1, 0x1f00
	s_bfe_u32 s15, s12, 0x10007
	s_or_b32 s0, s0, s33
	s_lshl_b32 s12, s12, 2
	s_ashr_i32 s1, s0, 31
	s_lshl_b32 s13, s15, 9
	s_and_b32 s12, s12, 0x180
	s_lshl_b64 s[0:1], s[0:1], 10
	s_or_b32 s12, s13, s12
	s_or_b32 s0, s0, s12
	s_mul_i32 s12, s96, 0x210000
	s_lshl_b32 s15, s15, 7
	s_or_b32 s12, s12, s15
	s_lshl_b64 s[48:49], s[0:1], 1
	s_mul_hi_i32 s13, s96, 0x210000
	s_add_u32 s0, s20, s48
	s_addc_u32 s1, s21, s49
	s_lshl_b64 s[12:13], s[12:13], 1
	s_add_u32 s54, s69, s12
	s_addc_u32 s55, s70, s13
	v_mov_b32_e32 v114, v0
	s_add_u32 s64, s67, s12
	s_addc_u32 s65, s68, s13
	v_readfirstlane_b32 s53, v114
	s_lshr_b32 s15, s53, 6
	s_lshl_b32 s80, s15, 11
	s_add_u32 s79, s80, 0x10000
	s_lshl_b32 s52, s15, 5
	s_lshl_b32 s12, s15, 3
	v_and_b32_e32 v1, 63, v0
	v_and_b32_e32 v16, 15, v1
	v_lshrrev_b32_e32 v17, 4, v1
	v_add_u32_e32 v12, s12, v17
	v_and_b32_e32 v6, 15, v12
	v_xor_b32_e32 v6, v6, v16
	v_lshlrev_b32_e32 v6, 4, v6
	v_lshl_or_b32 v246, v12, 9, v6
	v_and_b32_e32 v6, 7, v12
	v_lshrrev_b32_e32 v7, 1, v16
	v_xor_b32_e32 v6, v6, v7
	v_and_b32_e32 v7, 1, v16
	v_lshl_or_b32 v6, v6, 1, v7
	v_lshlrev_b32_e32 v6, 4, v6
	v_lshl_or_b32 v248, v12, 9, v6
	v_add_u32_e32 v12, s12, v17
	v_add_u32_e32 v12, 4, v12
	v_and_b32_e32 v6, 15, v12
	v_xor_b32_e32 v6, v6, v16
	v_lshlrev_b32_e32 v6, 4, v6
	v_lshl_or_b32 v247, v12, 9, v6
	v_and_b32_e32 v6, 7, v12
	v_lshrrev_b32_e32 v7, 1, v16
	v_xor_b32_e32 v6, v6, v7
	v_and_b32_e32 v7, 1, v16
	v_lshl_or_b32 v6, v6, 1, v7
	v_lshlrev_b32_e32 v6, 4, v6
	v_lshl_or_b32 v249, v12, 9, v6
	v_add_u32_e32 v6, s52, v16
	v_lshlrev_b32_e32 v6, 11, v6
	v_lshl_or_b32 v13, v17, 4, v6
	v_add_u32_e32 v14, 0x8000, v13
	global_load_dwordx4 v[146:149], v13, s[0:1] offset:0
	global_load_dwordx4 v[150:153], v13, s[0:1] offset:64
	global_load_dwordx4 v[154:157], v13, s[0:1] offset:128
	global_load_dwordx4 v[158:161], v13, s[0:1] offset:192
	global_load_dwordx4 v[162:165], v14, s[0:1] offset:0
	global_load_dwordx4 v[166:169], v14, s[0:1] offset:64
	global_load_dwordx4 v[170:173], v14, s[0:1] offset:128
	global_load_dwordx4 v[174:177], v14, s[0:1] offset:192
	v_lshlrev_b32_e32 v15, 5, v17
	global_load_dwordx4 v[18:21], v15, s[26:27] offset:0
	global_load_dwordx4 v[22:25], v15, s[26:27] offset:16
	global_load_dwordx4 v[26:29], v15, s[26:27] offset:128
	global_load_dwordx4 v[30:33], v15, s[26:27] offset:144
	global_load_dwordx4 v[34:37], v15, s[26:27] offset:256
	global_load_dwordx4 v[38:41], v15, s[26:27] offset:272
	global_load_dwordx4 v[42:45], v15, s[26:27] offset:384
	global_load_dwordx4 v[46:49], v15, s[26:27] offset:400
	s_add_u32 s13, s33, s52
	s_lshr_b32 s13, s13, 6
	s_lshl_b32 s13, s13, 7
	v_add_u32_e32 v200, s13, v15
	global_load_dwordx4 v[82:85], v200, s[4:5] offset:0
	global_load_dwordx4 v[90:93], v200, s[6:7] offset:0
	global_load_dwordx4 v[86:89], v200, s[4:5] offset:16
	global_load_dwordx4 v[94:97], v200, s[6:7] offset:16
	v_add_u32_e32 v6, s52, v16
	v_and_b32_e32 v6, 63, v6
	v_lshl_or_b32 v200, v6, 7, v15
	global_load_dwordx4 v[98:101], v200, s[4:5] offset:0
	global_load_dwordx4 v[106:109], v200, s[6:7] offset:0
	global_load_dwordx4 v[102:105], v200, s[4:5] offset:16
	global_load_dwordx4 v[110:113], v200, s[6:7] offset:16
	v_add_u32_e32 v6, s52, v16
	v_add_u32_e32 v6, 16, v6
	v_and_b32_e32 v6, 63, v6
	v_lshl_or_b32 v200, v6, 7, v15
	global_load_dwordx4 v[114:117], v200, s[4:5] offset:0
	global_load_dwordx4 v[122:125], v200, s[6:7] offset:0
	global_load_dwordx4 v[118:121], v200, s[4:5] offset:16
	global_load_dwordx4 v[126:129], v200, s[6:7] offset:16
	s_mov_b32 s98, s54
	s_mov_b32 s99, s55
	s_mov_b32 s100, s64
	s_mov_b32 s101, s65
	s_add_u32 m0, s79, 0
	s_nop 0
	global_load_lds_dwordx4 v246, s[98:99]
	s_add_u32 m0, s79, 1024
	s_nop 0
	global_load_lds_dwordx4 v247, s[98:99]
	s_add_u32 m0, s80, 0
	s_nop 0
	global_load_lds_dwordx4 v248, s[100:101]
	s_add_u32 m0, s80, 1024
	s_nop 0
	global_load_lds_dwordx4 v249, s[100:101]
	s_add_u32 s98, s98, 0x8000
	s_addc_u32 s99, s99, 0
	s_add_u32 s100, s100, 0x8000
	s_addc_u32 s101, s101, 0
	s_add_u32 m0, s79, 16384
	s_nop 0
	global_load_lds_dwordx4 v246, s[98:99]
	s_add_u32 m0, s79, 17408
	s_nop 0
	global_load_lds_dwordx4 v247, s[98:99]
	s_add_u32 m0, s80, 16384
	s_nop 0
	global_load_lds_dwordx4 v248, s[100:101]
	s_add_u32 m0, s80, 17408
	s_nop 0
	global_load_lds_dwordx4 v249, s[100:101]
	s_add_u32 s98, s98, 0x8000
	s_addc_u32 s99, s99, 0
	s_add_u32 s100, s100, 0x8000
	s_addc_u32 s101, s101, 0
	s_add_u32 m0, s79, 32768
	s_nop 0
	global_load_lds_dwordx4 v246, s[98:99]
	s_add_u32 m0, s79, 33792
	s_nop 0
	global_load_lds_dwordx4 v247, s[98:99]
	s_add_u32 m0, s80, 32768
	s_nop 0
	global_load_lds_dwordx4 v248, s[100:101]
	s_add_u32 m0, s80, 33792
	s_nop 0
	global_load_lds_dwordx4 v249, s[100:101]
	s_add_u32 s98, s98, 0x8000
	s_addc_u32 s99, s99, 0
	s_add_u32 m0, s79, 49152
	s_nop 0
	global_load_lds_dwordx4 v246, s[98:99]
	s_add_u32 m0, s79, 50176
	s_nop 0
	global_load_lds_dwordx4 v247, s[98:99]
	v_lshlrev_b32_e32 v7, 8, v16
	v_or_b32_e32 v6, 0, v17
	v_xor_b32_e32 v6, v6, v16
	v_lshl_or_b32 v6, v6, 4, v7
	v_add_u32_e32 v234, 0x10000, v6
	v_or_b32_e32 v6, 4, v17
	v_xor_b32_e32 v6, v6, v16
	v_lshl_or_b32 v6, v6, 4, v7
	v_add_u32_e32 v235, 0x10000, v6
	v_or_b32_e32 v6, 8, v17
	v_xor_b32_e32 v6, v6, v16
	v_lshl_or_b32 v6, v6, 4, v7
	v_add_u32_e32 v236, 0x10000, v6
	v_or_b32_e32 v6, 12, v17
	v_xor_b32_e32 v6, v6, v16
	v_lshl_or_b32 v6, v6, 4, v7
	v_add_u32_e32 v237, 0x10000, v6
	v_bfe_u32 v6, v1, 2, 2
	v_lshl_or_b32 v6, v17, 2, v6
	v_and_b32_e32 v201, 7, v6
	v_and_b32_e32 v7, 3, v1
	v_lshlrev_b32_e32 v7, 3, v7
	v_lshl_or_b32 v7, v6, 8, v7
	v_xor_b32_e32 v12, 0, v201
	v_lshl_or_b32 v238, v12, 5, v7
	v_xor_b32_e32 v12, 1, v201
	v_lshl_or_b32 v239, v12, 5, v7
	v_xor_b32_e32 v12, 2, v201
	v_lshl_or_b32 v240, v12, 5, v7
	v_xor_b32_e32 v12, 3, v201
	v_lshl_or_b32 v241, v12, 5, v7
	v_xor_b32_e32 v12, 4, v201
	v_lshl_or_b32 v242, v12, 5, v7
	v_xor_b32_e32 v12, 5, v201
	v_lshl_or_b32 v243, v12, 5, v7
	v_xor_b32_e32 v12, 6, v201
	v_lshl_or_b32 v244, v12, 5, v7
	v_xor_b32_e32 v12, 7, v201
	v_lshl_or_b32 v245, v12, 5, v7
	s_waitcnt vmcnt(14)
; #define QF(d, e) __uint_as_float(((unsigned)(unsigned short)qr[d][e]) << 16)
; template <typename TQ> ...
;     ...
;   {
;     float ss = 0.f;
;     ...
; #pragma unroll
;     for (int d0 = 0; d0 < 8; ++d0)
; #pragma unroll
;       for (int e = 0; e < 8; ++e) { const float x = QF(d0, e); ss += x * x; }
;     ss += __shfl_xor(ss, 32);
;     const float rn = (SCALE * 1.4426950408889634f) / sqrtf(ss * (1.0f / 128.0f) + 1e-6f);
;     const int t = trow0 + wid * QBLK + r32; const int prow = t >> 6, pcol = t & 63;
; #pragma unroll
;     for (int hf = 0; hf < 2; ++hf)
; #pragma unroll
;       for (int dd = 0; dd < 2; ++dd) {
;         const int dl = 4 * hf + dd, du = dl + 2;
;         const int f0 = 16 * dd + 8 * hi;
;         const float* cp = rc + (hf ? pcol : prow) * 32 + f0; const float* sp = rsn + (hf ? pcol : prow) * 32 + f0;
;         const float* gl = gq + 16 * dl + 8 * hi; const float* gu = gq + 16 * du + 8 * hi;
;         unsigned wl[4], wu[4];
; #pragma unroll
;         for (int e = 0; e < 8; e += 2) {
;           float o1[2], o2[2];
; #pragma unroll
;           for (int k = 0; k < 2; ++k) { const float x1 = QF(dl, e + k) * rn * gl[e + k], x2 = QF(du, e + k) * rn * gu[e + k]; const float c = cp[e + k], sn = sp[e + k];
;             o1[k] = x1 * c - x2 * sn; o2[k] = x2 * c + x1 * sn; }
;           wl[e >> 1] = cvtpk(o1[0], o1[1]); wu[e >> 1] = cvtpk(o2[0], o2[1]);
;         }
;         u32x4 vl = {wl[0], wl[1], wl[2], wl[3]}, vu = {wu[0], wu[1], wu[2], wu[3]};
;         qr[dl] = *reinterpret_cast<bf16x8*>(&vl); qr[du] = *reinterpret_cast<bf16x8*>(&vu);
;       }
	v_lshlrev_b32_e32 v50, 16, v146
	v_and_b32_e32 v51, 0xffff0000, v146
	v_lshlrev_b32_e32 v52, 16, v147
	v_and_b32_e32 v53, 0xffff0000, v147
	v_lshlrev_b32_e32 v54, 16, v148
	v_and_b32_e32 v55, 0xffff0000, v148
	v_lshlrev_b32_e32 v56, 16, v149
	v_and_b32_e32 v57, 0xffff0000, v149
	v_lshlrev_b32_e32 v58, 16, v150
	v_and_b32_e32 v59, 0xffff0000, v150
	v_lshlrev_b32_e32 v60, 16, v151
	v_and_b32_e32 v61, 0xffff0000, v151
	v_lshlrev_b32_e32 v62, 16, v152
	v_and_b32_e32 v63, 0xffff0000, v152
	v_lshlrev_b32_e32 v64, 16, v153
	v_and_b32_e32 v65, 0xffff0000, v153
	v_lshlrev_b32_e32 v66, 16, v154
	v_and_b32_e32 v67, 0xffff0000, v154
	v_lshlrev_b32_e32 v68, 16, v155
	v_and_b32_e32 v69, 0xffff0000, v155
	v_lshlrev_b32_e32 v70, 16, v156
	v_and_b32_e32 v71, 0xffff0000, v156
	v_lshlrev_b32_e32 v72, 16, v157
	v_and_b32_e32 v73, 0xffff0000, v157
	v_lshlrev_b32_e32 v74, 16, v158
	v_and_b32_e32 v75, 0xffff0000, v158
	v_lshlrev_b32_e32 v76, 16, v159
	v_and_b32_e32 v77, 0xffff0000, v159
	v_lshlrev_b32_e32 v78, 16, v160
	v_and_b32_e32 v79, 0xffff0000, v160
	v_lshlrev_b32_e32 v80, 16, v161
	v_and_b32_e32 v81, 0xffff0000, v161
	v_mul_f32_e32 v130, v50, v50
	v_fmac_f32_e32 v130, v51, v51
	v_fmac_f32_e32 v130, v52, v52
	v_fmac_f32_e32 v130, v53, v53
	v_fmac_f32_e32 v130, v54, v54
	v_fmac_f32_e32 v130, v55, v55
	v_fmac_f32_e32 v130, v56, v56
	v_fmac_f32_e32 v130, v57, v57
	v_fmac_f32_e32 v130, v58, v58
	v_fmac_f32_e32 v130, v59, v59
	v_fmac_f32_e32 v130, v60, v60
	v_fmac_f32_e32 v130, v61, v61
	v_fmac_f32_e32 v130, v62, v62
	v_fmac_f32_e32 v130, v63, v63
	v_fmac_f32_e32 v130, v64, v64
	v_fmac_f32_e32 v130, v65, v65
	v_fmac_f32_e32 v130, v66, v66
	v_fmac_f32_e32 v130, v67, v67
	v_fmac_f32_e32 v130, v68, v68
	v_fmac_f32_e32 v130, v69, v69
	v_fmac_f32_e32 v130, v70, v70
	v_fmac_f32_e32 v130, v71, v71
	v_fmac_f32_e32 v130, v72, v72
	v_fmac_f32_e32 v130, v73, v73
	v_fmac_f32_e32 v130, v74, v74
	v_fmac_f32_e32 v130, v75, v75
	v_fmac_f32_e32 v130, v76, v76
	v_fmac_f32_e32 v130, v77, v77
	v_fmac_f32_e32 v130, v78, v78
	v_fmac_f32_e32 v130, v79, v79
	v_fmac_f32_e32 v130, v80, v80
	v_fmac_f32_e32 v130, v81, v81
	ds_swizzle_b32 v132, v130 offset:swizzle(SWAP,16)
	s_waitcnt lgkmcnt(0)
	v_add_f32_e32 v130, v130, v132
	v_mov_b32_e32 v132, v130
	s_nop 1
	v_permlane32_swap_b32_e32 v130, v132
	v_add_f32_e32 v130, v130, v132
	v_fmamk_f32 v130, v130, 0x3c000000, v199
	v_rsq_f32_e32 v130, v130
	s_nop 0
	v_mul_f32_e32 v131, s77, v130
	v_mul_f32_e32 v50, v50, v131
	v_mul_f32_e32 v50, v50, v18
	v_mul_f32_e32 v51, v51, v131
	v_mul_f32_e32 v51, v51, v19
	v_mul_f32_e32 v52, v52, v131
	v_mul_f32_e32 v52, v52, v20
	v_mul_f32_e32 v53, v53, v131
	v_mul_f32_e32 v53, v53, v21
	v_mul_f32_e32 v54, v54, v131
	v_mul_f32_e32 v54, v54, v22
	v_mul_f32_e32 v55, v55, v131
	v_mul_f32_e32 v55, v55, v23
	v_mul_f32_e32 v56, v56, v131
	v_mul_f32_e32 v56, v56, v24
	v_mul_f32_e32 v57, v57, v131
	v_mul_f32_e32 v57, v57, v25
	v_mul_f32_e32 v58, v58, v131
	v_mul_f32_e32 v58, v58, v26
	v_mul_f32_e32 v59, v59, v131
	v_mul_f32_e32 v59, v59, v27
	v_mul_f32_e32 v60, v60, v131
	v_mul_f32_e32 v60, v60, v28
	v_mul_f32_e32 v61, v61, v131
	v_mul_f32_e32 v61, v61, v29
	v_mul_f32_e32 v62, v62, v131
	v_mul_f32_e32 v62, v62, v30
	v_mul_f32_e32 v63, v63, v131
	v_mul_f32_e32 v63, v63, v31
	v_mul_f32_e32 v64, v64, v131
	v_mul_f32_e32 v64, v64, v32
	v_mul_f32_e32 v65, v65, v131
	v_mul_f32_e32 v65, v65, v33
	v_mul_f32_e32 v66, v66, v131
	v_mul_f32_e32 v66, v66, v34
	v_mul_f32_e32 v67, v67, v131
	v_mul_f32_e32 v67, v67, v35
	v_mul_f32_e32 v68, v68, v131
	v_mul_f32_e32 v68, v68, v36
	v_mul_f32_e32 v69, v69, v131
	v_mul_f32_e32 v69, v69, v37
	v_mul_f32_e32 v70, v70, v131
	v_mul_f32_e32 v70, v70, v38
	v_mul_f32_e32 v71, v71, v131
	v_mul_f32_e32 v71, v71, v39
	v_mul_f32_e32 v72, v72, v131
	v_mul_f32_e32 v72, v72, v40
	v_mul_f32_e32 v73, v73, v131
	v_mul_f32_e32 v73, v73, v41
	v_mul_f32_e32 v74, v74, v131
	v_mul_f32_e32 v74, v74, v42
	v_mul_f32_e32 v75, v75, v131
	v_mul_f32_e32 v75, v75, v43
	v_mul_f32_e32 v76, v76, v131
	v_mul_f32_e32 v76, v76, v44
	v_mul_f32_e32 v77, v77, v131
	v_mul_f32_e32 v77, v77, v45
	v_mul_f32_e32 v78, v78, v131
	v_mul_f32_e32 v78, v78, v46
	v_mul_f32_e32 v79, v79, v131
	v_mul_f32_e32 v79, v79, v47
	v_mul_f32_e32 v80, v80, v131
	v_mul_f32_e32 v80, v80, v48
	v_mul_f32_e32 v81, v81, v131
	v_mul_f32_e32 v81, v81, v49
	v_mul_f32_e32 v133, v58, v90
	v_mul_f32_e32 v134, v50, v90
	v_fma_f32 v50, v50, v82, -v133
	v_fma_f32 v58, v58, v82, v134
	v_mul_f32_e32 v133, v59, v91
	v_mul_f32_e32 v134, v51, v91
	v_fma_f32 v51, v51, v83, -v133
	v_fma_f32 v59, v59, v83, v134
	v_mul_f32_e32 v133, v60, v92
	v_mul_f32_e32 v134, v52, v92
	v_fma_f32 v52, v52, v84, -v133
	v_fma_f32 v60, v60, v84, v134
	v_mul_f32_e32 v133, v61, v93
	v_mul_f32_e32 v134, v53, v93
	v_fma_f32 v53, v53, v85, -v133
	v_fma_f32 v61, v61, v85, v134
	v_mul_f32_e32 v133, v62, v94
	v_mul_f32_e32 v134, v54, v94
	v_fma_f32 v54, v54, v86, -v133
	v_fma_f32 v62, v62, v86, v134
	v_mul_f32_e32 v133, v63, v95
	v_mul_f32_e32 v134, v55, v95
	v_fma_f32 v55, v55, v87, -v133
	v_fma_f32 v63, v63, v87, v134
	v_mul_f32_e32 v133, v64, v96
	v_mul_f32_e32 v134, v56, v96
	v_fma_f32 v56, v56, v88, -v133
	v_fma_f32 v64, v64, v88, v134
	v_mul_f32_e32 v133, v65, v97
	v_mul_f32_e32 v134, v57, v97
	v_fma_f32 v57, v57, v89, -v133
	v_fma_f32 v65, v65, v89, v134
	v_mul_f32_e32 v133, v74, v106
	v_mul_f32_e32 v134, v66, v106
	v_fma_f32 v66, v66, v98, -v133
	v_fma_f32 v74, v74, v98, v134
	v_mul_f32_e32 v133, v75, v107
	v_mul_f32_e32 v134, v67, v107
	v_fma_f32 v67, v67, v99, -v133
	v_fma_f32 v75, v75, v99, v134
	v_mul_f32_e32 v133, v76, v108
	v_mul_f32_e32 v134, v68, v108
	v_fma_f32 v68, v68, v100, -v133
; #define QF(d, e) __uint_as_float(((unsigned)(unsigned short)qr[d][e]) << 16)
; template <typename TQ> ...
;     ...
;   {
;     float ss = 0.f;
;     ...
; #pragma unroll
;     for (int d0 = 0; d0 < 8; ++d0)
; #pragma unroll
;       for (int e = 0; e < 8; ++e) { const float x = QF(d0, e); ss += x * x; }
;     ss += __shfl_xor(ss, 32);
;     const float rn = (SCALE * 1.4426950408889634f) / sqrtf(ss * (1.0f / 128.0f) + 1e-6f);
;     const int t = trow0 + wid * QBLK + r32; const int prow = t >> 6, pcol = t & 63;
; #pragma unroll
;     for (int hf = 0; hf < 2; ++hf)
; #pragma unroll
;       for (int dd = 0; dd < 2; ++dd) {
;         const int dl = 4 * hf + dd, du = dl + 2;
;         const int f0 = 16 * dd + 8 * hi;
;         const float* cp = rc + (hf ? pcol : prow) * 32 + f0; const float* sp = rsn + (hf ? pcol : prow) * 32 + f0;
;         const float* gl = gq + 16 * dl + 8 * hi; const float* gu = gq + 16 * du + 8 * hi;
;         unsigned wl[4], wu[4];
; #pragma unroll
;         for (int e = 0; e < 8; e += 2) {
;           float o1[2], o2[2];
; #pragma unroll
;           for (int k = 0; k < 2; ++k) { const float x1 = QF(dl, e + k) * rn * gl[e + k], x2 = QF(du, e + k) * rn * gu[e + k]; const float c = cp[e + k], sn = sp[e + k];
;             o1[k] = x1 * c - x2 * sn; o2[k] = x2 * c + x1 * sn; }
;           wl[e >> 1] = cvtpk(o1[0], o1[1]); wu[e >> 1] = cvtpk(o2[0], o2[1]);
;         }
;         u32x4 vl = {wl[0], wl[1], wl[2], wl[3]}, vu = {wu[0], wu[1], wu[2], wu[3]};
;         qr[dl] = *reinterpret_cast<bf16x8*>(&vl); qr[du] = *reinterpret_cast<bf16x8*>(&vu);
;       }
;   }
	v_fma_f32 v76, v76, v100, v134
	v_mul_f32_e32 v133, v77, v109
	v_mul_f32_e32 v134, v69, v109
	v_fma_f32 v69, v69, v101, -v133
	v_fma_f32 v77, v77, v101, v134
	v_mul_f32_e32 v133, v78, v110
	v_mul_f32_e32 v134, v70, v110
	v_fma_f32 v70, v70, v102, -v133
	v_fma_f32 v78, v78, v102, v134
	v_mul_f32_e32 v133, v79, v111
	v_mul_f32_e32 v134, v71, v111
	v_fma_f32 v71, v71, v103, -v133
	v_fma_f32 v79, v79, v103, v134
	v_mul_f32_e32 v133, v80, v112
	v_mul_f32_e32 v134, v72, v112
	v_fma_f32 v72, v72, v104, -v133
	v_fma_f32 v80, v80, v104, v134
	v_mul_f32_e32 v133, v81, v113
	v_mul_f32_e32 v134, v73, v113
	v_fma_f32 v73, v73, v105, -v133
	v_fma_f32 v81, v81, v105, v134
	v_cvt_pk_bf16_f32 v146, v50, v51
	v_cvt_pk_bf16_f32 v147, v52, v53
	v_cvt_pk_bf16_f32 v148, v54, v55
	v_cvt_pk_bf16_f32 v149, v56, v57
	v_cvt_pk_bf16_f32 v150, v58, v59
	v_cvt_pk_bf16_f32 v151, v60, v61
	v_cvt_pk_bf16_f32 v152, v62, v63
	v_cvt_pk_bf16_f32 v153, v64, v65
	v_cvt_pk_bf16_f32 v154, v66, v67
	v_cvt_pk_bf16_f32 v155, v68, v69
	v_cvt_pk_bf16_f32 v156, v70, v71
	v_cvt_pk_bf16_f32 v157, v72, v73
	v_cvt_pk_bf16_f32 v158, v74, v75
	v_cvt_pk_bf16_f32 v159, v76, v77
	v_cvt_pk_bf16_f32 v160, v78, v79
	v_cvt_pk_bf16_f32 v161, v80, v81
	v_lshlrev_b32_e32 v50, 16, v162
	v_and_b32_e32 v51, 0xffff0000, v162
	v_lshlrev_b32_e32 v52, 16, v163
	v_and_b32_e32 v53, 0xffff0000, v163
	v_lshlrev_b32_e32 v54, 16, v164
	v_and_b32_e32 v55, 0xffff0000, v164
	v_lshlrev_b32_e32 v56, 16, v165
	v_and_b32_e32 v57, 0xffff0000, v165
	v_lshlrev_b32_e32 v58, 16, v166
	v_and_b32_e32 v59, 0xffff0000, v166
	v_lshlrev_b32_e32 v60, 16, v167
	v_and_b32_e32 v61, 0xffff0000, v167
	v_lshlrev_b32_e32 v62, 16, v168
	v_and_b32_e32 v63, 0xffff0000, v168
	v_lshlrev_b32_e32 v64, 16, v169
	v_and_b32_e32 v65, 0xffff0000, v169
	v_lshlrev_b32_e32 v66, 16, v170
	v_and_b32_e32 v67, 0xffff0000, v170
	v_lshlrev_b32_e32 v68, 16, v171
	v_and_b32_e32 v69, 0xffff0000, v171
	v_lshlrev_b32_e32 v70, 16, v172
	v_and_b32_e32 v71, 0xffff0000, v172
	v_lshlrev_b32_e32 v72, 16, v173
	v_and_b32_e32 v73, 0xffff0000, v173
	v_lshlrev_b32_e32 v74, 16, v174
	v_and_b32_e32 v75, 0xffff0000, v174
	v_lshlrev_b32_e32 v76, 16, v175
	v_and_b32_e32 v77, 0xffff0000, v175
	v_lshlrev_b32_e32 v78, 16, v176
	v_and_b32_e32 v79, 0xffff0000, v176
	v_lshlrev_b32_e32 v80, 16, v177
	v_and_b32_e32 v81, 0xffff0000, v177
	v_mul_f32_e32 v130, v50, v50
	v_fmac_f32_e32 v130, v51, v51
	v_fmac_f32_e32 v130, v52, v52
	v_fmac_f32_e32 v130, v53, v53
	v_fmac_f32_e32 v130, v54, v54
	v_fmac_f32_e32 v130, v55, v55
	v_fmac_f32_e32 v130, v56, v56
	v_fmac_f32_e32 v130, v57, v57
	v_fmac_f32_e32 v130, v58, v58
	v_fmac_f32_e32 v130, v59, v59
	v_fmac_f32_e32 v130, v60, v60
	v_fmac_f32_e32 v130, v61, v61
	v_fmac_f32_e32 v130, v62, v62
	v_fmac_f32_e32 v130, v63, v63
	v_fmac_f32_e32 v130, v64, v64
	v_fmac_f32_e32 v130, v65, v65
	v_fmac_f32_e32 v130, v66, v66
	v_fmac_f32_e32 v130, v67, v67
	v_fmac_f32_e32 v130, v68, v68
	v_fmac_f32_e32 v130, v69, v69
	v_fmac_f32_e32 v130, v70, v70
	v_fmac_f32_e32 v130, v71, v71
	v_fmac_f32_e32 v130, v72, v72
	v_fmac_f32_e32 v130, v73, v73
	v_fmac_f32_e32 v130, v74, v74
	v_fmac_f32_e32 v130, v75, v75
	v_fmac_f32_e32 v130, v76, v76
	v_fmac_f32_e32 v130, v77, v77
	v_fmac_f32_e32 v130, v78, v78
	v_fmac_f32_e32 v130, v79, v79
	v_fmac_f32_e32 v130, v80, v80
	v_fmac_f32_e32 v130, v81, v81
	ds_swizzle_b32 v132, v130 offset:swizzle(SWAP,16)
	s_waitcnt lgkmcnt(0)
	v_add_f32_e32 v130, v130, v132
	v_mov_b32_e32 v132, v130
	s_nop 1
	v_permlane32_swap_b32_e32 v130, v132
	v_add_f32_e32 v130, v130, v132
	v_fmamk_f32 v130, v130, 0x3c000000, v199
	v_rsq_f32_e32 v130, v130
	s_nop 0
	v_mul_f32_e32 v131, s77, v130
	v_mul_f32_e32 v50, v50, v131
	v_mul_f32_e32 v50, v50, v18
	v_mul_f32_e32 v51, v51, v131
	v_mul_f32_e32 v51, v51, v19
	v_mul_f32_e32 v52, v52, v131
	v_mul_f32_e32 v52, v52, v20
	v_mul_f32_e32 v53, v53, v131
	v_mul_f32_e32 v53, v53, v21
	v_mul_f32_e32 v54, v54, v131
	v_mul_f32_e32 v54, v54, v22
	v_mul_f32_e32 v55, v55, v131
	v_mul_f32_e32 v55, v55, v23
	v_mul_f32_e32 v56, v56, v131
	v_mul_f32_e32 v56, v56, v24
	v_mul_f32_e32 v57, v57, v131
	v_mul_f32_e32 v57, v57, v25
	v_mul_f32_e32 v58, v58, v131
	v_mul_f32_e32 v58, v58, v26
	v_mul_f32_e32 v59, v59, v131
	v_mul_f32_e32 v59, v59, v27
	v_mul_f32_e32 v60, v60, v131
	v_mul_f32_e32 v60, v60, v28
	v_mul_f32_e32 v61, v61, v131
	v_mul_f32_e32 v61, v61, v29
	v_mul_f32_e32 v62, v62, v131
	v_mul_f32_e32 v62, v62, v30
	v_mul_f32_e32 v63, v63, v131
	v_mul_f32_e32 v63, v63, v31
	v_mul_f32_e32 v64, v64, v131
	v_mul_f32_e32 v64, v64, v32
	v_mul_f32_e32 v65, v65, v131
	v_mul_f32_e32 v65, v65, v33
	v_mul_f32_e32 v66, v66, v131
	v_mul_f32_e32 v66, v66, v34
	v_mul_f32_e32 v67, v67, v131
	v_mul_f32_e32 v67, v67, v35
	v_mul_f32_e32 v68, v68, v131
	v_mul_f32_e32 v68, v68, v36
	v_mul_f32_e32 v69, v69, v131
	v_mul_f32_e32 v69, v69, v37
	v_mul_f32_e32 v70, v70, v131
	v_mul_f32_e32 v70, v70, v38
	v_mul_f32_e32 v71, v71, v131
	v_mul_f32_e32 v71, v71, v39
	v_mul_f32_e32 v72, v72, v131
	v_mul_f32_e32 v72, v72, v40
	v_mul_f32_e32 v73, v73, v131
	v_mul_f32_e32 v73, v73, v41
	v_mul_f32_e32 v74, v74, v131
	v_mul_f32_e32 v74, v74, v42
	v_mul_f32_e32 v75, v75, v131
	v_mul_f32_e32 v75, v75, v43
	v_mul_f32_e32 v76, v76, v131
	v_mul_f32_e32 v76, v76, v44
	v_mul_f32_e32 v77, v77, v131
	v_mul_f32_e32 v77, v77, v45
	v_mul_f32_e32 v78, v78, v131
	v_mul_f32_e32 v78, v78, v46
	v_mul_f32_e32 v79, v79, v131
	v_mul_f32_e32 v79, v79, v47
	v_mul_f32_e32 v80, v80, v131
	v_mul_f32_e32 v80, v80, v48
	v_mul_f32_e32 v81, v81, v131
	v_mul_f32_e32 v81, v81, v49
	v_mul_f32_e32 v133, v58, v90
	v_mul_f32_e32 v134, v50, v90
	v_fma_f32 v50, v50, v82, -v133
	v_fma_f32 v58, v58, v82, v134
; #define SBAR() __builtin_amdgcn_sched_barrier(0)
; #define QF(d, e) __uint_as_float(((unsigned)(unsigned short)qr[d][e]) << 16)
; template <typename TQ> ...
;     ...
;           for (int k = 0; k < 2; ++k) { const float x1 = QF(dl, e + k) * rn * gl[e + k], x2 = QF(du, e + k) * rn * gu[e + k]; const float c = cp[e + k], sn = sp[e + k];
;             o1[k] = x1 * c - x2 * sn; o2[k] = x2 * c + x1 * sn; }
;           wl[e >> 1] = cvtpk(o1[0], o1[1]); wu[e >> 1] = cvtpk(o2[0], o2[1]);
;         }
;         u32x4 vl = {wl[0], wl[1], wl[2], wl[3]}, vu = {wu[0], wu[1], wu[2], wu[3]};
;         qr[dl] = *reinterpret_cast<bf16x8*>(&vl); qr[du] = *reinterpret_cast<bf16x8*>(&vu);
;       }
;   }
;     ...
;   SBAR();
;   f32x16 pA0, pA1, pB0, pB1; bf16x8 pa0, pa1, pa2, pa3; const int NT = seq / KVBLK;
;   f32x16 negm;
; #pragma unroll
;   for (int r = 0; r < 16; ++r) negm[r] = -mC;
;   asm volatile("" : "+v"(negm));
;   asm volatile("s_waitcnt vmcnt(0)" ::: "memory"); SWRITE(0, SE); __syncthreads();
;   qkt(pA0, pA1, K_lds, qr, r32, hi, negm); partialSM(pA0, pA1, mC);
	v_mul_f32_e32 v133, v59, v91
	v_mul_f32_e32 v134, v51, v91
	v_fma_f32 v51, v51, v83, -v133
	v_fma_f32 v59, v59, v83, v134
	v_mul_f32_e32 v133, v60, v92
	v_mul_f32_e32 v134, v52, v92
	v_fma_f32 v52, v52, v84, -v133
	v_fma_f32 v60, v60, v84, v134
	v_mul_f32_e32 v133, v61, v93
	v_mul_f32_e32 v134, v53, v93
	v_fma_f32 v53, v53, v85, -v133
	v_fma_f32 v61, v61, v85, v134
	v_mul_f32_e32 v133, v62, v94
	v_mul_f32_e32 v134, v54, v94
	v_fma_f32 v54, v54, v86, -v133
	v_fma_f32 v62, v62, v86, v134
	v_mul_f32_e32 v133, v63, v95
	v_mul_f32_e32 v134, v55, v95
	v_fma_f32 v55, v55, v87, -v133
	v_fma_f32 v63, v63, v87, v134
	v_mul_f32_e32 v133, v64, v96
	v_mul_f32_e32 v134, v56, v96
	v_fma_f32 v56, v56, v88, -v133
	v_fma_f32 v64, v64, v88, v134
	v_mul_f32_e32 v133, v65, v97
	v_mul_f32_e32 v134, v57, v97
	v_fma_f32 v57, v57, v89, -v133
	v_fma_f32 v65, v65, v89, v134
	v_mul_f32_e32 v133, v74, v122
	v_mul_f32_e32 v134, v66, v122
	v_fma_f32 v66, v66, v114, -v133
	v_fma_f32 v74, v74, v114, v134
	v_mul_f32_e32 v133, v75, v123
	v_mul_f32_e32 v134, v67, v123
	v_fma_f32 v67, v67, v115, -v133
	v_fma_f32 v75, v75, v115, v134
	v_mul_f32_e32 v133, v76, v124
	v_mul_f32_e32 v134, v68, v124
	v_fma_f32 v68, v68, v116, -v133
	v_fma_f32 v76, v76, v116, v134
	v_mul_f32_e32 v133, v77, v125
	v_mul_f32_e32 v134, v69, v125
	v_fma_f32 v69, v69, v117, -v133
	v_fma_f32 v77, v77, v117, v134
	v_mul_f32_e32 v133, v78, v126
	v_mul_f32_e32 v134, v70, v126
	v_fma_f32 v70, v70, v118, -v133
	v_fma_f32 v78, v78, v118, v134
	v_mul_f32_e32 v133, v79, v127
	v_mul_f32_e32 v134, v71, v127
	v_fma_f32 v71, v71, v119, -v133
	v_fma_f32 v79, v79, v119, v134
	v_mul_f32_e32 v133, v80, v128
	v_mul_f32_e32 v134, v72, v128
	v_fma_f32 v72, v72, v120, -v133
	v_fma_f32 v80, v80, v120, v134
	v_mul_f32_e32 v133, v81, v129
	v_mul_f32_e32 v134, v73, v129
	v_fma_f32 v73, v73, v121, -v133
	v_fma_f32 v81, v81, v121, v134
	v_cvt_pk_bf16_f32 v162, v50, v51
	v_cvt_pk_bf16_f32 v163, v52, v53
	v_cvt_pk_bf16_f32 v164, v54, v55
	v_cvt_pk_bf16_f32 v165, v56, v57
	v_cvt_pk_bf16_f32 v166, v58, v59
	v_cvt_pk_bf16_f32 v167, v60, v61
	v_cvt_pk_bf16_f32 v168, v62, v63
	v_cvt_pk_bf16_f32 v169, v64, v65
	v_cvt_pk_bf16_f32 v170, v66, v67
	v_cvt_pk_bf16_f32 v171, v68, v69
	v_cvt_pk_bf16_f32 v172, v70, v71
	v_cvt_pk_bf16_f32 v173, v72, v73
	v_cvt_pk_bf16_f32 v174, v74, v75
	v_cvt_pk_bf16_f32 v175, v76, v77
	v_cvt_pk_bf16_f32 v176, v78, v79
	v_cvt_pk_bf16_f32 v177, v80, v81
	v_mov_b32_e32 v18, 0
	v_mov_b32_e32 v19, 0
	v_mov_b32_e32 v20, 0
	v_mov_b32_e32 v21, 0
	v_mov_b32_e32 v22, 0
	v_mov_b32_e32 v23, 0
	v_mov_b32_e32 v24, 0
	v_mov_b32_e32 v25, 0
	v_mov_b32_e32 v26, 0
	v_mov_b32_e32 v27, 0
	v_mov_b32_e32 v28, 0
	v_mov_b32_e32 v29, 0
	v_mov_b32_e32 v30, 0
	v_mov_b32_e32 v31, 0
	v_mov_b32_e32 v32, 0
	v_mov_b32_e32 v33, 0
	v_mov_b32_e32 v34, 0
	v_mov_b32_e32 v35, 0
	v_mov_b32_e32 v36, 0
	v_mov_b32_e32 v37, 0
	v_mov_b32_e32 v38, 0
	v_mov_b32_e32 v39, 0
	v_mov_b32_e32 v40, 0
	v_mov_b32_e32 v41, 0
	v_mov_b32_e32 v42, 0
	v_mov_b32_e32 v43, 0
	v_mov_b32_e32 v44, 0
	v_mov_b32_e32 v45, 0
	v_mov_b32_e32 v46, 0
	v_mov_b32_e32 v47, 0
	v_mov_b32_e32 v48, 0
	v_mov_b32_e32 v49, 0
	v_mov_b32_e32 v50, 0
	v_mov_b32_e32 v51, 0
	v_mov_b32_e32 v52, 0
	v_mov_b32_e32 v53, 0
	v_mov_b32_e32 v54, 0
	v_mov_b32_e32 v55, 0
	v_mov_b32_e32 v56, 0
	v_mov_b32_e32 v57, 0
	v_mov_b32_e32 v58, 0
	v_mov_b32_e32 v59, 0
	v_mov_b32_e32 v60, 0
	v_mov_b32_e32 v61, 0
	v_mov_b32_e32 v62, 0
	v_mov_b32_e32 v63, 0
	v_mov_b32_e32 v64, 0
	v_mov_b32_e32 v65, 0
	v_mov_b32_e32 v66, 0
	v_mov_b32_e32 v67, 0
	v_mov_b32_e32 v68, 0
	v_mov_b32_e32 v69, 0
	v_mov_b32_e32 v70, 0
	v_mov_b32_e32 v71, 0
	v_mov_b32_e32 v72, 0
	v_mov_b32_e32 v73, 0
	v_mov_b32_e32 v74, 0
	v_mov_b32_e32 v75, 0
	v_mov_b32_e32 v76, 0
	v_mov_b32_e32 v77, 0
	v_mov_b32_e32 v78, 0
	v_mov_b32_e32 v79, 0
	v_mov_b32_e32 v80, 0
	v_mov_b32_e32 v81, 0
	v_mov_b32_e32 v250, 0
	v_mov_b32_e32 v251, 0
	s_waitcnt vmcnt(0)
	s_barrier
	ds_read_b128 v[178:181], v234 offset:0
	ds_read_b128 v[182:185], v234 offset:4096
	ds_read_b128 v[186:189], v234 offset:8192
	ds_read_b128 v[190:193], v234 offset:12288
	s_waitcnt lgkmcnt(3)
	v_mfma_f32_16x16x32_bf16 v[82:85], v[178:181], v[146:149], v[2:5]
	v_mfma_f32_16x16x32_bf16 v[86:89], v[178:181], v[162:165], v[2:5]
	ds_read_b128 v[178:181], v235 offset:0
	s_waitcnt lgkmcnt(3)
	v_mfma_f32_16x16x32_bf16 v[90:93], v[182:185], v[146:149], v[2:5]
	v_mfma_f32_16x16x32_bf16 v[94:97], v[182:185], v[162:165], v[2:5]
	ds_read_b128 v[182:185], v235 offset:4096
	s_waitcnt lgkmcnt(3)
	v_mfma_f32_16x16x32_bf16 v[98:101], v[186:189], v[146:149], v[2:5]
	v_mfma_f32_16x16x32_bf16 v[102:105], v[186:189], v[162:165], v[2:5]
	ds_read_b128 v[186:189], v235 offset:8192
	s_waitcnt lgkmcnt(3)
	v_mfma_f32_16x16x32_bf16 v[106:109], v[190:193], v[146:149], v[2:5]
	v_mfma_f32_16x16x32_bf16 v[110:113], v[190:193], v[162:165], v[2:5]
	ds_read_b128 v[190:193], v235 offset:12288
	s_waitcnt lgkmcnt(3)
	v_mfma_f32_16x16x32_bf16 v[82:85], v[178:181], v[150:153], v[82:85]
	v_mfma_f32_16x16x32_bf16 v[86:89], v[178:181], v[166:169], v[86:89]
	ds_read_b128 v[178:181], v236 offset:0
	s_waitcnt lgkmcnt(3)
	v_mfma_f32_16x16x32_bf16 v[90:93], v[182:185], v[150:153], v[90:93]
	v_mfma_f32_16x16x32_bf16 v[94:97], v[182:185], v[166:169], v[94:97]
	ds_read_b128 v[182:185], v236 offset:4096
	s_waitcnt lgkmcnt(3)
	v_mfma_f32_16x16x32_bf16 v[98:101], v[186:189], v[150:153], v[98:101]
	v_mfma_f32_16x16x32_bf16 v[102:105], v[186:189], v[166:169], v[102:105]
	ds_read_b128 v[186:189], v236 offset:8192
	s_waitcnt lgkmcnt(3)
	v_mfma_f32_16x16x32_bf16 v[106:109], v[190:193], v[150:153], v[106:109]
	v_mfma_f32_16x16x32_bf16 v[110:113], v[190:193], v[166:169], v[110:113]
	ds_read_b128 v[190:193], v236 offset:12288
	s_waitcnt lgkmcnt(3)
; #define SBAR() __builtin_amdgcn_sched_barrier(0)
; #define SLOAD(i, k0) do { sr_[i].vs0 = St::ld8(&Vh[(long)((k0) + sr) * LDK + sc]); sr_[i].vs1 = St::ld8(&Vh[(long)((k0) + 32 + sr) * LDK + sc]); \
;     sr_[i].ks0 = St::ld8(&Kh[(long)((k0) + sr) * LDK + sc]); sr_[i].ks1 = St::ld8(&Kh[(long)((k0) + 32 + sr) * LDK + sc]); } while (0)
; #define SWAIT() do { if constexpr (SDEPTH == 2) asm volatile("s_waitcnt vmcnt(4)" ::: "memory"); else asm volatile("s_waitcnt vmcnt(0)" ::: "memory"); } while (0)
; template <typename TQ> ...
;     ...
;   qkt(pA0, pA1, K_lds, qr, r32, hi, negm); partialSM(pA0, pA1, mC);
;   SLOAD(SO, KVBLK); if constexpr (SDEPTH == 2) { if (2 < NT) SLOAD(SE, 2 * KVBLK); }
;   SWAIT(); SWRITE(1, SO); __syncthreads();
;   for (int j = 1; j + 1 < NT; j += 2) {
;     SBAR(); SLOAD(SO, (j + SDEPTH) * KVBLK); SBAR();
;     qkt(pB0, pB1, (bf16*)((char*)K_lds + SHM_K), qr, r32, hi, negm);
;     finishSM(pA0, pA1, l_reg, pa0, pa1, pa2, pa3); SBAR();
;     pv_d0(o, vb0, pa0, pa1, pa2, pa3); partialSM(pB0, pB1, mC);
;     __syncthreads(); SWAIT(); SWRITE(0, SE);
;     __syncthreads();
;     SBAR(); if (SDEPTH == 1 || j + 3 < NT) SLOAD(SE, (j + 1 + SDEPTH) * KVBLK); SBAR();
;     qkt(pA0, pA1, K_lds, qr, r32, hi, negm);
	v_mfma_f32_16x16x32_bf16 v[82:85], v[178:181], v[154:157], v[82:85]
	v_mfma_f32_16x16x32_bf16 v[86:89], v[178:181], v[170:173], v[86:89]
	ds_read_b128 v[178:181], v237 offset:0
	s_waitcnt lgkmcnt(3)
	v_mfma_f32_16x16x32_bf16 v[90:93], v[182:185], v[154:157], v[90:93]
	v_mfma_f32_16x16x32_bf16 v[94:97], v[182:185], v[170:173], v[94:97]
	ds_read_b128 v[182:185], v237 offset:4096
	s_waitcnt lgkmcnt(3)
	v_mfma_f32_16x16x32_bf16 v[98:101], v[186:189], v[154:157], v[98:101]
	v_mfma_f32_16x16x32_bf16 v[102:105], v[186:189], v[170:173], v[102:105]
	ds_read_b128 v[186:189], v237 offset:8192
	s_waitcnt lgkmcnt(3)
	v_mfma_f32_16x16x32_bf16 v[106:109], v[190:193], v[154:157], v[106:109]
	v_mfma_f32_16x16x32_bf16 v[110:113], v[190:193], v[170:173], v[110:113]
	ds_read_b128 v[190:193], v237 offset:12288
	s_waitcnt lgkmcnt(3)
	v_mfma_f32_16x16x32_bf16 v[82:85], v[178:181], v[158:161], v[82:85]
	v_mfma_f32_16x16x32_bf16 v[86:89], v[178:181], v[174:177], v[86:89]
	s_waitcnt lgkmcnt(2)
	v_mfma_f32_16x16x32_bf16 v[90:93], v[182:185], v[158:161], v[90:93]
	v_mfma_f32_16x16x32_bf16 v[94:97], v[182:185], v[174:177], v[94:97]
	s_waitcnt lgkmcnt(1)
	v_mfma_f32_16x16x32_bf16 v[98:101], v[186:189], v[158:161], v[98:101]
	v_mfma_f32_16x16x32_bf16 v[102:105], v[186:189], v[174:177], v[102:105]
	s_waitcnt lgkmcnt(0)
	v_mfma_f32_16x16x32_bf16 v[106:109], v[190:193], v[158:161], v[106:109]
	v_mfma_f32_16x16x32_bf16 v[110:113], v[190:193], v[174:177], v[110:113]
	s_nop 7
	v_exp_f32_e32 v82, v82
	v_exp_f32_e32 v83, v83
	v_exp_f32_e32 v84, v84
	v_exp_f32_e32 v85, v85
	v_exp_f32_e32 v86, v86
	v_exp_f32_e32 v87, v87
	v_exp_f32_e32 v88, v88
	v_exp_f32_e32 v89, v89
	v_exp_f32_e32 v90, v90
	v_exp_f32_e32 v91, v91
	v_exp_f32_e32 v92, v92
	v_exp_f32_e32 v93, v93
	v_exp_f32_e32 v94, v94
	v_exp_f32_e32 v95, v95
	v_exp_f32_e32 v96, v96
	v_exp_f32_e32 v97, v97
	v_exp_f32_e32 v98, v98
	v_exp_f32_e32 v99, v99
	v_exp_f32_e32 v100, v100
	v_exp_f32_e32 v101, v101
	v_exp_f32_e32 v102, v102
	v_exp_f32_e32 v103, v103
	v_exp_f32_e32 v104, v104
	v_exp_f32_e32 v105, v105
	v_exp_f32_e32 v106, v106
	v_exp_f32_e32 v107, v107
	v_exp_f32_e32 v108, v108
	v_exp_f32_e32 v109, v109
	v_exp_f32_e32 v110, v110
	v_exp_f32_e32 v111, v111
	v_exp_f32_e32 v112, v112
	v_exp_f32_e32 v113, v113
	ds_read_b128 v[178:181], v234 offset:16384
	ds_read_b128 v[182:185], v234 offset:20480
	ds_read_b128 v[186:189], v234 offset:24576
	ds_read_b128 v[190:193], v234 offset:28672
	s_mov_b32 s15, 0
	s_waitcnt lgkmcnt(3)
	v_mfma_f32_16x16x32_bf16 v[114:117], v[178:181], v[146:149], v[2:5]
	v_add_f32_e32 v250, v82, v250
	v_mfma_f32_16x16x32_bf16 v[118:121], v[178:181], v[162:165], v[2:5]
	ds_read_b128 v[178:181], v235 offset:16384
	v_add_f32_e32 v250, v83, v250
	v_add_f32_e32 v250, v84, v250
	s_waitcnt lgkmcnt(3)
	v_mfma_f32_16x16x32_bf16 v[122:125], v[182:185], v[146:149], v[2:5]
	v_add_f32_e32 v250, v85, v250
	v_mfma_f32_16x16x32_bf16 v[126:129], v[182:185], v[162:165], v[2:5]
	ds_read_b128 v[182:185], v235 offset:20480
	v_add_f32_e32 v250, v90, v250
	v_add_f32_e32 v250, v91, v250
	s_waitcnt lgkmcnt(3)
	v_mfma_f32_16x16x32_bf16 v[130:133], v[186:189], v[146:149], v[2:5]
	v_add_f32_e32 v250, v92, v250
	v_mfma_f32_16x16x32_bf16 v[134:137], v[186:189], v[162:165], v[2:5]
	ds_read_b128 v[186:189], v235 offset:24576
	v_add_f32_e32 v250, v93, v250
	v_cvt_pk_bf16_f32 v82, v82, v83
	s_waitcnt lgkmcnt(3)
	v_mfma_f32_16x16x32_bf16 v[138:141], v[190:193], v[146:149], v[2:5]
	v_cvt_pk_bf16_f32 v83, v84, v85
	v_mfma_f32_16x16x32_bf16 v[142:145], v[190:193], v[162:165], v[2:5]
	ds_read_b128 v[190:193], v235 offset:28672
	v_cvt_pk_bf16_f32 v84, v90, v91
	v_cvt_pk_bf16_f32 v85, v92, v93
	s_waitcnt lgkmcnt(3)
	v_mfma_f32_16x16x32_bf16 v[114:117], v[178:181], v[150:153], v[114:117]
	v_add_f32_e32 v251, v86, v251
	v_mfma_f32_16x16x32_bf16 v[118:121], v[178:181], v[166:169], v[118:121]
	ds_read_b128 v[178:181], v236 offset:16384
	v_add_f32_e32 v251, v87, v251
	v_add_f32_e32 v251, v88, v251
	s_waitcnt lgkmcnt(3)
	v_mfma_f32_16x16x32_bf16 v[122:125], v[182:185], v[150:153], v[122:125]
	v_add_f32_e32 v251, v89, v251
	v_mfma_f32_16x16x32_bf16 v[126:129], v[182:185], v[166:169], v[126:129]
	ds_read_b128 v[182:185], v236 offset:20480
	v_add_f32_e32 v251, v94, v251
	v_add_f32_e32 v251, v95, v251
	s_waitcnt lgkmcnt(3)
	v_mfma_f32_16x16x32_bf16 v[130:133], v[186:189], v[150:153], v[130:133]
	v_add_f32_e32 v251, v96, v251
	v_mfma_f32_16x16x32_bf16 v[134:137], v[186:189], v[166:169], v[134:137]
	ds_read_b128 v[186:189], v236 offset:24576
	v_add_f32_e32 v251, v97, v251
	v_cvt_pk_bf16_f32 v86, v86, v87
	s_waitcnt lgkmcnt(3)
	v_mfma_f32_16x16x32_bf16 v[138:141], v[190:193], v[150:153], v[138:141]
	v_cvt_pk_bf16_f32 v87, v88, v89
	v_mfma_f32_16x16x32_bf16 v[142:145], v[190:193], v[166:169], v[142:145]
	ds_read_b128 v[190:193], v236 offset:28672
	v_cvt_pk_bf16_f32 v88, v94, v95
	v_cvt_pk_bf16_f32 v89, v96, v97
	s_waitcnt lgkmcnt(3)
	v_mfma_f32_16x16x32_bf16 v[114:117], v[178:181], v[154:157], v[114:117]
	v_add_f32_e32 v250, v98, v250
	v_mfma_f32_16x16x32_bf16 v[118:121], v[178:181], v[170:173], v[118:121]
	ds_read_b128 v[178:181], v237 offset:16384
	v_add_f32_e32 v250, v99, v250
	v_add_f32_e32 v250, v100, v250
	s_waitcnt lgkmcnt(3)
	v_mfma_f32_16x16x32_bf16 v[122:125], v[182:185], v[154:157], v[122:125]
	v_add_f32_e32 v250, v101, v250
	v_mfma_f32_16x16x32_bf16 v[126:129], v[182:185], v[170:173], v[126:129]
	ds_read_b128 v[182:185], v237 offset:20480
	v_add_f32_e32 v250, v106, v250
	v_add_f32_e32 v250, v107, v250
	s_waitcnt lgkmcnt(3)
; #define SBAR() __builtin_amdgcn_sched_barrier(0)
; #define SLOAD(i, k0) do { sr_[i].vs0 = St::ld8(&Vh[(long)((k0) + sr) * LDK + sc]); sr_[i].vs1 = St::ld8(&Vh[(long)((k0) + 32 + sr) * LDK + sc]); \
;     sr_[i].ks0 = St::ld8(&Kh[(long)((k0) + sr) * LDK + sc]); sr_[i].ks1 = St::ld8(&Kh[(long)((k0) + 32 + sr) * LDK + sc]); } while (0)
; #define SWAIT() do { if constexpr (SDEPTH == 2) asm volatile("s_waitcnt vmcnt(4)" ::: "memory"); else asm volatile("s_waitcnt vmcnt(0)" ::: "memory"); } while (0)
; template <typename TQ> ...
;     ...
;   for (int j = 1; j + 1 < NT; j += 2) {
;     SBAR(); SLOAD(SO, (j + SDEPTH) * KVBLK); SBAR();
;     qkt(pB0, pB1, (bf16*)((char*)K_lds + SHM_K), qr, r32, hi, negm);
;     finishSM(pA0, pA1, l_reg, pa0, pa1, pa2, pa3); SBAR();
;     pv_d0(o, vb0, pa0, pa1, pa2, pa3); partialSM(pB0, pB1, mC);
;     __syncthreads(); SWAIT(); SWRITE(0, SE);
;     __syncthreads();
;     SBAR(); if (SDEPTH == 1 || j + 3 < NT) SLOAD(SE, (j + 1 + SDEPTH) * KVBLK); SBAR();
;     qkt(pA0, pA1, K_lds, qr, r32, hi, negm);
;     finishSM(pB0, pB1, l_reg, pa0, pa1, pa2, pa3); SBAR();
;     pv_d0(o, vb0 + (int)SHM_V, pa0, pa1, pa2, pa3); partialSM(pA0, pA1, mC);
;     __syncthreads(); SWAIT(); SWRITE(1, SO);
;     __syncthreads();
	v_mfma_f32_16x16x32_bf16 v[130:133], v[186:189], v[154:157], v[130:133]
	v_add_f32_e32 v250, v108, v250
	ds_read_b64_tr_b16 v[202:203], v238 offset:0
	ds_read_b64_tr_b16 v[204:205], v238 offset:4096
	v_mfma_f32_16x16x32_bf16 v[134:137], v[186:189], v[170:173], v[134:137]
	ds_read_b128 v[186:189], v237 offset:24576
	v_add_f32_e32 v250, v109, v250
	v_cvt_pk_bf16_f32 v98, v98, v99
	s_waitcnt lgkmcnt(5)
	v_mfma_f32_16x16x32_bf16 v[138:141], v[190:193], v[154:157], v[138:141]
	v_cvt_pk_bf16_f32 v99, v100, v101
	ds_read_b64_tr_b16 v[206:207], v239 offset:0
	ds_read_b64_tr_b16 v[208:209], v239 offset:4096
	v_mfma_f32_16x16x32_bf16 v[142:145], v[190:193], v[170:173], v[142:145]
	ds_read_b128 v[190:193], v237 offset:28672
	v_cvt_pk_bf16_f32 v100, v106, v107
	v_cvt_pk_bf16_f32 v101, v108, v109
	s_waitcnt lgkmcnt(7)
	v_mfma_f32_16x16x32_bf16 v[114:117], v[178:181], v[158:161], v[114:117]
	v_add_f32_e32 v251, v102, v251
	ds_read_b64_tr_b16 v[210:211], v240 offset:0
	ds_read_b64_tr_b16 v[212:213], v240 offset:4096
	v_mfma_f32_16x16x32_bf16 v[118:121], v[178:181], v[174:177], v[118:121]
	v_add_f32_e32 v251, v103, v251
	v_add_f32_e32 v251, v104, v251
	s_waitcnt lgkmcnt(8)
	v_mfma_f32_16x16x32_bf16 v[122:125], v[182:185], v[158:161], v[122:125]
	v_add_f32_e32 v251, v105, v251
	ds_read_b64_tr_b16 v[214:215], v241 offset:0
	ds_read_b64_tr_b16 v[216:217], v241 offset:4096
	v_mfma_f32_16x16x32_bf16 v[126:129], v[182:185], v[174:177], v[126:129]
	v_add_f32_e32 v251, v110, v251
	v_add_f32_e32 v251, v111, v251
	s_waitcnt lgkmcnt(7)
	v_mfma_f32_16x16x32_bf16 v[130:133], v[186:189], v[158:161], v[130:133]
	v_add_f32_e32 v251, v112, v251
	ds_read_b64_tr_b16 v[218:219], v242 offset:0
	ds_read_b64_tr_b16 v[220:221], v242 offset:4096
	v_mfma_f32_16x16x32_bf16 v[134:137], v[186:189], v[174:177], v[134:137]
	v_add_f32_e32 v251, v113, v251
	v_cvt_pk_bf16_f32 v102, v102, v103
	s_waitcnt lgkmcnt(6)
	v_mfma_f32_16x16x32_bf16 v[138:141], v[190:193], v[158:161], v[138:141]
	v_cvt_pk_bf16_f32 v103, v104, v105
	ds_read_b64_tr_b16 v[222:223], v243 offset:0
	ds_read_b64_tr_b16 v[224:225], v243 offset:4096
	v_mfma_f32_16x16x32_bf16 v[142:145], v[190:193], v[174:177], v[142:145]
	v_cvt_pk_bf16_f32 v104, v110, v111
	v_cvt_pk_bf16_f32 v105, v112, v113
	v_mfma_f32_16x16x32_bf16 v[18:21], v[202:205], v[82:85], v[18:21]
	v_exp_f32_e32 v114, v114
	v_mfma_f32_16x16x32_bf16 v[22:25], v[202:205], v[86:89], v[22:25]
	ds_read_b64_tr_b16 v[202:203], v244 offset:0
	ds_read_b64_tr_b16 v[204:205], v244 offset:4096
	v_exp_f32_e32 v115, v115
	v_mfma_f32_16x16x32_bf16 v[26:29], v[206:209], v[82:85], v[26:29]
	v_exp_f32_e32 v116, v116
	v_mfma_f32_16x16x32_bf16 v[30:33], v[206:209], v[86:89], v[30:33]
	ds_read_b64_tr_b16 v[206:207], v245 offset:0
	ds_read_b64_tr_b16 v[208:209], v245 offset:4096
	v_exp_f32_e32 v117, v117
	s_waitcnt lgkmcnt(10)
	v_mfma_f32_16x16x32_bf16 v[34:37], v[210:213], v[82:85], v[34:37]
	v_exp_f32_e32 v118, v118
	v_mfma_f32_16x16x32_bf16 v[38:41], v[210:213], v[86:89], v[38:41]
	ds_read_b64_tr_b16 v[210:211], v238 offset:8192
	ds_read_b64_tr_b16 v[212:213], v238 offset:12288
	v_exp_f32_e32 v119, v119
	s_waitcnt lgkmcnt(10)
	v_mfma_f32_16x16x32_bf16 v[42:45], v[214:217], v[82:85], v[42:45]
	v_exp_f32_e32 v120, v120
	v_mfma_f32_16x16x32_bf16 v[46:49], v[214:217], v[86:89], v[46:49]
	ds_read_b64_tr_b16 v[214:215], v239 offset:8192
	ds_read_b64_tr_b16 v[216:217], v239 offset:12288
	v_exp_f32_e32 v121, v121
	s_waitcnt lgkmcnt(10)
	v_mfma_f32_16x16x32_bf16 v[50:53], v[218:221], v[82:85], v[50:53]
	v_exp_f32_e32 v122, v122
	v_mfma_f32_16x16x32_bf16 v[54:57], v[218:221], v[86:89], v[54:57]
	ds_read_b64_tr_b16 v[218:219], v240 offset:8192
	ds_read_b64_tr_b16 v[220:221], v240 offset:12288
	v_exp_f32_e32 v123, v123
	s_waitcnt lgkmcnt(10)
	v_mfma_f32_16x16x32_bf16 v[58:61], v[222:225], v[82:85], v[58:61]
	v_exp_f32_e32 v124, v124
	v_mfma_f32_16x16x32_bf16 v[62:65], v[222:225], v[86:89], v[62:65]
	ds_read_b64_tr_b16 v[222:223], v241 offset:8192
	ds_read_b64_tr_b16 v[224:225], v241 offset:12288
	v_exp_f32_e32 v125, v125
	s_waitcnt lgkmcnt(10)
	v_mfma_f32_16x16x32_bf16 v[66:69], v[202:205], v[82:85], v[66:69]
	v_exp_f32_e32 v126, v126
	v_mfma_f32_16x16x32_bf16 v[70:73], v[202:205], v[86:89], v[70:73]
	ds_read_b64_tr_b16 v[202:203], v242 offset:8192
	ds_read_b64_tr_b16 v[204:205], v242 offset:12288
	v_exp_f32_e32 v127, v127
	s_waitcnt lgkmcnt(10)
	v_mfma_f32_16x16x32_bf16 v[74:77], v[206:209], v[82:85], v[74:77]
	v_exp_f32_e32 v128, v128
	v_mfma_f32_16x16x32_bf16 v[78:81], v[206:209], v[86:89], v[78:81]
	ds_read_b64_tr_b16 v[206:207], v243 offset:8192
	ds_read_b64_tr_b16 v[208:209], v243 offset:12288
	v_exp_f32_e32 v129, v129
	s_waitcnt lgkmcnt(10)
	v_mfma_f32_16x16x32_bf16 v[18:21], v[210:213], v[98:101], v[18:21]
	v_exp_f32_e32 v130, v130
	v_mfma_f32_16x16x32_bf16 v[22:25], v[210:213], v[102:105], v[22:25]
	ds_read_b64_tr_b16 v[210:211], v244 offset:8192
	ds_read_b64_tr_b16 v[212:213], v244 offset:12288
	v_exp_f32_e32 v131, v131
	s_waitcnt lgkmcnt(10)
	v_mfma_f32_16x16x32_bf16 v[26:29], v[214:217], v[98:101], v[26:29]
	v_exp_f32_e32 v132, v132
	v_mfma_f32_16x16x32_bf16 v[30:33], v[214:217], v[102:105], v[30:33]
	ds_read_b64_tr_b16 v[214:215], v245 offset:8192
	ds_read_b64_tr_b16 v[216:217], v245 offset:12288
	v_exp_f32_e32 v133, v133
	s_waitcnt lgkmcnt(10)
	v_mfma_f32_16x16x32_bf16 v[34:37], v[218:221], v[98:101], v[34:37]
	v_exp_f32_e32 v134, v134
	v_mfma_f32_16x16x32_bf16 v[38:41], v[218:221], v[102:105], v[38:41]
	v_exp_f32_e32 v135, v135
	s_waitcnt lgkmcnt(8)
	v_mfma_f32_16x16x32_bf16 v[42:45], v[222:225], v[98:101], v[42:45]
	v_exp_f32_e32 v136, v136
	v_mfma_f32_16x16x32_bf16 v[46:49], v[222:225], v[102:105], v[46:49]
	v_exp_f32_e32 v137, v137
	s_waitcnt lgkmcnt(6)
	v_mfma_f32_16x16x32_bf16 v[50:53], v[202:205], v[98:101], v[50:53]
	v_exp_f32_e32 v138, v138
	v_mfma_f32_16x16x32_bf16 v[54:57], v[202:205], v[102:105], v[54:57]
	v_exp_f32_e32 v139, v139
	s_waitcnt lgkmcnt(4)
	v_mfma_f32_16x16x32_bf16 v[58:61], v[206:209], v[98:101], v[58:61]
	v_exp_f32_e32 v140, v140
	v_mfma_f32_16x16x32_bf16 v[62:65], v[206:209], v[102:105], v[62:65]
	v_exp_f32_e32 v141, v141
	s_waitcnt lgkmcnt(2)
	v_mfma_f32_16x16x32_bf16 v[66:69], v[210:213], v[98:101], v[66:69]
	v_exp_f32_e32 v142, v142
	v_mfma_f32_16x16x32_bf16 v[70:73], v[210:213], v[102:105], v[70:73]
	v_exp_f32_e32 v143, v143
	s_waitcnt lgkmcnt(0)
	v_mfma_f32_16x16x32_bf16 v[74:77], v[214:217], v[98:101], v[74:77]
	v_exp_f32_e32 v144, v144
	v_mfma_f32_16x16x32_bf16 v[78:81], v[214:217], v[102:105], v[78:81]
	v_exp_f32_e32 v145, v145
	s_waitcnt vmcnt(0)
	s_cmp_lt_u32 s53, 256
	s_cbranch_scc1 .Lattn_noprio
	s_setprio 1
; #define SBAR() __builtin_amdgcn_sched_barrier(0)
; #define SLOAD(i, k0) do { sr_[i].vs0 = St::ld8(&Vh[(long)((k0) + sr) * LDK + sc]); sr_[i].vs1 = St::ld8(&Vh[(long)((k0) + 32 + sr) * LDK + sc]); \
;     sr_[i].ks0 = St::ld8(&Kh[(long)((k0) + sr) * LDK + sc]); sr_[i].ks1 = St::ld8(&Kh[(long)((k0) + 32 + sr) * LDK + sc]); } while (0)
; #define SWAIT() do { if constexpr (SDEPTH == 2) asm volatile("s_waitcnt vmcnt(4)" ::: "memory"); else asm volatile("s_waitcnt vmcnt(0)" ::: "memory"); } while (0)
; template <typename TQ> ...
;     ...
;   for (int j = 1; j + 1 < NT; j += 2) {
;     SBAR(); SLOAD(SO, (j + SDEPTH) * KVBLK); SBAR();
;     qkt(pB0, pB1, (bf16*)((char*)K_lds + SHM_K), qr, r32, hi, negm);
;     finishSM(pA0, pA1, l_reg, pa0, pa1, pa2, pa3); SBAR();
;     pv_d0(o, vb0, pa0, pa1, pa2, pa3); partialSM(pB0, pB1, mC);
;     __syncthreads(); SWAIT(); SWRITE(0, SE);
;     __syncthreads();
;     SBAR(); if (SDEPTH == 1 || j + 3 < NT) SLOAD(SE, (j + 1 + SDEPTH) * KVBLK); SBAR();
;     qkt(pA0, pA1, K_lds, qr, r32, hi, negm);
;     finishSM(pB0, pB1, l_reg, pa0, pa1, pa2, pa3); SBAR();
;     pv_d0(o, vb0 + (int)SHM_V, pa0, pa1, pa2, pa3); partialSM(pA0, pA1, mC);
;     __syncthreads(); SWAIT(); SWRITE(1, SO);
;     __syncthreads();
;   }
.Lattn_noprio:
.Lattn_loop:
	s_barrier
	ds_read_b128 v[178:181], v234 offset:32768
	ds_read_b128 v[182:185], v234 offset:36864
	ds_read_b128 v[186:189], v234 offset:40960
	ds_read_b128 v[190:193], v234 offset:45056
	v_add_f32_e32 v250, v114, v250
	v_add_f32_e32 v250, v115, v250
	v_add_f32_e32 v250, v116, v250
	v_add_f32_e32 v250, v117, v250
	v_add_f32_e32 v250, v122, v250
	v_add_f32_e32 v250, v123, v250
	v_add_f32_e32 v250, v124, v250
	v_add_f32_e32 v250, v125, v250
	v_cvt_pk_bf16_f32 v114, v114, v115
	v_cvt_pk_bf16_f32 v115, v116, v117
	v_cvt_pk_bf16_f32 v116, v122, v123
	v_cvt_pk_bf16_f32 v117, v124, v125
	s_waitcnt lgkmcnt(3)
	v_mfma_f32_16x16x32_bf16 v[82:85], v[178:181], v[146:149], v[2:5]
	v_mfma_f32_16x16x32_bf16 v[86:89], v[178:181], v[162:165], v[2:5]
	ds_read_b128 v[178:181], v235 offset:32768
	s_waitcnt lgkmcnt(3)
	v_mfma_f32_16x16x32_bf16 v[90:93], v[182:185], v[146:149], v[2:5]
	s_add_u32 s98, s98, 0x8000
	s_addc_u32 s99, s99, 0
	s_add_u32 m0, s79, 0
	s_nop 0
	global_load_lds_dwordx4 v246, s[98:99]
	v_mfma_f32_16x16x32_bf16 v[94:97], v[182:185], v[162:165], v[2:5]
	ds_read_b128 v[182:185], v235 offset:36864
	s_waitcnt lgkmcnt(3)
	v_mfma_f32_16x16x32_bf16 v[98:101], v[186:189], v[146:149], v[2:5]
	v_mfma_f32_16x16x32_bf16 v[102:105], v[186:189], v[162:165], v[2:5]
	ds_read_b128 v[186:189], v235 offset:40960
	s_waitcnt lgkmcnt(3)
	v_mfma_f32_16x16x32_bf16 v[106:109], v[190:193], v[146:149], v[2:5]
	s_add_u32 m0, s79, 1024
	s_nop 0
	global_load_lds_dwordx4 v247, s[98:99]
	v_mfma_f32_16x16x32_bf16 v[110:113], v[190:193], v[162:165], v[2:5]
	ds_read_b128 v[190:193], v235 offset:45056
	s_waitcnt lgkmcnt(3)
	v_mfma_f32_16x16x32_bf16 v[82:85], v[178:181], v[150:153], v[82:85]
	v_add_f32_e32 v251, v118, v251
	v_mfma_f32_16x16x32_bf16 v[86:89], v[178:181], v[166:169], v[86:89]
	ds_read_b128 v[178:181], v236 offset:32768
	v_add_f32_e32 v251, v119, v251
	v_add_f32_e32 v251, v120, v251
	s_waitcnt lgkmcnt(3)
	v_mfma_f32_16x16x32_bf16 v[90:93], v[182:185], v[150:153], v[90:93]
	v_add_f32_e32 v251, v121, v251
	s_add_u32 s100, s100, 0x8000
	s_addc_u32 s101, s101, 0
	s_add_u32 m0, s80, 49152
	s_nop 0
	global_load_lds_dwordx4 v248, s[100:101]
	v_mfma_f32_16x16x32_bf16 v[94:97], v[182:185], v[166:169], v[94:97]
	ds_read_b128 v[182:185], v236 offset:36864
	v_add_f32_e32 v251, v126, v251
	v_add_f32_e32 v251, v127, v251
	s_waitcnt lgkmcnt(3)
	v_mfma_f32_16x16x32_bf16 v[98:101], v[186:189], v[150:153], v[98:101]
	v_add_f32_e32 v251, v128, v251
	v_mfma_f32_16x16x32_bf16 v[102:105], v[186:189], v[166:169], v[102:105]
	ds_read_b128 v[186:189], v236 offset:40960
	v_add_f32_e32 v251, v129, v251
	v_cvt_pk_bf16_f32 v118, v118, v119
	s_waitcnt lgkmcnt(3)
	v_mfma_f32_16x16x32_bf16 v[106:109], v[190:193], v[150:153], v[106:109]
	v_cvt_pk_bf16_f32 v119, v120, v121
	s_add_u32 m0, s80, 50176
	s_nop 0
	global_load_lds_dwordx4 v249, s[100:101]
	v_mfma_f32_16x16x32_bf16 v[110:113], v[190:193], v[166:169], v[110:113]
	ds_read_b128 v[190:193], v236 offset:45056
	v_cvt_pk_bf16_f32 v120, v126, v127
	v_cvt_pk_bf16_f32 v121, v128, v129
	s_waitcnt lgkmcnt(3)
	v_mfma_f32_16x16x32_bf16 v[82:85], v[178:181], v[154:157], v[82:85]
	v_add_f32_e32 v250, v130, v250
	v_mfma_f32_16x16x32_bf16 v[86:89], v[178:181], v[170:173], v[86:89]
	ds_read_b128 v[178:181], v237 offset:32768
	v_add_f32_e32 v250, v131, v250
	v_add_f32_e32 v250, v132, v250
	s_waitcnt lgkmcnt(3)
	v_mfma_f32_16x16x32_bf16 v[90:93], v[182:185], v[154:157], v[90:93]
	v_add_f32_e32 v250, v133, v250
	v_mfma_f32_16x16x32_bf16 v[94:97], v[182:185], v[170:173], v[94:97]
	ds_read_b128 v[182:185], v237 offset:36864
	v_add_f32_e32 v250, v138, v250
	v_add_f32_e32 v250, v139, v250
	s_waitcnt lgkmcnt(3)
	v_mfma_f32_16x16x32_bf16 v[98:101], v[186:189], v[154:157], v[98:101]
	v_add_f32_e32 v250, v140, v250
	ds_read_b64_tr_b16 v[202:203], v238 offset:16384
	ds_read_b64_tr_b16 v[204:205], v238 offset:20480
	v_mfma_f32_16x16x32_bf16 v[102:105], v[186:189], v[170:173], v[102:105]
	ds_read_b128 v[186:189], v237 offset:40960
	v_add_f32_e32 v250, v141, v250
	v_cvt_pk_bf16_f32 v130, v130, v131
	s_waitcnt lgkmcnt(5)
	v_mfma_f32_16x16x32_bf16 v[106:109], v[190:193], v[154:157], v[106:109]
	v_cvt_pk_bf16_f32 v131, v132, v133
	ds_read_b64_tr_b16 v[206:207], v239 offset:16384
	ds_read_b64_tr_b16 v[208:209], v239 offset:20480
	v_mfma_f32_16x16x32_bf16 v[110:113], v[190:193], v[170:173], v[110:113]
	ds_read_b128 v[190:193], v237 offset:45056
	v_cvt_pk_bf16_f32 v132, v138, v139
	v_cvt_pk_bf16_f32 v133, v140, v141
	s_waitcnt lgkmcnt(7)
	v_mfma_f32_16x16x32_bf16 v[82:85], v[178:181], v[158:161], v[82:85]
	v_add_f32_e32 v251, v134, v251
	ds_read_b64_tr_b16 v[210:211], v240 offset:16384
	ds_read_b64_tr_b16 v[212:213], v240 offset:20480
	v_mfma_f32_16x16x32_bf16 v[86:89], v[178:181], v[174:177], v[86:89]
	v_add_f32_e32 v251, v135, v251
	v_add_f32_e32 v251, v136, v251
	s_waitcnt lgkmcnt(8)
	v_mfma_f32_16x16x32_bf16 v[90:93], v[182:185], v[158:161], v[90:93]
	v_add_f32_e32 v251, v137, v251
	ds_read_b64_tr_b16 v[214:215], v241 offset:16384
	ds_read_b64_tr_b16 v[216:217], v241 offset:20480
	v_mfma_f32_16x16x32_bf16 v[94:97], v[182:185], v[174:177], v[94:97]
	v_add_f32_e32 v251, v142, v251
	v_add_f32_e32 v251, v143, v251
	s_waitcnt lgkmcnt(7)
	v_mfma_f32_16x16x32_bf16 v[98:101], v[186:189], v[158:161], v[98:101]
	v_add_f32_e32 v251, v144, v251
	ds_read_b64_tr_b16 v[218:219], v242 offset:16384
	ds_read_b64_tr_b16 v[220:221], v242 offset:20480
	v_mfma_f32_16x16x32_bf16 v[102:105], v[186:189], v[174:177], v[102:105]
	v_add_f32_e32 v251, v145, v251
	v_cvt_pk_bf16_f32 v134, v134, v135
	s_waitcnt lgkmcnt(6)
; #define SBAR() __builtin_amdgcn_sched_barrier(0)
; #define SLOAD(i, k0) do { sr_[i].vs0 = St::ld8(&Vh[(long)((k0) + sr) * LDK + sc]); sr_[i].vs1 = St::ld8(&Vh[(long)((k0) + 32 + sr) * LDK + sc]); \
;     sr_[i].ks0 = St::ld8(&Kh[(long)((k0) + sr) * LDK + sc]); sr_[i].ks1 = St::ld8(&Kh[(long)((k0) + 32 + sr) * LDK + sc]); } while (0)
; #define SWAIT() do { if constexpr (SDEPTH == 2) asm volatile("s_waitcnt vmcnt(4)" ::: "memory"); else asm volatile("s_waitcnt vmcnt(0)" ::: "memory"); } while (0)
; template <typename TQ> ...
;     ...
;   for (int j = 1; j + 1 < NT; j += 2) {
;     SBAR(); SLOAD(SO, (j + SDEPTH) * KVBLK); SBAR();
;     qkt(pB0, pB1, (bf16*)((char*)K_lds + SHM_K), qr, r32, hi, negm);
;     finishSM(pA0, pA1, l_reg, pa0, pa1, pa2, pa3); SBAR();
;     pv_d0(o, vb0, pa0, pa1, pa2, pa3); partialSM(pB0, pB1, mC);
;     __syncthreads(); SWAIT(); SWRITE(0, SE);
;     __syncthreads();
;     SBAR(); if (SDEPTH == 1 || j + 3 < NT) SLOAD(SE, (j + 1 + SDEPTH) * KVBLK); SBAR();
;     qkt(pA0, pA1, K_lds, qr, r32, hi, negm);
;     finishSM(pB0, pB1, l_reg, pa0, pa1, pa2, pa3); SBAR();
;     pv_d0(o, vb0 + (int)SHM_V, pa0, pa1, pa2, pa3); partialSM(pA0, pA1, mC);
;     __syncthreads(); SWAIT(); SWRITE(1, SO);
;     __syncthreads();
;   }
	v_mfma_f32_16x16x32_bf16 v[106:109], v[190:193], v[158:161], v[106:109]
	v_cvt_pk_bf16_f32 v135, v136, v137
	ds_read_b64_tr_b16 v[222:223], v243 offset:16384
	ds_read_b64_tr_b16 v[224:225], v243 offset:20480
	v_mfma_f32_16x16x32_bf16 v[110:113], v[190:193], v[174:177], v[110:113]
	v_cvt_pk_bf16_f32 v136, v142, v143
	v_cvt_pk_bf16_f32 v137, v144, v145
	v_mfma_f32_16x16x32_bf16 v[18:21], v[202:205], v[114:117], v[18:21]
	v_exp_f32_e32 v82, v82
	v_mfma_f32_16x16x32_bf16 v[22:25], v[202:205], v[118:121], v[22:25]
	ds_read_b64_tr_b16 v[202:203], v244 offset:16384
	ds_read_b64_tr_b16 v[204:205], v244 offset:20480
	v_exp_f32_e32 v83, v83
	v_mfma_f32_16x16x32_bf16 v[26:29], v[206:209], v[114:117], v[26:29]
	v_exp_f32_e32 v84, v84
	s_add_u32 s98, s98, 0x8000
	s_addc_u32 s99, s99, 0
	s_add_u32 m0, s79, 16384
	s_nop 0
	global_load_lds_dwordx4 v246, s[98:99]
	v_mfma_f32_16x16x32_bf16 v[30:33], v[206:209], v[118:121], v[30:33]
	ds_read_b64_tr_b16 v[206:207], v245 offset:16384
	ds_read_b64_tr_b16 v[208:209], v245 offset:20480
	v_exp_f32_e32 v85, v85
	s_waitcnt lgkmcnt(10)
	v_mfma_f32_16x16x32_bf16 v[34:37], v[210:213], v[114:117], v[34:37]
	v_exp_f32_e32 v86, v86
	v_mfma_f32_16x16x32_bf16 v[38:41], v[210:213], v[118:121], v[38:41]
	ds_read_b64_tr_b16 v[210:211], v238 offset:24576
	ds_read_b64_tr_b16 v[212:213], v238 offset:28672
	v_exp_f32_e32 v87, v87
	s_waitcnt lgkmcnt(10)
	v_mfma_f32_16x16x32_bf16 v[42:45], v[214:217], v[114:117], v[42:45]
	v_exp_f32_e32 v88, v88
	s_add_u32 m0, s79, 17408
	s_nop 0
	global_load_lds_dwordx4 v247, s[98:99]
	v_mfma_f32_16x16x32_bf16 v[46:49], v[214:217], v[118:121], v[46:49]
	ds_read_b64_tr_b16 v[214:215], v239 offset:24576
	ds_read_b64_tr_b16 v[216:217], v239 offset:28672
	v_exp_f32_e32 v89, v89
	s_waitcnt lgkmcnt(10)
	v_mfma_f32_16x16x32_bf16 v[50:53], v[218:221], v[114:117], v[50:53]
	v_exp_f32_e32 v90, v90
	v_mfma_f32_16x16x32_bf16 v[54:57], v[218:221], v[118:121], v[54:57]
	ds_read_b64_tr_b16 v[218:219], v240 offset:24576
	ds_read_b64_tr_b16 v[220:221], v240 offset:28672
	v_exp_f32_e32 v91, v91
	s_waitcnt lgkmcnt(10)
	v_mfma_f32_16x16x32_bf16 v[58:61], v[222:225], v[114:117], v[58:61]
	v_exp_f32_e32 v92, v92
	s_add_u32 s100, s100, 0x8000
	s_addc_u32 s101, s101, 0
	s_add_u32 m0, s80, 0
	s_nop 0
	global_load_lds_dwordx4 v248, s[100:101]
	v_mfma_f32_16x16x32_bf16 v[62:65], v[222:225], v[118:121], v[62:65]
	ds_read_b64_tr_b16 v[222:223], v241 offset:24576
	ds_read_b64_tr_b16 v[224:225], v241 offset:28672
	v_exp_f32_e32 v93, v93
	s_waitcnt lgkmcnt(10)
	v_mfma_f32_16x16x32_bf16 v[66:69], v[202:205], v[114:117], v[66:69]
	v_exp_f32_e32 v94, v94
	v_mfma_f32_16x16x32_bf16 v[70:73], v[202:205], v[118:121], v[70:73]
	ds_read_b64_tr_b16 v[202:203], v242 offset:24576
	ds_read_b64_tr_b16 v[204:205], v242 offset:28672
	v_exp_f32_e32 v95, v95
	s_waitcnt lgkmcnt(10)
	v_mfma_f32_16x16x32_bf16 v[74:77], v[206:209], v[114:117], v[74:77]
	v_exp_f32_e32 v96, v96
	s_add_u32 m0, s80, 1024
	s_nop 0
	global_load_lds_dwordx4 v249, s[100:101]
	v_mfma_f32_16x16x32_bf16 v[78:81], v[206:209], v[118:121], v[78:81]
	ds_read_b64_tr_b16 v[206:207], v243 offset:24576
	ds_read_b64_tr_b16 v[208:209], v243 offset:28672
	v_exp_f32_e32 v97, v97
	s_waitcnt lgkmcnt(10)
	v_mfma_f32_16x16x32_bf16 v[18:21], v[210:213], v[130:133], v[18:21]
	v_exp_f32_e32 v98, v98
	v_mfma_f32_16x16x32_bf16 v[22:25], v[210:213], v[134:137], v[22:25]
	ds_read_b64_tr_b16 v[210:211], v244 offset:24576
	ds_read_b64_tr_b16 v[212:213], v244 offset:28672
	v_exp_f32_e32 v99, v99
	s_waitcnt lgkmcnt(10)
	v_mfma_f32_16x16x32_bf16 v[26:29], v[214:217], v[130:133], v[26:29]
	v_exp_f32_e32 v100, v100
	v_mfma_f32_16x16x32_bf16 v[30:33], v[214:217], v[134:137], v[30:33]
	ds_read_b64_tr_b16 v[214:215], v245 offset:24576
	ds_read_b64_tr_b16 v[216:217], v245 offset:28672
	v_exp_f32_e32 v101, v101
	s_waitcnt lgkmcnt(10)
	v_mfma_f32_16x16x32_bf16 v[34:37], v[218:221], v[130:133], v[34:37]
	v_exp_f32_e32 v102, v102
	v_mfma_f32_16x16x32_bf16 v[38:41], v[218:221], v[134:137], v[38:41]
	v_exp_f32_e32 v103, v103
	s_waitcnt lgkmcnt(8)
	v_mfma_f32_16x16x32_bf16 v[42:45], v[222:225], v[130:133], v[42:45]
	v_exp_f32_e32 v104, v104
	v_mfma_f32_16x16x32_bf16 v[46:49], v[222:225], v[134:137], v[46:49]
	v_exp_f32_e32 v105, v105
	s_waitcnt lgkmcnt(6)
	v_mfma_f32_16x16x32_bf16 v[50:53], v[202:205], v[130:133], v[50:53]
	v_exp_f32_e32 v106, v106
	ds_read_b128 v[178:181], v234 offset:49152
	v_mfma_f32_16x16x32_bf16 v[54:57], v[202:205], v[134:137], v[54:57]
	v_exp_f32_e32 v107, v107
	s_waitcnt lgkmcnt(5)
	v_mfma_f32_16x16x32_bf16 v[58:61], v[206:209], v[130:133], v[58:61]
	v_exp_f32_e32 v108, v108
	ds_read_b128 v[182:185], v234 offset:53248
	v_mfma_f32_16x16x32_bf16 v[62:65], v[206:209], v[134:137], v[62:65]
	v_exp_f32_e32 v109, v109
	s_waitcnt lgkmcnt(4)
	v_mfma_f32_16x16x32_bf16 v[66:69], v[210:213], v[130:133], v[66:69]
	v_exp_f32_e32 v110, v110
	ds_read_b128 v[186:189], v234 offset:57344
	v_mfma_f32_16x16x32_bf16 v[70:73], v[210:213], v[134:137], v[70:73]
	v_exp_f32_e32 v111, v111
	s_waitcnt lgkmcnt(3)
	v_mfma_f32_16x16x32_bf16 v[74:77], v[214:217], v[130:133], v[74:77]
	v_exp_f32_e32 v112, v112
	ds_read_b128 v[190:193], v234 offset:61440
	v_mfma_f32_16x16x32_bf16 v[78:81], v[214:217], v[134:137], v[78:81]
	v_exp_f32_e32 v113, v113
	s_waitcnt lgkmcnt(3)
	v_mfma_f32_16x16x32_bf16 v[114:117], v[178:181], v[146:149], v[2:5]
	v_add_f32_e32 v250, v82, v250
	v_mfma_f32_16x16x32_bf16 v[118:121], v[178:181], v[162:165], v[2:5]
	ds_read_b128 v[178:181], v235 offset:49152
	v_add_f32_e32 v250, v83, v250
	v_add_f32_e32 v250, v84, v250
	s_waitcnt lgkmcnt(3)
; #define SBAR() __builtin_amdgcn_sched_barrier(0)
; #define SLOAD(i, k0) do { sr_[i].vs0 = St::ld8(&Vh[(long)((k0) + sr) * LDK + sc]); sr_[i].vs1 = St::ld8(&Vh[(long)((k0) + 32 + sr) * LDK + sc]); \
;     sr_[i].ks0 = St::ld8(&Kh[(long)((k0) + sr) * LDK + sc]); sr_[i].ks1 = St::ld8(&Kh[(long)((k0) + 32 + sr) * LDK + sc]); } while (0)
; #define SWAIT() do { if constexpr (SDEPTH == 2) asm volatile("s_waitcnt vmcnt(4)" ::: "memory"); else asm volatile("s_waitcnt vmcnt(0)" ::: "memory"); } while (0)
; template <typename TQ> ...
;     ...
;   for (int j = 1; j + 1 < NT; j += 2) {
;     SBAR(); SLOAD(SO, (j + SDEPTH) * KVBLK); SBAR();
;     qkt(pB0, pB1, (bf16*)((char*)K_lds + SHM_K), qr, r32, hi, negm);
;     finishSM(pA0, pA1, l_reg, pa0, pa1, pa2, pa3); SBAR();
;     pv_d0(o, vb0, pa0, pa1, pa2, pa3); partialSM(pB0, pB1, mC);
;     __syncthreads(); SWAIT(); SWRITE(0, SE);
;     __syncthreads();
;     SBAR(); if (SDEPTH == 1 || j + 3 < NT) SLOAD(SE, (j + 1 + SDEPTH) * KVBLK); SBAR();
;     qkt(pA0, pA1, K_lds, qr, r32, hi, negm);
;     finishSM(pB0, pB1, l_reg, pa0, pa1, pa2, pa3); SBAR();
;     pv_d0(o, vb0 + (int)SHM_V, pa0, pa1, pa2, pa3); partialSM(pA0, pA1, mC);
;     __syncthreads(); SWAIT(); SWRITE(1, SO);
;     __syncthreads();
;   }
	v_mfma_f32_16x16x32_bf16 v[122:125], v[182:185], v[146:149], v[2:5]
	v_add_f32_e32 v250, v85, v250
	v_mfma_f32_16x16x32_bf16 v[126:129], v[182:185], v[162:165], v[2:5]
	ds_read_b128 v[182:185], v235 offset:53248
	v_add_f32_e32 v250, v90, v250
	v_add_f32_e32 v250, v91, v250
	s_waitcnt lgkmcnt(3)
	v_mfma_f32_16x16x32_bf16 v[130:133], v[186:189], v[146:149], v[2:5]
	v_add_f32_e32 v250, v92, v250
	v_mfma_f32_16x16x32_bf16 v[134:137], v[186:189], v[162:165], v[2:5]
	ds_read_b128 v[186:189], v235 offset:57344
	v_add_f32_e32 v250, v93, v250
	v_cvt_pk_bf16_f32 v82, v82, v83
	s_waitcnt lgkmcnt(3)
	v_mfma_f32_16x16x32_bf16 v[138:141], v[190:193], v[146:149], v[2:5]
	v_cvt_pk_bf16_f32 v83, v84, v85
	v_mfma_f32_16x16x32_bf16 v[142:145], v[190:193], v[162:165], v[2:5]
	ds_read_b128 v[190:193], v235 offset:61440
	v_cvt_pk_bf16_f32 v84, v90, v91
	v_cvt_pk_bf16_f32 v85, v92, v93
	s_waitcnt lgkmcnt(3)
	v_mfma_f32_16x16x32_bf16 v[114:117], v[178:181], v[150:153], v[114:117]
	v_add_f32_e32 v251, v86, v251
	v_mfma_f32_16x16x32_bf16 v[118:121], v[178:181], v[166:169], v[118:121]
	ds_read_b128 v[178:181], v236 offset:49152
	v_add_f32_e32 v251, v87, v251
	v_add_f32_e32 v251, v88, v251
	s_waitcnt lgkmcnt(3)
	v_mfma_f32_16x16x32_bf16 v[122:125], v[182:185], v[150:153], v[122:125]
	v_add_f32_e32 v251, v89, v251
	v_mfma_f32_16x16x32_bf16 v[126:129], v[182:185], v[166:169], v[126:129]
	ds_read_b128 v[182:185], v236 offset:53248
	v_add_f32_e32 v251, v94, v251
	v_add_f32_e32 v251, v95, v251
	s_waitcnt lgkmcnt(3)
	v_mfma_f32_16x16x32_bf16 v[130:133], v[186:189], v[150:153], v[130:133]
	v_add_f32_e32 v251, v96, v251
	v_mfma_f32_16x16x32_bf16 v[134:137], v[186:189], v[166:169], v[134:137]
	ds_read_b128 v[186:189], v236 offset:57344
	v_add_f32_e32 v251, v97, v251
	v_cvt_pk_bf16_f32 v86, v86, v87
	s_waitcnt lgkmcnt(3)
	v_mfma_f32_16x16x32_bf16 v[138:141], v[190:193], v[150:153], v[138:141]
	v_cvt_pk_bf16_f32 v87, v88, v89
	v_mfma_f32_16x16x32_bf16 v[142:145], v[190:193], v[166:169], v[142:145]
	ds_read_b128 v[190:193], v236 offset:61440
	v_cvt_pk_bf16_f32 v88, v94, v95
	v_cvt_pk_bf16_f32 v89, v96, v97
	s_waitcnt lgkmcnt(3)
	v_mfma_f32_16x16x32_bf16 v[114:117], v[178:181], v[154:157], v[114:117]
	v_add_f32_e32 v250, v98, v250
	v_mfma_f32_16x16x32_bf16 v[118:121], v[178:181], v[170:173], v[118:121]
	ds_read_b128 v[178:181], v237 offset:49152
	v_add_f32_e32 v250, v99, v250
	v_add_f32_e32 v250, v100, v250
	s_waitcnt lgkmcnt(3)
	v_mfma_f32_16x16x32_bf16 v[122:125], v[182:185], v[154:157], v[122:125]
	v_add_f32_e32 v250, v101, v250
	v_mfma_f32_16x16x32_bf16 v[126:129], v[182:185], v[170:173], v[126:129]
	ds_read_b128 v[182:185], v237 offset:53248
	v_add_f32_e32 v250, v106, v250
	v_add_f32_e32 v250, v107, v250
	s_waitcnt lgkmcnt(3)
	v_mfma_f32_16x16x32_bf16 v[130:133], v[186:189], v[154:157], v[130:133]
	v_add_f32_e32 v250, v108, v250
	ds_read_b64_tr_b16 v[202:203], v238 offset:32768
	ds_read_b64_tr_b16 v[204:205], v238 offset:36864
	v_mfma_f32_16x16x32_bf16 v[134:137], v[186:189], v[170:173], v[134:137]
	ds_read_b128 v[186:189], v237 offset:57344
	v_add_f32_e32 v250, v109, v250
	v_cvt_pk_bf16_f32 v98, v98, v99
	s_waitcnt lgkmcnt(5)
	v_mfma_f32_16x16x32_bf16 v[138:141], v[190:193], v[154:157], v[138:141]
	v_cvt_pk_bf16_f32 v99, v100, v101
	ds_read_b64_tr_b16 v[206:207], v239 offset:32768
	ds_read_b64_tr_b16 v[208:209], v239 offset:36864
	v_mfma_f32_16x16x32_bf16 v[142:145], v[190:193], v[170:173], v[142:145]
	ds_read_b128 v[190:193], v237 offset:61440
	v_cvt_pk_bf16_f32 v100, v106, v107
	v_cvt_pk_bf16_f32 v101, v108, v109
	s_waitcnt lgkmcnt(7)
	v_mfma_f32_16x16x32_bf16 v[114:117], v[178:181], v[158:161], v[114:117]
	v_add_f32_e32 v251, v102, v251
	ds_read_b64_tr_b16 v[210:211], v240 offset:32768
	ds_read_b64_tr_b16 v[212:213], v240 offset:36864
	v_mfma_f32_16x16x32_bf16 v[118:121], v[178:181], v[174:177], v[118:121]
	v_add_f32_e32 v251, v103, v251
	v_add_f32_e32 v251, v104, v251
	s_waitcnt lgkmcnt(8)
	v_mfma_f32_16x16x32_bf16 v[122:125], v[182:185], v[158:161], v[122:125]
	v_add_f32_e32 v251, v105, v251
	ds_read_b64_tr_b16 v[214:215], v241 offset:32768
	ds_read_b64_tr_b16 v[216:217], v241 offset:36864
	v_mfma_f32_16x16x32_bf16 v[126:129], v[182:185], v[174:177], v[126:129]
	v_add_f32_e32 v251, v110, v251
	v_add_f32_e32 v251, v111, v251
	s_waitcnt lgkmcnt(7)
	v_mfma_f32_16x16x32_bf16 v[130:133], v[186:189], v[158:161], v[130:133]
	v_add_f32_e32 v251, v112, v251
	ds_read_b64_tr_b16 v[218:219], v242 offset:32768
	ds_read_b64_tr_b16 v[220:221], v242 offset:36864
	v_mfma_f32_16x16x32_bf16 v[134:137], v[186:189], v[174:177], v[134:137]
	v_add_f32_e32 v251, v113, v251
	v_cvt_pk_bf16_f32 v102, v102, v103
	s_waitcnt lgkmcnt(6)
	v_mfma_f32_16x16x32_bf16 v[138:141], v[190:193], v[158:161], v[138:141]
	v_cvt_pk_bf16_f32 v103, v104, v105
	ds_read_b64_tr_b16 v[222:223], v243 offset:32768
	ds_read_b64_tr_b16 v[224:225], v243 offset:36864
	v_mfma_f32_16x16x32_bf16 v[142:145], v[190:193], v[174:177], v[142:145]
	v_cvt_pk_bf16_f32 v104, v110, v111
	v_cvt_pk_bf16_f32 v105, v112, v113
	v_mfma_f32_16x16x32_bf16 v[18:21], v[202:205], v[82:85], v[18:21]
	v_exp_f32_e32 v114, v114
	v_mfma_f32_16x16x32_bf16 v[22:25], v[202:205], v[86:89], v[22:25]
	ds_read_b64_tr_b16 v[202:203], v244 offset:32768
	ds_read_b64_tr_b16 v[204:205], v244 offset:36864
	v_exp_f32_e32 v115, v115
	v_mfma_f32_16x16x32_bf16 v[26:29], v[206:209], v[82:85], v[26:29]
	v_exp_f32_e32 v116, v116
	v_mfma_f32_16x16x32_bf16 v[30:33], v[206:209], v[86:89], v[30:33]
	ds_read_b64_tr_b16 v[206:207], v245 offset:32768
	ds_read_b64_tr_b16 v[208:209], v245 offset:36864
	v_exp_f32_e32 v117, v117
	s_waitcnt lgkmcnt(10)
; #define SBAR() __builtin_amdgcn_sched_barrier(0)
; #define SLOAD(i, k0) do { sr_[i].vs0 = St::ld8(&Vh[(long)((k0) + sr) * LDK + sc]); sr_[i].vs1 = St::ld8(&Vh[(long)((k0) + 32 + sr) * LDK + sc]); \
;     sr_[i].ks0 = St::ld8(&Kh[(long)((k0) + sr) * LDK + sc]); sr_[i].ks1 = St::ld8(&Kh[(long)((k0) + 32 + sr) * LDK + sc]); } while (0)
; #define SWAIT() do { if constexpr (SDEPTH == 2) asm volatile("s_waitcnt vmcnt(4)" ::: "memory"); else asm volatile("s_waitcnt vmcnt(0)" ::: "memory"); } while (0)
; template <typename TQ> ...
;     ...
;   for (int j = 1; j + 1 < NT; j += 2) {
;     SBAR(); SLOAD(SO, (j + SDEPTH) * KVBLK); SBAR();
;     qkt(pB0, pB1, (bf16*)((char*)K_lds + SHM_K), qr, r32, hi, negm);
;     finishSM(pA0, pA1, l_reg, pa0, pa1, pa2, pa3); SBAR();
;     pv_d0(o, vb0, pa0, pa1, pa2, pa3); partialSM(pB0, pB1, mC);
;     __syncthreads(); SWAIT(); SWRITE(0, SE);
;     __syncthreads();
;     SBAR(); if (SDEPTH == 1 || j + 3 < NT) SLOAD(SE, (j + 1 + SDEPTH) * KVBLK); SBAR();
;     qkt(pA0, pA1, K_lds, qr, r32, hi, negm);
;     finishSM(pB0, pB1, l_reg, pa0, pa1, pa2, pa3); SBAR();
;     pv_d0(o, vb0 + (int)SHM_V, pa0, pa1, pa2, pa3); partialSM(pA0, pA1, mC);
;     __syncthreads(); SWAIT(); SWRITE(1, SO);
;     __syncthreads();
;   }
	v_mfma_f32_16x16x32_bf16 v[34:37], v[210:213], v[82:85], v[34:37]
	v_exp_f32_e32 v118, v118
	v_mfma_f32_16x16x32_bf16 v[38:41], v[210:213], v[86:89], v[38:41]
	ds_read_b64_tr_b16 v[210:211], v238 offset:40960
	ds_read_b64_tr_b16 v[212:213], v238 offset:45056
	v_exp_f32_e32 v119, v119
	s_waitcnt lgkmcnt(10)
	v_mfma_f32_16x16x32_bf16 v[42:45], v[214:217], v[82:85], v[42:45]
	v_exp_f32_e32 v120, v120
	v_mfma_f32_16x16x32_bf16 v[46:49], v[214:217], v[86:89], v[46:49]
	ds_read_b64_tr_b16 v[214:215], v239 offset:40960
	ds_read_b64_tr_b16 v[216:217], v239 offset:45056
	v_exp_f32_e32 v121, v121
	s_waitcnt lgkmcnt(10)
	v_mfma_f32_16x16x32_bf16 v[50:53], v[218:221], v[82:85], v[50:53]
	v_exp_f32_e32 v122, v122
	v_mfma_f32_16x16x32_bf16 v[54:57], v[218:221], v[86:89], v[54:57]
	ds_read_b64_tr_b16 v[218:219], v240 offset:40960
	ds_read_b64_tr_b16 v[220:221], v240 offset:45056
	v_exp_f32_e32 v123, v123
	s_waitcnt lgkmcnt(10)
	v_mfma_f32_16x16x32_bf16 v[58:61], v[222:225], v[82:85], v[58:61]
	v_exp_f32_e32 v124, v124
	v_mfma_f32_16x16x32_bf16 v[62:65], v[222:225], v[86:89], v[62:65]
	ds_read_b64_tr_b16 v[222:223], v241 offset:40960
	ds_read_b64_tr_b16 v[224:225], v241 offset:45056
	v_exp_f32_e32 v125, v125
	s_waitcnt lgkmcnt(10)
	v_mfma_f32_16x16x32_bf16 v[66:69], v[202:205], v[82:85], v[66:69]
	v_exp_f32_e32 v126, v126
	v_mfma_f32_16x16x32_bf16 v[70:73], v[202:205], v[86:89], v[70:73]
	ds_read_b64_tr_b16 v[202:203], v242 offset:40960
	ds_read_b64_tr_b16 v[204:205], v242 offset:45056
	v_exp_f32_e32 v127, v127
	s_waitcnt lgkmcnt(10)
	v_mfma_f32_16x16x32_bf16 v[74:77], v[206:209], v[82:85], v[74:77]
	v_exp_f32_e32 v128, v128
	v_mfma_f32_16x16x32_bf16 v[78:81], v[206:209], v[86:89], v[78:81]
	ds_read_b64_tr_b16 v[206:207], v243 offset:40960
	ds_read_b64_tr_b16 v[208:209], v243 offset:45056
	v_exp_f32_e32 v129, v129
	s_waitcnt lgkmcnt(10)
	v_mfma_f32_16x16x32_bf16 v[18:21], v[210:213], v[98:101], v[18:21]
	v_exp_f32_e32 v130, v130
	v_mfma_f32_16x16x32_bf16 v[22:25], v[210:213], v[102:105], v[22:25]
	ds_read_b64_tr_b16 v[210:211], v244 offset:40960
	ds_read_b64_tr_b16 v[212:213], v244 offset:45056
	v_exp_f32_e32 v131, v131
	s_waitcnt lgkmcnt(10)
	v_mfma_f32_16x16x32_bf16 v[26:29], v[214:217], v[98:101], v[26:29]
	v_exp_f32_e32 v132, v132
	v_mfma_f32_16x16x32_bf16 v[30:33], v[214:217], v[102:105], v[30:33]
	ds_read_b64_tr_b16 v[214:215], v245 offset:40960
	ds_read_b64_tr_b16 v[216:217], v245 offset:45056
	v_exp_f32_e32 v133, v133
	s_waitcnt lgkmcnt(10)
	v_mfma_f32_16x16x32_bf16 v[34:37], v[218:221], v[98:101], v[34:37]
	v_exp_f32_e32 v134, v134
	v_mfma_f32_16x16x32_bf16 v[38:41], v[218:221], v[102:105], v[38:41]
	v_exp_f32_e32 v135, v135
	s_waitcnt lgkmcnt(8)
	v_mfma_f32_16x16x32_bf16 v[42:45], v[222:225], v[98:101], v[42:45]
	v_exp_f32_e32 v136, v136
	v_mfma_f32_16x16x32_bf16 v[46:49], v[222:225], v[102:105], v[46:49]
	v_exp_f32_e32 v137, v137
	s_waitcnt lgkmcnt(6)
	v_mfma_f32_16x16x32_bf16 v[50:53], v[202:205], v[98:101], v[50:53]
	v_exp_f32_e32 v138, v138
	v_mfma_f32_16x16x32_bf16 v[54:57], v[202:205], v[102:105], v[54:57]
	v_exp_f32_e32 v139, v139
	s_waitcnt lgkmcnt(4)
	v_mfma_f32_16x16x32_bf16 v[58:61], v[206:209], v[98:101], v[58:61]
	v_exp_f32_e32 v140, v140
	v_mfma_f32_16x16x32_bf16 v[62:65], v[206:209], v[102:105], v[62:65]
	v_exp_f32_e32 v141, v141
	s_waitcnt lgkmcnt(2)
	v_mfma_f32_16x16x32_bf16 v[66:69], v[210:213], v[98:101], v[66:69]
	v_exp_f32_e32 v142, v142
	v_mfma_f32_16x16x32_bf16 v[70:73], v[210:213], v[102:105], v[70:73]
	v_exp_f32_e32 v143, v143
	s_waitcnt lgkmcnt(0)
	v_mfma_f32_16x16x32_bf16 v[74:77], v[214:217], v[98:101], v[74:77]
	v_exp_f32_e32 v144, v144
	v_mfma_f32_16x16x32_bf16 v[78:81], v[214:217], v[102:105], v[78:81]
	v_exp_f32_e32 v145, v145
	s_waitcnt vmcnt(0)
	s_barrier
	ds_read_b128 v[178:181], v234 offset:0
	ds_read_b128 v[182:185], v234 offset:4096
	ds_read_b128 v[186:189], v234 offset:8192
	ds_read_b128 v[190:193], v234 offset:12288
	v_add_f32_e32 v250, v114, v250
	v_add_f32_e32 v250, v115, v250
	v_add_f32_e32 v250, v116, v250
	v_add_f32_e32 v250, v117, v250
	v_add_f32_e32 v250, v122, v250
	v_add_f32_e32 v250, v123, v250
	v_add_f32_e32 v250, v124, v250
	v_add_f32_e32 v250, v125, v250
	v_cvt_pk_bf16_f32 v114, v114, v115
	v_cvt_pk_bf16_f32 v115, v116, v117
	v_cvt_pk_bf16_f32 v116, v122, v123
	v_cvt_pk_bf16_f32 v117, v124, v125
	s_waitcnt lgkmcnt(3)
	v_mfma_f32_16x16x32_bf16 v[82:85], v[178:181], v[146:149], v[2:5]
	v_mfma_f32_16x16x32_bf16 v[86:89], v[178:181], v[162:165], v[2:5]
	ds_read_b128 v[178:181], v235 offset:0
	s_waitcnt lgkmcnt(3)
	v_mfma_f32_16x16x32_bf16 v[90:93], v[182:185], v[146:149], v[2:5]
	s_add_u32 s98, s98, 0x8000
	s_addc_u32 s99, s99, 0
	s_add_u32 m0, s79, 32768
	s_nop 0
	global_load_lds_dwordx4 v246, s[98:99]
	v_mfma_f32_16x16x32_bf16 v[94:97], v[182:185], v[162:165], v[2:5]
	ds_read_b128 v[182:185], v235 offset:4096
	s_waitcnt lgkmcnt(3)
	v_mfma_f32_16x16x32_bf16 v[98:101], v[186:189], v[146:149], v[2:5]
	v_mfma_f32_16x16x32_bf16 v[102:105], v[186:189], v[162:165], v[2:5]
	ds_read_b128 v[186:189], v235 offset:8192
	s_waitcnt lgkmcnt(3)
	v_mfma_f32_16x16x32_bf16 v[106:109], v[190:193], v[146:149], v[2:5]
	s_add_u32 m0, s79, 33792
	s_nop 0
	global_load_lds_dwordx4 v247, s[98:99]
	v_mfma_f32_16x16x32_bf16 v[110:113], v[190:193], v[162:165], v[2:5]
	ds_read_b128 v[190:193], v235 offset:12288
	s_waitcnt lgkmcnt(3)
	v_mfma_f32_16x16x32_bf16 v[82:85], v[178:181], v[150:153], v[82:85]
	v_add_f32_e32 v251, v118, v251
	v_mfma_f32_16x16x32_bf16 v[86:89], v[178:181], v[166:169], v[86:89]
	ds_read_b128 v[178:181], v236 offset:0
	v_add_f32_e32 v251, v119, v251
	v_add_f32_e32 v251, v120, v251
	s_waitcnt lgkmcnt(3)
; #define SBAR() __builtin_amdgcn_sched_barrier(0)
; #define SLOAD(i, k0) do { sr_[i].vs0 = St::ld8(&Vh[(long)((k0) + sr) * LDK + sc]); sr_[i].vs1 = St::ld8(&Vh[(long)((k0) + 32 + sr) * LDK + sc]); \
;     sr_[i].ks0 = St::ld8(&Kh[(long)((k0) + sr) * LDK + sc]); sr_[i].ks1 = St::ld8(&Kh[(long)((k0) + 32 + sr) * LDK + sc]); } while (0)
; #define SWAIT() do { if constexpr (SDEPTH == 2) asm volatile("s_waitcnt vmcnt(4)" ::: "memory"); else asm volatile("s_waitcnt vmcnt(0)" ::: "memory"); } while (0)
; template <typename TQ> ...
;     ...
;   for (int j = 1; j + 1 < NT; j += 2) {
;     SBAR(); SLOAD(SO, (j + SDEPTH) * KVBLK); SBAR();
;     qkt(pB0, pB1, (bf16*)((char*)K_lds + SHM_K), qr, r32, hi, negm);
;     finishSM(pA0, pA1, l_reg, pa0, pa1, pa2, pa3); SBAR();
;     pv_d0(o, vb0, pa0, pa1, pa2, pa3); partialSM(pB0, pB1, mC);
;     __syncthreads(); SWAIT(); SWRITE(0, SE);
;     __syncthreads();
;     SBAR(); if (SDEPTH == 1 || j + 3 < NT) SLOAD(SE, (j + 1 + SDEPTH) * KVBLK); SBAR();
;     qkt(pA0, pA1, K_lds, qr, r32, hi, negm);
;     finishSM(pB0, pB1, l_reg, pa0, pa1, pa2, pa3); SBAR();
;     pv_d0(o, vb0 + (int)SHM_V, pa0, pa1, pa2, pa3); partialSM(pA0, pA1, mC);
;     __syncthreads(); SWAIT(); SWRITE(1, SO);
;     __syncthreads();
;   }
	v_mfma_f32_16x16x32_bf16 v[90:93], v[182:185], v[150:153], v[90:93]
	v_add_f32_e32 v251, v121, v251
	s_add_u32 s100, s100, 0x8000
	s_addc_u32 s101, s101, 0
	s_add_u32 m0, s80, 16384
	s_nop 0
	global_load_lds_dwordx4 v248, s[100:101]
	v_mfma_f32_16x16x32_bf16 v[94:97], v[182:185], v[166:169], v[94:97]
	ds_read_b128 v[182:185], v236 offset:4096
	v_add_f32_e32 v251, v126, v251
	v_add_f32_e32 v251, v127, v251
	s_waitcnt lgkmcnt(3)
	v_mfma_f32_16x16x32_bf16 v[98:101], v[186:189], v[150:153], v[98:101]
	v_add_f32_e32 v251, v128, v251
	v_mfma_f32_16x16x32_bf16 v[102:105], v[186:189], v[166:169], v[102:105]
	ds_read_b128 v[186:189], v236 offset:8192
	v_add_f32_e32 v251, v129, v251
	v_cvt_pk_bf16_f32 v118, v118, v119
	s_waitcnt lgkmcnt(3)
	v_mfma_f32_16x16x32_bf16 v[106:109], v[190:193], v[150:153], v[106:109]
	v_cvt_pk_bf16_f32 v119, v120, v121
	s_add_u32 m0, s80, 17408
	s_nop 0
	global_load_lds_dwordx4 v249, s[100:101]
	v_mfma_f32_16x16x32_bf16 v[110:113], v[190:193], v[166:169], v[110:113]
	ds_read_b128 v[190:193], v236 offset:12288
	v_cvt_pk_bf16_f32 v120, v126, v127
	v_cvt_pk_bf16_f32 v121, v128, v129
	s_waitcnt lgkmcnt(3)
	v_mfma_f32_16x16x32_bf16 v[82:85], v[178:181], v[154:157], v[82:85]
	v_add_f32_e32 v250, v130, v250
	v_mfma_f32_16x16x32_bf16 v[86:89], v[178:181], v[170:173], v[86:89]
	ds_read_b128 v[178:181], v237 offset:0
	v_add_f32_e32 v250, v131, v250
	v_add_f32_e32 v250, v132, v250
	s_waitcnt lgkmcnt(3)
	v_mfma_f32_16x16x32_bf16 v[90:93], v[182:185], v[154:157], v[90:93]
	v_add_f32_e32 v250, v133, v250
	v_mfma_f32_16x16x32_bf16 v[94:97], v[182:185], v[170:173], v[94:97]
	ds_read_b128 v[182:185], v237 offset:4096
	v_add_f32_e32 v250, v138, v250
	v_add_f32_e32 v250, v139, v250
	s_waitcnt lgkmcnt(3)
	v_mfma_f32_16x16x32_bf16 v[98:101], v[186:189], v[154:157], v[98:101]
	v_add_f32_e32 v250, v140, v250
	ds_read_b64_tr_b16 v[202:203], v238 offset:49152
	ds_read_b64_tr_b16 v[204:205], v238 offset:53248
	v_mfma_f32_16x16x32_bf16 v[102:105], v[186:189], v[170:173], v[102:105]
	ds_read_b128 v[186:189], v237 offset:8192
	v_add_f32_e32 v250, v141, v250
	v_cvt_pk_bf16_f32 v130, v130, v131
	s_waitcnt lgkmcnt(5)
	v_mfma_f32_16x16x32_bf16 v[106:109], v[190:193], v[154:157], v[106:109]
	v_cvt_pk_bf16_f32 v131, v132, v133
	ds_read_b64_tr_b16 v[206:207], v239 offset:49152
	ds_read_b64_tr_b16 v[208:209], v239 offset:53248
	v_mfma_f32_16x16x32_bf16 v[110:113], v[190:193], v[170:173], v[110:113]
	ds_read_b128 v[190:193], v237 offset:12288
	v_cvt_pk_bf16_f32 v132, v138, v139
	v_cvt_pk_bf16_f32 v133, v140, v141
	s_waitcnt lgkmcnt(7)
	v_mfma_f32_16x16x32_bf16 v[82:85], v[178:181], v[158:161], v[82:85]
	v_add_f32_e32 v251, v134, v251
	ds_read_b64_tr_b16 v[210:211], v240 offset:49152
	ds_read_b64_tr_b16 v[212:213], v240 offset:53248
	v_mfma_f32_16x16x32_bf16 v[86:89], v[178:181], v[174:177], v[86:89]
	v_add_f32_e32 v251, v135, v251
	v_add_f32_e32 v251, v136, v251
	s_waitcnt lgkmcnt(8)
	v_mfma_f32_16x16x32_bf16 v[90:93], v[182:185], v[158:161], v[90:93]
	v_add_f32_e32 v251, v137, v251
	ds_read_b64_tr_b16 v[214:215], v241 offset:49152
	ds_read_b64_tr_b16 v[216:217], v241 offset:53248
	v_mfma_f32_16x16x32_bf16 v[94:97], v[182:185], v[174:177], v[94:97]
	v_add_f32_e32 v251, v142, v251
	v_add_f32_e32 v251, v143, v251
	s_waitcnt lgkmcnt(7)
	v_mfma_f32_16x16x32_bf16 v[98:101], v[186:189], v[158:161], v[98:101]
	v_add_f32_e32 v251, v144, v251
	ds_read_b64_tr_b16 v[218:219], v242 offset:49152
	ds_read_b64_tr_b16 v[220:221], v242 offset:53248
	v_mfma_f32_16x16x32_bf16 v[102:105], v[186:189], v[174:177], v[102:105]
	v_add_f32_e32 v251, v145, v251
	v_cvt_pk_bf16_f32 v134, v134, v135
	s_waitcnt lgkmcnt(6)
	v_mfma_f32_16x16x32_bf16 v[106:109], v[190:193], v[158:161], v[106:109]
	v_cvt_pk_bf16_f32 v135, v136, v137
	ds_read_b64_tr_b16 v[222:223], v243 offset:49152
	ds_read_b64_tr_b16 v[224:225], v243 offset:53248
	v_mfma_f32_16x16x32_bf16 v[110:113], v[190:193], v[174:177], v[110:113]
	v_cvt_pk_bf16_f32 v136, v142, v143
	v_cvt_pk_bf16_f32 v137, v144, v145
	v_mfma_f32_16x16x32_bf16 v[18:21], v[202:205], v[114:117], v[18:21]
	v_exp_f32_e32 v82, v82
	v_mfma_f32_16x16x32_bf16 v[22:25], v[202:205], v[118:121], v[22:25]
	ds_read_b64_tr_b16 v[202:203], v244 offset:49152
	ds_read_b64_tr_b16 v[204:205], v244 offset:53248
	v_exp_f32_e32 v83, v83
	v_mfma_f32_16x16x32_bf16 v[26:29], v[206:209], v[114:117], v[26:29]
	v_exp_f32_e32 v84, v84
	s_add_u32 s98, s98, 0x8000
	s_addc_u32 s99, s99, 0
	s_add_u32 m0, s79, 49152
	s_nop 0
	global_load_lds_dwordx4 v246, s[98:99]
	v_mfma_f32_16x16x32_bf16 v[30:33], v[206:209], v[118:121], v[30:33]
	ds_read_b64_tr_b16 v[206:207], v245 offset:49152
	ds_read_b64_tr_b16 v[208:209], v245 offset:53248
	v_exp_f32_e32 v85, v85
	s_waitcnt lgkmcnt(10)
	v_mfma_f32_16x16x32_bf16 v[34:37], v[210:213], v[114:117], v[34:37]
	v_exp_f32_e32 v86, v86
	v_mfma_f32_16x16x32_bf16 v[38:41], v[210:213], v[118:121], v[38:41]
	ds_read_b64_tr_b16 v[210:211], v238 offset:57344
	ds_read_b64_tr_b16 v[212:213], v238 offset:61440
	v_exp_f32_e32 v87, v87
	s_waitcnt lgkmcnt(10)
	v_mfma_f32_16x16x32_bf16 v[42:45], v[214:217], v[114:117], v[42:45]
	v_exp_f32_e32 v88, v88
	s_add_u32 m0, s79, 50176
	s_nop 0
	global_load_lds_dwordx4 v247, s[98:99]
	v_mfma_f32_16x16x32_bf16 v[46:49], v[214:217], v[118:121], v[46:49]
	ds_read_b64_tr_b16 v[214:215], v239 offset:57344
	ds_read_b64_tr_b16 v[216:217], v239 offset:61440
	v_exp_f32_e32 v89, v89
	s_waitcnt lgkmcnt(10)
	v_mfma_f32_16x16x32_bf16 v[50:53], v[218:221], v[114:117], v[50:53]
	v_exp_f32_e32 v90, v90
	v_mfma_f32_16x16x32_bf16 v[54:57], v[218:221], v[118:121], v[54:57]
	ds_read_b64_tr_b16 v[218:219], v240 offset:57344
	ds_read_b64_tr_b16 v[220:221], v240 offset:61440
	v_exp_f32_e32 v91, v91
	s_waitcnt lgkmcnt(10)
; #define SBAR() __builtin_amdgcn_sched_barrier(0)
; #define SLOAD(i, k0) do { sr_[i].vs0 = St::ld8(&Vh[(long)((k0) + sr) * LDK + sc]); sr_[i].vs1 = St::ld8(&Vh[(long)((k0) + 32 + sr) * LDK + sc]); \
;     sr_[i].ks0 = St::ld8(&Kh[(long)((k0) + sr) * LDK + sc]); sr_[i].ks1 = St::ld8(&Kh[(long)((k0) + 32 + sr) * LDK + sc]); } while (0)
; #define SWAIT() do { if constexpr (SDEPTH == 2) asm volatile("s_waitcnt vmcnt(4)" ::: "memory"); else asm volatile("s_waitcnt vmcnt(0)" ::: "memory"); } while (0)
; template <typename TQ> ...
;     ...
;   for (int j = 1; j + 1 < NT; j += 2) {
;     SBAR(); SLOAD(SO, (j + SDEPTH) * KVBLK); SBAR();
;     qkt(pB0, pB1, (bf16*)((char*)K_lds + SHM_K), qr, r32, hi, negm);
;     finishSM(pA0, pA1, l_reg, pa0, pa1, pa2, pa3); SBAR();
;     pv_d0(o, vb0, pa0, pa1, pa2, pa3); partialSM(pB0, pB1, mC);
;     __syncthreads(); SWAIT(); SWRITE(0, SE);
;     __syncthreads();
;     SBAR(); if (SDEPTH == 1 || j + 3 < NT) SLOAD(SE, (j + 1 + SDEPTH) * KVBLK); SBAR();
;     qkt(pA0, pA1, K_lds, qr, r32, hi, negm);
;     finishSM(pB0, pB1, l_reg, pa0, pa1, pa2, pa3); SBAR();
;     pv_d0(o, vb0 + (int)SHM_V, pa0, pa1, pa2, pa3); partialSM(pA0, pA1, mC);
;     __syncthreads(); SWAIT(); SWRITE(1, SO);
;     __syncthreads();
;   }
	v_mfma_f32_16x16x32_bf16 v[58:61], v[222:225], v[114:117], v[58:61]
	v_exp_f32_e32 v92, v92
	s_add_u32 s100, s100, 0x8000
	s_addc_u32 s101, s101, 0
	s_add_u32 m0, s80, 32768
	s_nop 0
	global_load_lds_dwordx4 v248, s[100:101]
	v_mfma_f32_16x16x32_bf16 v[62:65], v[222:225], v[118:121], v[62:65]
	ds_read_b64_tr_b16 v[222:223], v241 offset:57344
	ds_read_b64_tr_b16 v[224:225], v241 offset:61440
	v_exp_f32_e32 v93, v93
	s_waitcnt lgkmcnt(10)
	v_mfma_f32_16x16x32_bf16 v[66:69], v[202:205], v[114:117], v[66:69]
	v_exp_f32_e32 v94, v94
	v_mfma_f32_16x16x32_bf16 v[70:73], v[202:205], v[118:121], v[70:73]
	ds_read_b64_tr_b16 v[202:203], v242 offset:57344
	ds_read_b64_tr_b16 v[204:205], v242 offset:61440
	v_exp_f32_e32 v95, v95
	s_waitcnt lgkmcnt(10)
	v_mfma_f32_16x16x32_bf16 v[74:77], v[206:209], v[114:117], v[74:77]
	v_exp_f32_e32 v96, v96
	s_add_u32 m0, s80, 33792
	s_nop 0
	global_load_lds_dwordx4 v249, s[100:101]
	v_mfma_f32_16x16x32_bf16 v[78:81], v[206:209], v[118:121], v[78:81]
	ds_read_b64_tr_b16 v[206:207], v243 offset:57344
	ds_read_b64_tr_b16 v[208:209], v243 offset:61440
	v_exp_f32_e32 v97, v97
	s_waitcnt lgkmcnt(10)
	v_mfma_f32_16x16x32_bf16 v[18:21], v[210:213], v[130:133], v[18:21]
	v_exp_f32_e32 v98, v98
	v_mfma_f32_16x16x32_bf16 v[22:25], v[210:213], v[134:137], v[22:25]
	ds_read_b64_tr_b16 v[210:211], v244 offset:57344
	ds_read_b64_tr_b16 v[212:213], v244 offset:61440
	v_exp_f32_e32 v99, v99
	s_waitcnt lgkmcnt(10)
	v_mfma_f32_16x16x32_bf16 v[26:29], v[214:217], v[130:133], v[26:29]
	v_exp_f32_e32 v100, v100
	v_mfma_f32_16x16x32_bf16 v[30:33], v[214:217], v[134:137], v[30:33]
	ds_read_b64_tr_b16 v[214:215], v245 offset:57344
	ds_read_b64_tr_b16 v[216:217], v245 offset:61440
	v_exp_f32_e32 v101, v101
	s_waitcnt lgkmcnt(10)
	v_mfma_f32_16x16x32_bf16 v[34:37], v[218:221], v[130:133], v[34:37]
	v_exp_f32_e32 v102, v102
	v_mfma_f32_16x16x32_bf16 v[38:41], v[218:221], v[134:137], v[38:41]
	v_exp_f32_e32 v103, v103
	s_waitcnt lgkmcnt(8)
	v_mfma_f32_16x16x32_bf16 v[42:45], v[222:225], v[130:133], v[42:45]
	v_exp_f32_e32 v104, v104
	v_mfma_f32_16x16x32_bf16 v[46:49], v[222:225], v[134:137], v[46:49]
	v_exp_f32_e32 v105, v105
	s_waitcnt lgkmcnt(6)
	v_mfma_f32_16x16x32_bf16 v[50:53], v[202:205], v[130:133], v[50:53]
	v_exp_f32_e32 v106, v106
	ds_read_b128 v[178:181], v234 offset:16384
	v_mfma_f32_16x16x32_bf16 v[54:57], v[202:205], v[134:137], v[54:57]
	v_exp_f32_e32 v107, v107
	s_waitcnt lgkmcnt(5)
	v_mfma_f32_16x16x32_bf16 v[58:61], v[206:209], v[130:133], v[58:61]
	v_exp_f32_e32 v108, v108
	ds_read_b128 v[182:185], v234 offset:20480
	v_mfma_f32_16x16x32_bf16 v[62:65], v[206:209], v[134:137], v[62:65]
	v_exp_f32_e32 v109, v109
	s_waitcnt lgkmcnt(4)
	v_mfma_f32_16x16x32_bf16 v[66:69], v[210:213], v[130:133], v[66:69]
	v_exp_f32_e32 v110, v110
	ds_read_b128 v[186:189], v234 offset:24576
	v_mfma_f32_16x16x32_bf16 v[70:73], v[210:213], v[134:137], v[70:73]
	v_exp_f32_e32 v111, v111
	s_waitcnt lgkmcnt(3)
	v_mfma_f32_16x16x32_bf16 v[74:77], v[214:217], v[130:133], v[74:77]
	v_exp_f32_e32 v112, v112
	ds_read_b128 v[190:193], v234 offset:28672
	v_mfma_f32_16x16x32_bf16 v[78:81], v[214:217], v[134:137], v[78:81]
	v_exp_f32_e32 v113, v113
	s_waitcnt lgkmcnt(3)
	v_mfma_f32_16x16x32_bf16 v[114:117], v[178:181], v[146:149], v[2:5]
	v_add_f32_e32 v250, v82, v250
	v_mfma_f32_16x16x32_bf16 v[118:121], v[178:181], v[162:165], v[2:5]
	ds_read_b128 v[178:181], v235 offset:16384
	v_add_f32_e32 v250, v83, v250
	v_add_f32_e32 v250, v84, v250
	s_waitcnt lgkmcnt(3)
	v_mfma_f32_16x16x32_bf16 v[122:125], v[182:185], v[146:149], v[2:5]
	v_add_f32_e32 v250, v85, v250
	v_mfma_f32_16x16x32_bf16 v[126:129], v[182:185], v[162:165], v[2:5]
	ds_read_b128 v[182:185], v235 offset:20480
	v_add_f32_e32 v250, v90, v250
	v_add_f32_e32 v250, v91, v250
	s_waitcnt lgkmcnt(3)
	v_mfma_f32_16x16x32_bf16 v[130:133], v[186:189], v[146:149], v[2:5]
	v_add_f32_e32 v250, v92, v250
	v_mfma_f32_16x16x32_bf16 v[134:137], v[186:189], v[162:165], v[2:5]
	ds_read_b128 v[186:189], v235 offset:24576
	v_add_f32_e32 v250, v93, v250
	v_cvt_pk_bf16_f32 v82, v82, v83
	s_waitcnt lgkmcnt(3)
	v_mfma_f32_16x16x32_bf16 v[138:141], v[190:193], v[146:149], v[2:5]
	v_cvt_pk_bf16_f32 v83, v84, v85
	v_mfma_f32_16x16x32_bf16 v[142:145], v[190:193], v[162:165], v[2:5]
	ds_read_b128 v[190:193], v235 offset:28672
	v_cvt_pk_bf16_f32 v84, v90, v91
	v_cvt_pk_bf16_f32 v85, v92, v93
	s_waitcnt lgkmcnt(3)
	v_mfma_f32_16x16x32_bf16 v[114:117], v[178:181], v[150:153], v[114:117]
	v_add_f32_e32 v251, v86, v251
	v_mfma_f32_16x16x32_bf16 v[118:121], v[178:181], v[166:169], v[118:121]
	ds_read_b128 v[178:181], v236 offset:16384
	v_add_f32_e32 v251, v87, v251
	v_add_f32_e32 v251, v88, v251
	s_waitcnt lgkmcnt(3)
	v_mfma_f32_16x16x32_bf16 v[122:125], v[182:185], v[150:153], v[122:125]
	v_add_f32_e32 v251, v89, v251
	v_mfma_f32_16x16x32_bf16 v[126:129], v[182:185], v[166:169], v[126:129]
	ds_read_b128 v[182:185], v236 offset:20480
	v_add_f32_e32 v251, v94, v251
	v_add_f32_e32 v251, v95, v251
	s_waitcnt lgkmcnt(3)
	v_mfma_f32_16x16x32_bf16 v[130:133], v[186:189], v[150:153], v[130:133]
	v_add_f32_e32 v251, v96, v251
	v_mfma_f32_16x16x32_bf16 v[134:137], v[186:189], v[166:169], v[134:137]
	ds_read_b128 v[186:189], v236 offset:24576
	v_add_f32_e32 v251, v97, v251
	v_cvt_pk_bf16_f32 v86, v86, v87
	s_waitcnt lgkmcnt(3)
	v_mfma_f32_16x16x32_bf16 v[138:141], v[190:193], v[150:153], v[138:141]
	v_cvt_pk_bf16_f32 v87, v88, v89
	v_mfma_f32_16x16x32_bf16 v[142:145], v[190:193], v[166:169], v[142:145]
	ds_read_b128 v[190:193], v236 offset:28672
	v_cvt_pk_bf16_f32 v88, v94, v95
	v_cvt_pk_bf16_f32 v89, v96, v97
	s_waitcnt lgkmcnt(3)
; #define SBAR() __builtin_amdgcn_sched_barrier(0)
; #define SLOAD(i, k0) do { sr_[i].vs0 = St::ld8(&Vh[(long)((k0) + sr) * LDK + sc]); sr_[i].vs1 = St::ld8(&Vh[(long)((k0) + 32 + sr) * LDK + sc]); \
;     sr_[i].ks0 = St::ld8(&Kh[(long)((k0) + sr) * LDK + sc]); sr_[i].ks1 = St::ld8(&Kh[(long)((k0) + 32 + sr) * LDK + sc]); } while (0)
; #define SWAIT() do { if constexpr (SDEPTH == 2) asm volatile("s_waitcnt vmcnt(4)" ::: "memory"); else asm volatile("s_waitcnt vmcnt(0)" ::: "memory"); } while (0)
; template <typename TQ> ...
;     ...
;   for (int j = 1; j + 1 < NT; j += 2) {
;     SBAR(); SLOAD(SO, (j + SDEPTH) * KVBLK); SBAR();
;     qkt(pB0, pB1, (bf16*)((char*)K_lds + SHM_K), qr, r32, hi, negm);
;     finishSM(pA0, pA1, l_reg, pa0, pa1, pa2, pa3); SBAR();
;     pv_d0(o, vb0, pa0, pa1, pa2, pa3); partialSM(pB0, pB1, mC);
;     __syncthreads(); SWAIT(); SWRITE(0, SE);
;     __syncthreads();
;     SBAR(); if (SDEPTH == 1 || j + 3 < NT) SLOAD(SE, (j + 1 + SDEPTH) * KVBLK); SBAR();
;     qkt(pA0, pA1, K_lds, qr, r32, hi, negm);
;     finishSM(pB0, pB1, l_reg, pa0, pa1, pa2, pa3); SBAR();
;     pv_d0(o, vb0 + (int)SHM_V, pa0, pa1, pa2, pa3); partialSM(pA0, pA1, mC);
;     __syncthreads(); SWAIT(); SWRITE(1, SO);
;     __syncthreads();
;   }
	v_mfma_f32_16x16x32_bf16 v[114:117], v[178:181], v[154:157], v[114:117]
	v_add_f32_e32 v250, v98, v250
	v_mfma_f32_16x16x32_bf16 v[118:121], v[178:181], v[170:173], v[118:121]
	ds_read_b128 v[178:181], v237 offset:16384
	v_add_f32_e32 v250, v99, v250
	v_add_f32_e32 v250, v100, v250
	s_waitcnt lgkmcnt(3)
	v_mfma_f32_16x16x32_bf16 v[122:125], v[182:185], v[154:157], v[122:125]
	v_add_f32_e32 v250, v101, v250
	v_mfma_f32_16x16x32_bf16 v[126:129], v[182:185], v[170:173], v[126:129]
	ds_read_b128 v[182:185], v237 offset:20480
	v_add_f32_e32 v250, v106, v250
	v_add_f32_e32 v250, v107, v250
	s_waitcnt lgkmcnt(3)
	v_mfma_f32_16x16x32_bf16 v[130:133], v[186:189], v[154:157], v[130:133]
	v_add_f32_e32 v250, v108, v250
	ds_read_b64_tr_b16 v[202:203], v238 offset:0
	ds_read_b64_tr_b16 v[204:205], v238 offset:4096
	v_mfma_f32_16x16x32_bf16 v[134:137], v[186:189], v[170:173], v[134:137]
	ds_read_b128 v[186:189], v237 offset:24576
	v_add_f32_e32 v250, v109, v250
	v_cvt_pk_bf16_f32 v98, v98, v99
	s_waitcnt lgkmcnt(5)
	v_mfma_f32_16x16x32_bf16 v[138:141], v[190:193], v[154:157], v[138:141]
	v_cvt_pk_bf16_f32 v99, v100, v101
	ds_read_b64_tr_b16 v[206:207], v239 offset:0
	ds_read_b64_tr_b16 v[208:209], v239 offset:4096
	v_mfma_f32_16x16x32_bf16 v[142:145], v[190:193], v[170:173], v[142:145]
	ds_read_b128 v[190:193], v237 offset:28672
	v_cvt_pk_bf16_f32 v100, v106, v107
	v_cvt_pk_bf16_f32 v101, v108, v109
	s_waitcnt lgkmcnt(7)
	v_mfma_f32_16x16x32_bf16 v[114:117], v[178:181], v[158:161], v[114:117]
	v_add_f32_e32 v251, v102, v251
	ds_read_b64_tr_b16 v[210:211], v240 offset:0
	ds_read_b64_tr_b16 v[212:213], v240 offset:4096
	v_mfma_f32_16x16x32_bf16 v[118:121], v[178:181], v[174:177], v[118:121]
	v_add_f32_e32 v251, v103, v251
	v_add_f32_e32 v251, v104, v251
	s_waitcnt lgkmcnt(8)
	v_mfma_f32_16x16x32_bf16 v[122:125], v[182:185], v[158:161], v[122:125]
	v_add_f32_e32 v251, v105, v251
	ds_read_b64_tr_b16 v[214:215], v241 offset:0
	ds_read_b64_tr_b16 v[216:217], v241 offset:4096
	v_mfma_f32_16x16x32_bf16 v[126:129], v[182:185], v[174:177], v[126:129]
	v_add_f32_e32 v251, v110, v251
	v_add_f32_e32 v251, v111, v251
	s_waitcnt lgkmcnt(7)
	v_mfma_f32_16x16x32_bf16 v[130:133], v[186:189], v[158:161], v[130:133]
	v_add_f32_e32 v251, v112, v251
	ds_read_b64_tr_b16 v[218:219], v242 offset:0
	ds_read_b64_tr_b16 v[220:221], v242 offset:4096
	v_mfma_f32_16x16x32_bf16 v[134:137], v[186:189], v[174:177], v[134:137]
	v_add_f32_e32 v251, v113, v251
	v_cvt_pk_bf16_f32 v102, v102, v103
	s_waitcnt lgkmcnt(6)
	v_mfma_f32_16x16x32_bf16 v[138:141], v[190:193], v[158:161], v[138:141]
	v_cvt_pk_bf16_f32 v103, v104, v105
	ds_read_b64_tr_b16 v[222:223], v243 offset:0
	ds_read_b64_tr_b16 v[224:225], v243 offset:4096
	v_mfma_f32_16x16x32_bf16 v[142:145], v[190:193], v[174:177], v[142:145]
	v_cvt_pk_bf16_f32 v104, v110, v111
	v_cvt_pk_bf16_f32 v105, v112, v113
	v_mfma_f32_16x16x32_bf16 v[18:21], v[202:205], v[82:85], v[18:21]
	v_exp_f32_e32 v114, v114
	v_mfma_f32_16x16x32_bf16 v[22:25], v[202:205], v[86:89], v[22:25]
	ds_read_b64_tr_b16 v[202:203], v244 offset:0
	ds_read_b64_tr_b16 v[204:205], v244 offset:4096
	v_exp_f32_e32 v115, v115
	v_mfma_f32_16x16x32_bf16 v[26:29], v[206:209], v[82:85], v[26:29]
	v_exp_f32_e32 v116, v116
	v_mfma_f32_16x16x32_bf16 v[30:33], v[206:209], v[86:89], v[30:33]
	ds_read_b64_tr_b16 v[206:207], v245 offset:0
	ds_read_b64_tr_b16 v[208:209], v245 offset:4096
	v_exp_f32_e32 v117, v117
	s_waitcnt lgkmcnt(10)
	v_mfma_f32_16x16x32_bf16 v[34:37], v[210:213], v[82:85], v[34:37]
	v_exp_f32_e32 v118, v118
	v_mfma_f32_16x16x32_bf16 v[38:41], v[210:213], v[86:89], v[38:41]
	ds_read_b64_tr_b16 v[210:211], v238 offset:8192
	ds_read_b64_tr_b16 v[212:213], v238 offset:12288
	v_exp_f32_e32 v119, v119
	s_waitcnt lgkmcnt(10)
	v_mfma_f32_16x16x32_bf16 v[42:45], v[214:217], v[82:85], v[42:45]
	v_exp_f32_e32 v120, v120
	v_mfma_f32_16x16x32_bf16 v[46:49], v[214:217], v[86:89], v[46:49]
	ds_read_b64_tr_b16 v[214:215], v239 offset:8192
	ds_read_b64_tr_b16 v[216:217], v239 offset:12288
	v_exp_f32_e32 v121, v121
	s_waitcnt lgkmcnt(10)
	v_mfma_f32_16x16x32_bf16 v[50:53], v[218:221], v[82:85], v[50:53]
	v_exp_f32_e32 v122, v122
	v_mfma_f32_16x16x32_bf16 v[54:57], v[218:221], v[86:89], v[54:57]
	ds_read_b64_tr_b16 v[218:219], v240 offset:8192
	ds_read_b64_tr_b16 v[220:221], v240 offset:12288
	v_exp_f32_e32 v123, v123
	s_waitcnt lgkmcnt(10)
	v_mfma_f32_16x16x32_bf16 v[58:61], v[222:225], v[82:85], v[58:61]
	v_exp_f32_e32 v124, v124
	v_mfma_f32_16x16x32_bf16 v[62:65], v[222:225], v[86:89], v[62:65]
	ds_read_b64_tr_b16 v[222:223], v241 offset:8192
	ds_read_b64_tr_b16 v[224:225], v241 offset:12288
	v_exp_f32_e32 v125, v125
	s_waitcnt lgkmcnt(10)
	v_mfma_f32_16x16x32_bf16 v[66:69], v[202:205], v[82:85], v[66:69]
	v_exp_f32_e32 v126, v126
	v_mfma_f32_16x16x32_bf16 v[70:73], v[202:205], v[86:89], v[70:73]
	ds_read_b64_tr_b16 v[202:203], v242 offset:8192
	ds_read_b64_tr_b16 v[204:205], v242 offset:12288
	v_exp_f32_e32 v127, v127
	s_waitcnt lgkmcnt(10)
	v_mfma_f32_16x16x32_bf16 v[74:77], v[206:209], v[82:85], v[74:77]
	v_exp_f32_e32 v128, v128
	v_mfma_f32_16x16x32_bf16 v[78:81], v[206:209], v[86:89], v[78:81]
	ds_read_b64_tr_b16 v[206:207], v243 offset:8192
	ds_read_b64_tr_b16 v[208:209], v243 offset:12288
	v_exp_f32_e32 v129, v129
	s_waitcnt lgkmcnt(10)
	v_mfma_f32_16x16x32_bf16 v[18:21], v[210:213], v[98:101], v[18:21]
	v_exp_f32_e32 v130, v130
	v_mfma_f32_16x16x32_bf16 v[22:25], v[210:213], v[102:105], v[22:25]
	ds_read_b64_tr_b16 v[210:211], v244 offset:8192
	ds_read_b64_tr_b16 v[212:213], v244 offset:12288
	v_exp_f32_e32 v131, v131
	s_waitcnt lgkmcnt(10)
; #define SBAR() __builtin_amdgcn_sched_barrier(0)
; #define SLOAD(i, k0) do { sr_[i].vs0 = St::ld8(&Vh[(long)((k0) + sr) * LDK + sc]); sr_[i].vs1 = St::ld8(&Vh[(long)((k0) + 32 + sr) * LDK + sc]); \
;     sr_[i].ks0 = St::ld8(&Kh[(long)((k0) + sr) * LDK + sc]); sr_[i].ks1 = St::ld8(&Kh[(long)((k0) + 32 + sr) * LDK + sc]); } while (0)
; #define SWAIT() do { if constexpr (SDEPTH == 2) asm volatile("s_waitcnt vmcnt(4)" ::: "memory"); else asm volatile("s_waitcnt vmcnt(0)" ::: "memory"); } while (0)
; template <typename TQ> ...
;     ...
;   for (int j = 1; j + 1 < NT; j += 2) {
;     SBAR(); SLOAD(SO, (j + SDEPTH) * KVBLK); SBAR();
;     qkt(pB0, pB1, (bf16*)((char*)K_lds + SHM_K), qr, r32, hi, negm);
;     finishSM(pA0, pA1, l_reg, pa0, pa1, pa2, pa3); SBAR();
;     pv_d0(o, vb0, pa0, pa1, pa2, pa3); partialSM(pB0, pB1, mC);
;     __syncthreads(); SWAIT(); SWRITE(0, SE);
;     __syncthreads();
;     SBAR(); if (SDEPTH == 1 || j + 3 < NT) SLOAD(SE, (j + 1 + SDEPTH) * KVBLK); SBAR();
;     qkt(pA0, pA1, K_lds, qr, r32, hi, negm);
;     finishSM(pB0, pB1, l_reg, pa0, pa1, pa2, pa3); SBAR();
;     pv_d0(o, vb0 + (int)SHM_V, pa0, pa1, pa2, pa3); partialSM(pA0, pA1, mC);
;     __syncthreads(); SWAIT(); SWRITE(1, SO);
;     __syncthreads();
;   }
;   SBAR(); qkt(pB0, pB1, (bf16*)((char*)K_lds + SHM_K), qr, r32, hi, negm);
;   finishSM(pA0, pA1, l_reg, pa0, pa1, pa2, pa3); SBAR();
;   pv_d0(o, vb0, pa0, pa1, pa2, pa3); partialSM(pB0, pB1, mC);
;   __syncthreads();
;   finishSM(pB0, pB1, l_reg, pa0, pa1, pa2, pa3); SBAR();
;   pv_d0(o, vb0 + (int)SHM_V, pa0, pa1, pa2, pa3);
	v_mfma_f32_16x16x32_bf16 v[26:29], v[214:217], v[98:101], v[26:29]
	v_exp_f32_e32 v132, v132
	v_mfma_f32_16x16x32_bf16 v[30:33], v[214:217], v[102:105], v[30:33]
	ds_read_b64_tr_b16 v[214:215], v245 offset:8192
	ds_read_b64_tr_b16 v[216:217], v245 offset:12288
	v_exp_f32_e32 v133, v133
	s_waitcnt lgkmcnt(10)
	v_mfma_f32_16x16x32_bf16 v[34:37], v[218:221], v[98:101], v[34:37]
	v_exp_f32_e32 v134, v134
	v_mfma_f32_16x16x32_bf16 v[38:41], v[218:221], v[102:105], v[38:41]
	v_exp_f32_e32 v135, v135
	s_waitcnt lgkmcnt(8)
	v_mfma_f32_16x16x32_bf16 v[42:45], v[222:225], v[98:101], v[42:45]
	v_exp_f32_e32 v136, v136
	v_mfma_f32_16x16x32_bf16 v[46:49], v[222:225], v[102:105], v[46:49]
	v_exp_f32_e32 v137, v137
	s_waitcnt lgkmcnt(6)
	v_mfma_f32_16x16x32_bf16 v[50:53], v[202:205], v[98:101], v[50:53]
	v_exp_f32_e32 v138, v138
	v_mfma_f32_16x16x32_bf16 v[54:57], v[202:205], v[102:105], v[54:57]
	v_exp_f32_e32 v139, v139
	s_waitcnt lgkmcnt(4)
	v_mfma_f32_16x16x32_bf16 v[58:61], v[206:209], v[98:101], v[58:61]
	v_exp_f32_e32 v140, v140
	v_mfma_f32_16x16x32_bf16 v[62:65], v[206:209], v[102:105], v[62:65]
	v_exp_f32_e32 v141, v141
	s_waitcnt lgkmcnt(2)
	v_mfma_f32_16x16x32_bf16 v[66:69], v[210:213], v[98:101], v[66:69]
	v_exp_f32_e32 v142, v142
	v_mfma_f32_16x16x32_bf16 v[70:73], v[210:213], v[102:105], v[70:73]
	v_exp_f32_e32 v143, v143
	s_waitcnt lgkmcnt(0)
	v_mfma_f32_16x16x32_bf16 v[74:77], v[214:217], v[98:101], v[74:77]
	v_exp_f32_e32 v144, v144
	v_mfma_f32_16x16x32_bf16 v[78:81], v[214:217], v[102:105], v[78:81]
	v_exp_f32_e32 v145, v145
	s_waitcnt vmcnt(0)
	s_add_i32 s15, s15, 1
	s_cmp_lt_u32 s15, 32
	s_cbranch_scc1 .Lattn_loop
	s_barrier
	ds_read_b128 v[178:181], v234 offset:32768
	ds_read_b128 v[182:185], v234 offset:36864
	ds_read_b128 v[186:189], v234 offset:40960
	ds_read_b128 v[190:193], v234 offset:45056
	v_add_f32_e32 v250, v114, v250
	v_add_f32_e32 v250, v115, v250
	v_add_f32_e32 v250, v116, v250
	v_add_f32_e32 v250, v117, v250
	v_add_f32_e32 v250, v122, v250
	v_add_f32_e32 v250, v123, v250
	v_add_f32_e32 v250, v124, v250
	v_add_f32_e32 v250, v125, v250
	v_cvt_pk_bf16_f32 v114, v114, v115
	v_cvt_pk_bf16_f32 v115, v116, v117
	v_cvt_pk_bf16_f32 v116, v122, v123
	v_cvt_pk_bf16_f32 v117, v124, v125
	s_waitcnt lgkmcnt(3)
	v_mfma_f32_16x16x32_bf16 v[82:85], v[178:181], v[146:149], v[2:5]
	v_mfma_f32_16x16x32_bf16 v[86:89], v[178:181], v[162:165], v[2:5]
	ds_read_b128 v[178:181], v235 offset:32768
	s_waitcnt lgkmcnt(3)
	v_mfma_f32_16x16x32_bf16 v[90:93], v[182:185], v[146:149], v[2:5]
	s_add_u32 s100, s100, 0x8000
	s_addc_u32 s101, s101, 0
	s_add_u32 m0, s80, 49152
	s_nop 0
	global_load_lds_dwordx4 v248, s[100:101]
	v_mfma_f32_16x16x32_bf16 v[94:97], v[182:185], v[162:165], v[2:5]
	ds_read_b128 v[182:185], v235 offset:36864
	s_waitcnt lgkmcnt(3)
	v_mfma_f32_16x16x32_bf16 v[98:101], v[186:189], v[146:149], v[2:5]
	v_mfma_f32_16x16x32_bf16 v[102:105], v[186:189], v[162:165], v[2:5]
	ds_read_b128 v[186:189], v235 offset:40960
	s_waitcnt lgkmcnt(3)
	v_mfma_f32_16x16x32_bf16 v[106:109], v[190:193], v[146:149], v[2:5]
	s_add_u32 m0, s80, 50176
	s_nop 0
	global_load_lds_dwordx4 v249, s[100:101]
	v_mfma_f32_16x16x32_bf16 v[110:113], v[190:193], v[162:165], v[2:5]
	ds_read_b128 v[190:193], v235 offset:45056
	s_waitcnt lgkmcnt(3)
	v_mfma_f32_16x16x32_bf16 v[82:85], v[178:181], v[150:153], v[82:85]
	v_add_f32_e32 v251, v118, v251
	v_mfma_f32_16x16x32_bf16 v[86:89], v[178:181], v[166:169], v[86:89]
	ds_read_b128 v[178:181], v236 offset:32768
	v_add_f32_e32 v251, v119, v251
	v_add_f32_e32 v251, v120, v251
	s_waitcnt lgkmcnt(3)
	v_mfma_f32_16x16x32_bf16 v[90:93], v[182:185], v[150:153], v[90:93]
	v_add_f32_e32 v251, v121, v251
	v_mfma_f32_16x16x32_bf16 v[94:97], v[182:185], v[166:169], v[94:97]
	ds_read_b128 v[182:185], v236 offset:36864
	v_add_f32_e32 v251, v126, v251
	v_add_f32_e32 v251, v127, v251
	s_waitcnt lgkmcnt(3)
	v_mfma_f32_16x16x32_bf16 v[98:101], v[186:189], v[150:153], v[98:101]
	v_add_f32_e32 v251, v128, v251
	v_mfma_f32_16x16x32_bf16 v[102:105], v[186:189], v[166:169], v[102:105]
	ds_read_b128 v[186:189], v236 offset:40960
	v_add_f32_e32 v251, v129, v251
	v_cvt_pk_bf16_f32 v118, v118, v119
	s_waitcnt lgkmcnt(3)
	v_mfma_f32_16x16x32_bf16 v[106:109], v[190:193], v[150:153], v[106:109]
	v_cvt_pk_bf16_f32 v119, v120, v121
	v_mfma_f32_16x16x32_bf16 v[110:113], v[190:193], v[166:169], v[110:113]
	ds_read_b128 v[190:193], v236 offset:45056
	v_cvt_pk_bf16_f32 v120, v126, v127
	v_cvt_pk_bf16_f32 v121, v128, v129
	s_waitcnt lgkmcnt(3)
	v_mfma_f32_16x16x32_bf16 v[82:85], v[178:181], v[154:157], v[82:85]
	v_add_f32_e32 v250, v130, v250
	v_mfma_f32_16x16x32_bf16 v[86:89], v[178:181], v[170:173], v[86:89]
	ds_read_b128 v[178:181], v237 offset:32768
	v_add_f32_e32 v250, v131, v250
	v_add_f32_e32 v250, v132, v250
	s_waitcnt lgkmcnt(3)
	v_mfma_f32_16x16x32_bf16 v[90:93], v[182:185], v[154:157], v[90:93]
	v_add_f32_e32 v250, v133, v250
	v_mfma_f32_16x16x32_bf16 v[94:97], v[182:185], v[170:173], v[94:97]
	ds_read_b128 v[182:185], v237 offset:36864
	v_add_f32_e32 v250, v138, v250
	v_add_f32_e32 v250, v139, v250
	s_waitcnt lgkmcnt(3)
	v_mfma_f32_16x16x32_bf16 v[98:101], v[186:189], v[154:157], v[98:101]
	v_add_f32_e32 v250, v140, v250
	ds_read_b64_tr_b16 v[202:203], v238 offset:16384
	ds_read_b64_tr_b16 v[204:205], v238 offset:20480
	v_mfma_f32_16x16x32_bf16 v[102:105], v[186:189], v[170:173], v[102:105]
	ds_read_b128 v[186:189], v237 offset:40960
	v_add_f32_e32 v250, v141, v250
	v_cvt_pk_bf16_f32 v130, v130, v131
	s_waitcnt lgkmcnt(5)
; #define SBAR() __builtin_amdgcn_sched_barrier(0)
; template <typename TQ> ...
;     ...
;   SBAR(); qkt(pB0, pB1, (bf16*)((char*)K_lds + SHM_K), qr, r32, hi, negm);
;   finishSM(pA0, pA1, l_reg, pa0, pa1, pa2, pa3); SBAR();
;   pv_d0(o, vb0, pa0, pa1, pa2, pa3); partialSM(pB0, pB1, mC);
;   __syncthreads();
;   finishSM(pB0, pB1, l_reg, pa0, pa1, pa2, pa3); SBAR();
;   pv_d0(o, vb0 + (int)SHM_V, pa0, pa1, pa2, pa3);
	v_mfma_f32_16x16x32_bf16 v[106:109], v[190:193], v[154:157], v[106:109]
	v_cvt_pk_bf16_f32 v131, v132, v133
	ds_read_b64_tr_b16 v[206:207], v239 offset:16384
	ds_read_b64_tr_b16 v[208:209], v239 offset:20480
	v_mfma_f32_16x16x32_bf16 v[110:113], v[190:193], v[170:173], v[110:113]
	ds_read_b128 v[190:193], v237 offset:45056
	v_cvt_pk_bf16_f32 v132, v138, v139
	v_cvt_pk_bf16_f32 v133, v140, v141
	s_waitcnt lgkmcnt(7)
	v_mfma_f32_16x16x32_bf16 v[82:85], v[178:181], v[158:161], v[82:85]
	v_add_f32_e32 v251, v134, v251
	ds_read_b64_tr_b16 v[210:211], v240 offset:16384
	ds_read_b64_tr_b16 v[212:213], v240 offset:20480
	v_mfma_f32_16x16x32_bf16 v[86:89], v[178:181], v[174:177], v[86:89]
	v_add_f32_e32 v251, v135, v251
	v_add_f32_e32 v251, v136, v251
	s_waitcnt lgkmcnt(8)
	v_mfma_f32_16x16x32_bf16 v[90:93], v[182:185], v[158:161], v[90:93]
	v_add_f32_e32 v251, v137, v251
	ds_read_b64_tr_b16 v[214:215], v241 offset:16384
	ds_read_b64_tr_b16 v[216:217], v241 offset:20480
	v_mfma_f32_16x16x32_bf16 v[94:97], v[182:185], v[174:177], v[94:97]
	v_add_f32_e32 v251, v142, v251
	v_add_f32_e32 v251, v143, v251
	s_waitcnt lgkmcnt(7)
	v_mfma_f32_16x16x32_bf16 v[98:101], v[186:189], v[158:161], v[98:101]
	v_add_f32_e32 v251, v144, v251
	ds_read_b64_tr_b16 v[218:219], v242 offset:16384
	ds_read_b64_tr_b16 v[220:221], v242 offset:20480
	v_mfma_f32_16x16x32_bf16 v[102:105], v[186:189], v[174:177], v[102:105]
	v_add_f32_e32 v251, v145, v251
	v_cvt_pk_bf16_f32 v134, v134, v135
	s_waitcnt lgkmcnt(6)
	v_mfma_f32_16x16x32_bf16 v[106:109], v[190:193], v[158:161], v[106:109]
	v_cvt_pk_bf16_f32 v135, v136, v137
	ds_read_b64_tr_b16 v[222:223], v243 offset:16384
	ds_read_b64_tr_b16 v[224:225], v243 offset:20480
	v_mfma_f32_16x16x32_bf16 v[110:113], v[190:193], v[174:177], v[110:113]
	v_cvt_pk_bf16_f32 v136, v142, v143
	v_cvt_pk_bf16_f32 v137, v144, v145
	v_mfma_f32_16x16x32_bf16 v[18:21], v[202:205], v[114:117], v[18:21]
	v_exp_f32_e32 v82, v82
	v_mfma_f32_16x16x32_bf16 v[22:25], v[202:205], v[118:121], v[22:25]
	ds_read_b64_tr_b16 v[202:203], v244 offset:16384
	ds_read_b64_tr_b16 v[204:205], v244 offset:20480
	v_exp_f32_e32 v83, v83
	v_mfma_f32_16x16x32_bf16 v[26:29], v[206:209], v[114:117], v[26:29]
	v_exp_f32_e32 v84, v84
	v_mfma_f32_16x16x32_bf16 v[30:33], v[206:209], v[118:121], v[30:33]
	ds_read_b64_tr_b16 v[206:207], v245 offset:16384
	ds_read_b64_tr_b16 v[208:209], v245 offset:20480
	v_exp_f32_e32 v85, v85
	s_waitcnt lgkmcnt(10)
	v_mfma_f32_16x16x32_bf16 v[34:37], v[210:213], v[114:117], v[34:37]
	v_exp_f32_e32 v86, v86
	v_mfma_f32_16x16x32_bf16 v[38:41], v[210:213], v[118:121], v[38:41]
	ds_read_b64_tr_b16 v[210:211], v238 offset:24576
	ds_read_b64_tr_b16 v[212:213], v238 offset:28672
	v_exp_f32_e32 v87, v87
	s_waitcnt lgkmcnt(10)
	v_mfma_f32_16x16x32_bf16 v[42:45], v[214:217], v[114:117], v[42:45]
	v_exp_f32_e32 v88, v88
	v_mfma_f32_16x16x32_bf16 v[46:49], v[214:217], v[118:121], v[46:49]
	ds_read_b64_tr_b16 v[214:215], v239 offset:24576
	ds_read_b64_tr_b16 v[216:217], v239 offset:28672
	v_exp_f32_e32 v89, v89
	s_waitcnt lgkmcnt(10)
	v_mfma_f32_16x16x32_bf16 v[50:53], v[218:221], v[114:117], v[50:53]
	v_exp_f32_e32 v90, v90
	v_mfma_f32_16x16x32_bf16 v[54:57], v[218:221], v[118:121], v[54:57]
	ds_read_b64_tr_b16 v[218:219], v240 offset:24576
	ds_read_b64_tr_b16 v[220:221], v240 offset:28672
	v_exp_f32_e32 v91, v91
	s_waitcnt lgkmcnt(10)
	v_mfma_f32_16x16x32_bf16 v[58:61], v[222:225], v[114:117], v[58:61]
	v_exp_f32_e32 v92, v92
	v_mfma_f32_16x16x32_bf16 v[62:65], v[222:225], v[118:121], v[62:65]
	ds_read_b64_tr_b16 v[222:223], v241 offset:24576
	ds_read_b64_tr_b16 v[224:225], v241 offset:28672
	v_exp_f32_e32 v93, v93
	s_waitcnt lgkmcnt(10)
	v_mfma_f32_16x16x32_bf16 v[66:69], v[202:205], v[114:117], v[66:69]
	v_exp_f32_e32 v94, v94
	v_mfma_f32_16x16x32_bf16 v[70:73], v[202:205], v[118:121], v[70:73]
	ds_read_b64_tr_b16 v[202:203], v242 offset:24576
	ds_read_b64_tr_b16 v[204:205], v242 offset:28672
	v_exp_f32_e32 v95, v95
	s_waitcnt lgkmcnt(10)
	v_mfma_f32_16x16x32_bf16 v[74:77], v[206:209], v[114:117], v[74:77]
	v_exp_f32_e32 v96, v96
	v_mfma_f32_16x16x32_bf16 v[78:81], v[206:209], v[118:121], v[78:81]
	ds_read_b64_tr_b16 v[206:207], v243 offset:24576
	ds_read_b64_tr_b16 v[208:209], v243 offset:28672
	v_exp_f32_e32 v97, v97
	s_waitcnt lgkmcnt(10)
	v_mfma_f32_16x16x32_bf16 v[18:21], v[210:213], v[130:133], v[18:21]
	v_exp_f32_e32 v98, v98
	v_mfma_f32_16x16x32_bf16 v[22:25], v[210:213], v[134:137], v[22:25]
	ds_read_b64_tr_b16 v[210:211], v244 offset:24576
	ds_read_b64_tr_b16 v[212:213], v244 offset:28672
	v_exp_f32_e32 v99, v99
	s_waitcnt lgkmcnt(10)
	v_mfma_f32_16x16x32_bf16 v[26:29], v[214:217], v[130:133], v[26:29]
	v_exp_f32_e32 v100, v100
	v_mfma_f32_16x16x32_bf16 v[30:33], v[214:217], v[134:137], v[30:33]
	ds_read_b64_tr_b16 v[214:215], v245 offset:24576
	ds_read_b64_tr_b16 v[216:217], v245 offset:28672
	v_exp_f32_e32 v101, v101
	s_waitcnt lgkmcnt(10)
	v_mfma_f32_16x16x32_bf16 v[34:37], v[218:221], v[130:133], v[34:37]
	v_exp_f32_e32 v102, v102
	v_mfma_f32_16x16x32_bf16 v[38:41], v[218:221], v[134:137], v[38:41]
	v_exp_f32_e32 v103, v103
	s_waitcnt lgkmcnt(8)
	v_mfma_f32_16x16x32_bf16 v[42:45], v[222:225], v[130:133], v[42:45]
	v_exp_f32_e32 v104, v104
	v_mfma_f32_16x16x32_bf16 v[46:49], v[222:225], v[134:137], v[46:49]
	v_exp_f32_e32 v105, v105
	s_waitcnt lgkmcnt(6)
	v_mfma_f32_16x16x32_bf16 v[50:53], v[202:205], v[130:133], v[50:53]
	v_exp_f32_e32 v106, v106
	ds_read_b128 v[178:181], v234 offset:49152
	v_mfma_f32_16x16x32_bf16 v[54:57], v[202:205], v[134:137], v[54:57]
	v_exp_f32_e32 v107, v107
	s_waitcnt lgkmcnt(5)
; #define SBAR() __builtin_amdgcn_sched_barrier(0)
; template <typename TQ> ...
;     ...
;   SBAR(); qkt(pB0, pB1, (bf16*)((char*)K_lds + SHM_K), qr, r32, hi, negm);
;   finishSM(pA0, pA1, l_reg, pa0, pa1, pa2, pa3); SBAR();
;   pv_d0(o, vb0, pa0, pa1, pa2, pa3); partialSM(pB0, pB1, mC);
;   __syncthreads();
;   finishSM(pB0, pB1, l_reg, pa0, pa1, pa2, pa3); SBAR();
	v_mfma_f32_16x16x32_bf16 v[58:61], v[206:209], v[130:133], v[58:61]
	v_exp_f32_e32 v108, v108
	ds_read_b128 v[182:185], v234 offset:53248
	v_mfma_f32_16x16x32_bf16 v[62:65], v[206:209], v[134:137], v[62:65]
	v_exp_f32_e32 v109, v109
	s_waitcnt lgkmcnt(4)
	v_mfma_f32_16x16x32_bf16 v[66:69], v[210:213], v[130:133], v[66:69]
	v_exp_f32_e32 v110, v110
	ds_read_b128 v[186:189], v234 offset:57344
	v_mfma_f32_16x16x32_bf16 v[70:73], v[210:213], v[134:137], v[70:73]
	v_exp_f32_e32 v111, v111
	s_waitcnt lgkmcnt(3)
	v_mfma_f32_16x16x32_bf16 v[74:77], v[214:217], v[130:133], v[74:77]
	v_exp_f32_e32 v112, v112
	ds_read_b128 v[190:193], v234 offset:61440
	v_mfma_f32_16x16x32_bf16 v[78:81], v[214:217], v[134:137], v[78:81]
	v_exp_f32_e32 v113, v113
	s_waitcnt lgkmcnt(3)
	v_mfma_f32_16x16x32_bf16 v[114:117], v[178:181], v[146:149], v[2:5]
	v_add_f32_e32 v250, v82, v250
	v_mfma_f32_16x16x32_bf16 v[118:121], v[178:181], v[162:165], v[2:5]
	ds_read_b128 v[178:181], v235 offset:49152
	v_add_f32_e32 v250, v83, v250
	v_add_f32_e32 v250, v84, v250
	s_waitcnt lgkmcnt(3)
	v_mfma_f32_16x16x32_bf16 v[122:125], v[182:185], v[146:149], v[2:5]
	v_add_f32_e32 v250, v85, v250
	v_mfma_f32_16x16x32_bf16 v[126:129], v[182:185], v[162:165], v[2:5]
	ds_read_b128 v[182:185], v235 offset:53248
	v_add_f32_e32 v250, v90, v250
	v_add_f32_e32 v250, v91, v250
	s_waitcnt lgkmcnt(3)
	v_mfma_f32_16x16x32_bf16 v[130:133], v[186:189], v[146:149], v[2:5]
	v_add_f32_e32 v250, v92, v250
	v_mfma_f32_16x16x32_bf16 v[134:137], v[186:189], v[162:165], v[2:5]
	ds_read_b128 v[186:189], v235 offset:57344
	v_add_f32_e32 v250, v93, v250
	v_cvt_pk_bf16_f32 v82, v82, v83
	s_waitcnt lgkmcnt(3)
	v_mfma_f32_16x16x32_bf16 v[138:141], v[190:193], v[146:149], v[2:5]
	v_cvt_pk_bf16_f32 v83, v84, v85
	v_mfma_f32_16x16x32_bf16 v[142:145], v[190:193], v[162:165], v[2:5]
	ds_read_b128 v[190:193], v235 offset:61440
	v_cvt_pk_bf16_f32 v84, v90, v91
	v_cvt_pk_bf16_f32 v85, v92, v93
	s_waitcnt lgkmcnt(3)
	v_mfma_f32_16x16x32_bf16 v[114:117], v[178:181], v[150:153], v[114:117]
	v_add_f32_e32 v251, v86, v251
	v_mfma_f32_16x16x32_bf16 v[118:121], v[178:181], v[166:169], v[118:121]
	ds_read_b128 v[178:181], v236 offset:49152
	v_add_f32_e32 v251, v87, v251
	v_add_f32_e32 v251, v88, v251
	s_waitcnt lgkmcnt(3)
	v_mfma_f32_16x16x32_bf16 v[122:125], v[182:185], v[150:153], v[122:125]
	v_add_f32_e32 v251, v89, v251
	v_mfma_f32_16x16x32_bf16 v[126:129], v[182:185], v[166:169], v[126:129]
	ds_read_b128 v[182:185], v236 offset:53248
	v_add_f32_e32 v251, v94, v251
	v_add_f32_e32 v251, v95, v251
	s_waitcnt lgkmcnt(3)
	v_mfma_f32_16x16x32_bf16 v[130:133], v[186:189], v[150:153], v[130:133]
	v_add_f32_e32 v251, v96, v251
	v_mfma_f32_16x16x32_bf16 v[134:137], v[186:189], v[166:169], v[134:137]
	ds_read_b128 v[186:189], v236 offset:57344
	v_add_f32_e32 v251, v97, v251
	v_cvt_pk_bf16_f32 v86, v86, v87
	s_waitcnt lgkmcnt(3)
	v_mfma_f32_16x16x32_bf16 v[138:141], v[190:193], v[150:153], v[138:141]
	v_cvt_pk_bf16_f32 v87, v88, v89
	v_mfma_f32_16x16x32_bf16 v[142:145], v[190:193], v[166:169], v[142:145]
	ds_read_b128 v[190:193], v236 offset:61440
	v_cvt_pk_bf16_f32 v88, v94, v95
	v_cvt_pk_bf16_f32 v89, v96, v97
	s_waitcnt lgkmcnt(3)
	v_mfma_f32_16x16x32_bf16 v[114:117], v[178:181], v[154:157], v[114:117]
	v_add_f32_e32 v250, v98, v250
	v_mfma_f32_16x16x32_bf16 v[118:121], v[178:181], v[170:173], v[118:121]
	ds_read_b128 v[178:181], v237 offset:49152
	v_add_f32_e32 v250, v99, v250
	v_add_f32_e32 v250, v100, v250
	s_waitcnt lgkmcnt(3)
	v_mfma_f32_16x16x32_bf16 v[122:125], v[182:185], v[154:157], v[122:125]
	v_add_f32_e32 v250, v101, v250
	v_mfma_f32_16x16x32_bf16 v[126:129], v[182:185], v[170:173], v[126:129]
	ds_read_b128 v[182:185], v237 offset:53248
	v_add_f32_e32 v250, v106, v250
	v_add_f32_e32 v250, v107, v250
	s_waitcnt lgkmcnt(3)
	v_mfma_f32_16x16x32_bf16 v[130:133], v[186:189], v[154:157], v[130:133]
	v_add_f32_e32 v250, v108, v250
	ds_read_b64_tr_b16 v[202:203], v238 offset:32768
	ds_read_b64_tr_b16 v[204:205], v238 offset:36864
	v_mfma_f32_16x16x32_bf16 v[134:137], v[186:189], v[170:173], v[134:137]
	ds_read_b128 v[186:189], v237 offset:57344
	v_add_f32_e32 v250, v109, v250
	v_cvt_pk_bf16_f32 v98, v98, v99
	s_waitcnt lgkmcnt(5)
	v_mfma_f32_16x16x32_bf16 v[138:141], v[190:193], v[154:157], v[138:141]
	v_cvt_pk_bf16_f32 v99, v100, v101
	ds_read_b64_tr_b16 v[206:207], v239 offset:32768
	ds_read_b64_tr_b16 v[208:209], v239 offset:36864
	v_mfma_f32_16x16x32_bf16 v[142:145], v[190:193], v[170:173], v[142:145]
	ds_read_b128 v[190:193], v237 offset:61440
	v_cvt_pk_bf16_f32 v100, v106, v107
	v_cvt_pk_bf16_f32 v101, v108, v109
	s_waitcnt lgkmcnt(7)
	v_mfma_f32_16x16x32_bf16 v[114:117], v[178:181], v[158:161], v[114:117]
	v_add_f32_e32 v251, v102, v251
	ds_read_b64_tr_b16 v[210:211], v240 offset:32768
	ds_read_b64_tr_b16 v[212:213], v240 offset:36864
	v_mfma_f32_16x16x32_bf16 v[118:121], v[178:181], v[174:177], v[118:121]
	v_add_f32_e32 v251, v103, v251
	v_add_f32_e32 v251, v104, v251
	s_waitcnt lgkmcnt(8)
	v_mfma_f32_16x16x32_bf16 v[122:125], v[182:185], v[158:161], v[122:125]
	v_add_f32_e32 v251, v105, v251
	ds_read_b64_tr_b16 v[214:215], v241 offset:32768
	ds_read_b64_tr_b16 v[216:217], v241 offset:36864
	v_mfma_f32_16x16x32_bf16 v[126:129], v[182:185], v[174:177], v[126:129]
	v_add_f32_e32 v251, v110, v251
	v_add_f32_e32 v251, v111, v251
	s_waitcnt lgkmcnt(7)
	v_mfma_f32_16x16x32_bf16 v[130:133], v[186:189], v[158:161], v[130:133]
	v_add_f32_e32 v251, v112, v251
	ds_read_b64_tr_b16 v[218:219], v242 offset:32768
	ds_read_b64_tr_b16 v[220:221], v242 offset:36864
	v_mfma_f32_16x16x32_bf16 v[134:137], v[186:189], v[174:177], v[134:137]
	v_add_f32_e32 v251, v113, v251
	v_cvt_pk_bf16_f32 v102, v102, v103
	s_waitcnt lgkmcnt(6)
; #define SBAR() __builtin_amdgcn_sched_barrier(0)
; template <typename TQ> ...
;     ...
;   SBAR(); qkt(pB0, pB1, (bf16*)((char*)K_lds + SHM_K), qr, r32, hi, negm);
;   finishSM(pA0, pA1, l_reg, pa0, pa1, pa2, pa3); SBAR();
;   pv_d0(o, vb0, pa0, pa1, pa2, pa3); partialSM(pB0, pB1, mC);
;   __syncthreads();
;   finishSM(pB0, pB1, l_reg, pa0, pa1, pa2, pa3); SBAR();
;   pv_d0(o, vb0 + (int)SHM_V, pa0, pa1, pa2, pa3);
	v_mfma_f32_16x16x32_bf16 v[138:141], v[190:193], v[158:161], v[138:141]
	v_cvt_pk_bf16_f32 v103, v104, v105
	ds_read_b64_tr_b16 v[222:223], v243 offset:32768
	ds_read_b64_tr_b16 v[224:225], v243 offset:36864
	v_mfma_f32_16x16x32_bf16 v[142:145], v[190:193], v[174:177], v[142:145]
	v_cvt_pk_bf16_f32 v104, v110, v111
	v_cvt_pk_bf16_f32 v105, v112, v113
	v_mfma_f32_16x16x32_bf16 v[18:21], v[202:205], v[82:85], v[18:21]
	v_exp_f32_e32 v114, v114
	v_mfma_f32_16x16x32_bf16 v[22:25], v[202:205], v[86:89], v[22:25]
	ds_read_b64_tr_b16 v[202:203], v244 offset:32768
	ds_read_b64_tr_b16 v[204:205], v244 offset:36864
	v_exp_f32_e32 v115, v115
	v_mfma_f32_16x16x32_bf16 v[26:29], v[206:209], v[82:85], v[26:29]
	v_exp_f32_e32 v116, v116
	v_mfma_f32_16x16x32_bf16 v[30:33], v[206:209], v[86:89], v[30:33]
	ds_read_b64_tr_b16 v[206:207], v245 offset:32768
	ds_read_b64_tr_b16 v[208:209], v245 offset:36864
	v_exp_f32_e32 v117, v117
	s_waitcnt lgkmcnt(10)
	v_mfma_f32_16x16x32_bf16 v[34:37], v[210:213], v[82:85], v[34:37]
	v_exp_f32_e32 v118, v118
	v_mfma_f32_16x16x32_bf16 v[38:41], v[210:213], v[86:89], v[38:41]
	ds_read_b64_tr_b16 v[210:211], v238 offset:40960
	ds_read_b64_tr_b16 v[212:213], v238 offset:45056
	v_exp_f32_e32 v119, v119
	s_waitcnt lgkmcnt(10)
	v_mfma_f32_16x16x32_bf16 v[42:45], v[214:217], v[82:85], v[42:45]
	v_exp_f32_e32 v120, v120
	v_mfma_f32_16x16x32_bf16 v[46:49], v[214:217], v[86:89], v[46:49]
	ds_read_b64_tr_b16 v[214:215], v239 offset:40960
	ds_read_b64_tr_b16 v[216:217], v239 offset:45056
	v_exp_f32_e32 v121, v121
	s_waitcnt lgkmcnt(10)
	v_mfma_f32_16x16x32_bf16 v[50:53], v[218:221], v[82:85], v[50:53]
	v_exp_f32_e32 v122, v122
	v_mfma_f32_16x16x32_bf16 v[54:57], v[218:221], v[86:89], v[54:57]
	ds_read_b64_tr_b16 v[218:219], v240 offset:40960
	ds_read_b64_tr_b16 v[220:221], v240 offset:45056
	v_exp_f32_e32 v123, v123
	s_waitcnt lgkmcnt(10)
	v_mfma_f32_16x16x32_bf16 v[58:61], v[222:225], v[82:85], v[58:61]
	v_exp_f32_e32 v124, v124
	v_mfma_f32_16x16x32_bf16 v[62:65], v[222:225], v[86:89], v[62:65]
	ds_read_b64_tr_b16 v[222:223], v241 offset:40960
	ds_read_b64_tr_b16 v[224:225], v241 offset:45056
	v_exp_f32_e32 v125, v125
	s_waitcnt lgkmcnt(10)
	v_mfma_f32_16x16x32_bf16 v[66:69], v[202:205], v[82:85], v[66:69]
	v_exp_f32_e32 v126, v126
	v_mfma_f32_16x16x32_bf16 v[70:73], v[202:205], v[86:89], v[70:73]
	ds_read_b64_tr_b16 v[202:203], v242 offset:40960
	ds_read_b64_tr_b16 v[204:205], v242 offset:45056
	v_exp_f32_e32 v127, v127
	s_waitcnt lgkmcnt(10)
	v_mfma_f32_16x16x32_bf16 v[74:77], v[206:209], v[82:85], v[74:77]
	v_exp_f32_e32 v128, v128
	v_mfma_f32_16x16x32_bf16 v[78:81], v[206:209], v[86:89], v[78:81]
	ds_read_b64_tr_b16 v[206:207], v243 offset:40960
	ds_read_b64_tr_b16 v[208:209], v243 offset:45056
	v_exp_f32_e32 v129, v129
	s_waitcnt lgkmcnt(10)
	v_mfma_f32_16x16x32_bf16 v[18:21], v[210:213], v[98:101], v[18:21]
	v_exp_f32_e32 v130, v130
	v_mfma_f32_16x16x32_bf16 v[22:25], v[210:213], v[102:105], v[22:25]
	ds_read_b64_tr_b16 v[210:211], v244 offset:40960
	ds_read_b64_tr_b16 v[212:213], v244 offset:45056
	v_exp_f32_e32 v131, v131
	s_waitcnt lgkmcnt(10)
	v_mfma_f32_16x16x32_bf16 v[26:29], v[214:217], v[98:101], v[26:29]
	v_exp_f32_e32 v132, v132
	v_mfma_f32_16x16x32_bf16 v[30:33], v[214:217], v[102:105], v[30:33]
	ds_read_b64_tr_b16 v[214:215], v245 offset:40960
	ds_read_b64_tr_b16 v[216:217], v245 offset:45056
	v_exp_f32_e32 v133, v133
	s_waitcnt lgkmcnt(10)
	v_mfma_f32_16x16x32_bf16 v[34:37], v[218:221], v[98:101], v[34:37]
	v_exp_f32_e32 v134, v134
	v_mfma_f32_16x16x32_bf16 v[38:41], v[218:221], v[102:105], v[38:41]
	v_exp_f32_e32 v135, v135
	s_waitcnt lgkmcnt(8)
	v_mfma_f32_16x16x32_bf16 v[42:45], v[222:225], v[98:101], v[42:45]
	v_exp_f32_e32 v136, v136
	v_mfma_f32_16x16x32_bf16 v[46:49], v[222:225], v[102:105], v[46:49]
	v_exp_f32_e32 v137, v137
	s_waitcnt lgkmcnt(6)
	v_mfma_f32_16x16x32_bf16 v[50:53], v[202:205], v[98:101], v[50:53]
	v_exp_f32_e32 v138, v138
	v_mfma_f32_16x16x32_bf16 v[54:57], v[202:205], v[102:105], v[54:57]
	v_exp_f32_e32 v139, v139
	s_waitcnt lgkmcnt(4)
	v_mfma_f32_16x16x32_bf16 v[58:61], v[206:209], v[98:101], v[58:61]
	v_exp_f32_e32 v140, v140
	v_mfma_f32_16x16x32_bf16 v[62:65], v[206:209], v[102:105], v[62:65]
	v_exp_f32_e32 v141, v141
	s_waitcnt lgkmcnt(2)
	v_mfma_f32_16x16x32_bf16 v[66:69], v[210:213], v[98:101], v[66:69]
	v_exp_f32_e32 v142, v142
	v_mfma_f32_16x16x32_bf16 v[70:73], v[210:213], v[102:105], v[70:73]
	v_exp_f32_e32 v143, v143
	s_waitcnt lgkmcnt(0)
	v_mfma_f32_16x16x32_bf16 v[74:77], v[214:217], v[98:101], v[74:77]
	v_exp_f32_e32 v144, v144
	v_mfma_f32_16x16x32_bf16 v[78:81], v[214:217], v[102:105], v[78:81]
	v_exp_f32_e32 v145, v145
	s_waitcnt vmcnt(0)
	s_barrier
; #define SBAR() __builtin_amdgcn_sched_barrier(0)
; __device__ __forceinline__ void finishSM(f32x16& p0, f32x16& p1, float& l_reg, bf16x8& pa0, bf16x8& pa1, bf16x8& pa2, bf16x8& pa3) {
;   for (int r = 0; r < 16; ++r) p1[r] = __builtin_amdgcn_exp2f(p1[r]);
;   float ps = 0; for (int r = 0; r < 16; ++r) ps += p0[r]; for (int r = 0; r < 16; ++r) ps += p1[r];
;   { auto rr = __builtin_amdgcn_permlane32_swap(__float_as_uint(ps), __float_as_uint(ps), false, false);
;     ps = __uint_as_float(rr[0]) + __uint_as_float(rr[1]); }
;   l_reg += ps;
;     ...
;   PK4(p0, 0, pa0); PK4(p0, 8, pa1); PK4(p1, 0, pa2); PK4(p1, 8, pa3);
;     ...
; }
; template <typename TQ> ...
;     ...
;   finishSM(pB0, pB1, l_reg, pa0, pa1, pa2, pa3); SBAR();
;   pv_d0(o, vb0 + (int)SHM_V, pa0, pa1, pa2, pa3);
	v_add_f32_e32 v250, v114, v250
	v_add_f32_e32 v250, v115, v250
	v_add_f32_e32 v250, v116, v250
	v_add_f32_e32 v250, v117, v250
	v_add_f32_e32 v250, v122, v250
	v_add_f32_e32 v250, v123, v250
	v_add_f32_e32 v250, v124, v250
	v_add_f32_e32 v250, v125, v250
	v_cvt_pk_bf16_f32 v114, v114, v115
	v_cvt_pk_bf16_f32 v115, v116, v117
	v_cvt_pk_bf16_f32 v116, v122, v123
	v_cvt_pk_bf16_f32 v117, v124, v125
	v_add_f32_e32 v251, v118, v251
	v_add_f32_e32 v251, v119, v251
	v_add_f32_e32 v251, v120, v251
	v_add_f32_e32 v251, v121, v251
	v_add_f32_e32 v251, v126, v251
	v_add_f32_e32 v251, v127, v251
	v_add_f32_e32 v251, v128, v251
	v_add_f32_e32 v251, v129, v251
	v_cvt_pk_bf16_f32 v118, v118, v119
	v_cvt_pk_bf16_f32 v119, v120, v121
	v_cvt_pk_bf16_f32 v120, v126, v127
	v_cvt_pk_bf16_f32 v121, v128, v129
	v_add_f32_e32 v250, v130, v250
	v_add_f32_e32 v250, v131, v250
	v_add_f32_e32 v250, v132, v250
	v_add_f32_e32 v250, v133, v250
	v_add_f32_e32 v250, v138, v250
	v_add_f32_e32 v250, v139, v250
	v_add_f32_e32 v250, v140, v250
	v_add_f32_e32 v250, v141, v250
	v_cvt_pk_bf16_f32 v130, v130, v131
	v_cvt_pk_bf16_f32 v131, v132, v133
	v_cvt_pk_bf16_f32 v132, v138, v139
	v_cvt_pk_bf16_f32 v133, v140, v141
	v_add_f32_e32 v251, v134, v251
	v_add_f32_e32 v251, v135, v251
	v_add_f32_e32 v251, v136, v251
	v_add_f32_e32 v251, v137, v251
	v_add_f32_e32 v251, v142, v251
	v_add_f32_e32 v251, v143, v251
	v_add_f32_e32 v251, v144, v251
	v_add_f32_e32 v251, v145, v251
	v_cvt_pk_bf16_f32 v134, v134, v135
	v_cvt_pk_bf16_f32 v135, v136, v137
	v_cvt_pk_bf16_f32 v136, v142, v143
	v_cvt_pk_bf16_f32 v137, v144, v145
	ds_read_b64_tr_b16 v[202:203], v238 offset:49152
	ds_read_b64_tr_b16 v[204:205], v238 offset:53248
	ds_read_b64_tr_b16 v[206:207], v239 offset:49152
	ds_read_b64_tr_b16 v[208:209], v239 offset:53248
	ds_read_b64_tr_b16 v[210:211], v240 offset:49152
	ds_read_b64_tr_b16 v[212:213], v240 offset:53248
	ds_read_b64_tr_b16 v[214:215], v241 offset:49152
	ds_read_b64_tr_b16 v[216:217], v241 offset:53248
	ds_read_b64_tr_b16 v[218:219], v242 offset:49152
	ds_read_b64_tr_b16 v[220:221], v242 offset:53248
	ds_read_b64_tr_b16 v[222:223], v243 offset:49152
	ds_read_b64_tr_b16 v[224:225], v243 offset:53248
	s_waitcnt lgkmcnt(10)
	v_mfma_f32_16x16x32_bf16 v[18:21], v[202:205], v[114:117], v[18:21]
	v_mfma_f32_16x16x32_bf16 v[22:25], v[202:205], v[118:121], v[22:25]
	ds_read_b64_tr_b16 v[202:203], v244 offset:49152
	ds_read_b64_tr_b16 v[204:205], v244 offset:53248
	s_waitcnt lgkmcnt(10)
	v_mfma_f32_16x16x32_bf16 v[26:29], v[206:209], v[114:117], v[26:29]
	v_mfma_f32_16x16x32_bf16 v[30:33], v[206:209], v[118:121], v[30:33]
	ds_read_b64_tr_b16 v[206:207], v245 offset:49152
	ds_read_b64_tr_b16 v[208:209], v245 offset:53248
	s_waitcnt lgkmcnt(10)
	v_mfma_f32_16x16x32_bf16 v[34:37], v[210:213], v[114:117], v[34:37]
	v_mfma_f32_16x16x32_bf16 v[38:41], v[210:213], v[118:121], v[38:41]
	ds_read_b64_tr_b16 v[210:211], v238 offset:57344
	ds_read_b64_tr_b16 v[212:213], v238 offset:61440
	s_waitcnt lgkmcnt(10)
	v_mfma_f32_16x16x32_bf16 v[42:45], v[214:217], v[114:117], v[42:45]
	v_mfma_f32_16x16x32_bf16 v[46:49], v[214:217], v[118:121], v[46:49]
	ds_read_b64_tr_b16 v[214:215], v239 offset:57344
	ds_read_b64_tr_b16 v[216:217], v239 offset:61440
	s_waitcnt lgkmcnt(10)
	v_mfma_f32_16x16x32_bf16 v[50:53], v[218:221], v[114:117], v[50:53]
	v_mfma_f32_16x16x32_bf16 v[54:57], v[218:221], v[118:121], v[54:57]
	ds_read_b64_tr_b16 v[218:219], v240 offset:57344
	ds_read_b64_tr_b16 v[220:221], v240 offset:61440
	s_waitcnt lgkmcnt(10)
	v_mfma_f32_16x16x32_bf16 v[58:61], v[222:225], v[114:117], v[58:61]
	v_mfma_f32_16x16x32_bf16 v[62:65], v[222:225], v[118:121], v[62:65]
	ds_read_b64_tr_b16 v[222:223], v241 offset:57344
	ds_read_b64_tr_b16 v[224:225], v241 offset:61440
	s_waitcnt lgkmcnt(10)
	v_mfma_f32_16x16x32_bf16 v[66:69], v[202:205], v[114:117], v[66:69]
	v_mfma_f32_16x16x32_bf16 v[70:73], v[202:205], v[118:121], v[70:73]
	ds_read_b64_tr_b16 v[202:203], v242 offset:57344
	ds_read_b64_tr_b16 v[204:205], v242 offset:61440
	s_waitcnt lgkmcnt(10)
	v_mfma_f32_16x16x32_bf16 v[74:77], v[206:209], v[114:117], v[74:77]
	v_mfma_f32_16x16x32_bf16 v[78:81], v[206:209], v[118:121], v[78:81]
	ds_read_b64_tr_b16 v[206:207], v243 offset:57344
	ds_read_b64_tr_b16 v[208:209], v243 offset:61440
	s_waitcnt lgkmcnt(10)
	v_mfma_f32_16x16x32_bf16 v[18:21], v[210:213], v[130:133], v[18:21]
	v_mfma_f32_16x16x32_bf16 v[22:25], v[210:213], v[134:137], v[22:25]
	ds_read_b64_tr_b16 v[210:211], v244 offset:57344
	ds_read_b64_tr_b16 v[212:213], v244 offset:61440
	s_waitcnt lgkmcnt(10)
	v_mfma_f32_16x16x32_bf16 v[26:29], v[214:217], v[130:133], v[26:29]
	v_mfma_f32_16x16x32_bf16 v[30:33], v[214:217], v[134:137], v[30:33]
	ds_read_b64_tr_b16 v[214:215], v245 offset:57344
	ds_read_b64_tr_b16 v[216:217], v245 offset:61440
	s_waitcnt lgkmcnt(10)
	v_mfma_f32_16x16x32_bf16 v[34:37], v[218:221], v[130:133], v[34:37]
	v_mfma_f32_16x16x32_bf16 v[38:41], v[218:221], v[134:137], v[38:41]
	s_waitcnt lgkmcnt(8)
	v_mfma_f32_16x16x32_bf16 v[42:45], v[222:225], v[130:133], v[42:45]
	v_mfma_f32_16x16x32_bf16 v[46:49], v[222:225], v[134:137], v[46:49]
	s_waitcnt lgkmcnt(6)
; #define SBAR() __builtin_amdgcn_sched_barrier(0)
; __device__ __forceinline__ int crow(int r, int hi) { return (r & 3) + 8 * (r >> 2) + 4 * hi; }
; template <typename TQ> ...
;     ...
;   finishSM(pB0, pB1, l_reg, pa0, pa1, pa2, pa3); SBAR();
;   pv_d0(o, vb0 + (int)SHM_V, pa0, pa1, pa2, pa3);
;   if (hi == 0) li_l[r32] = l_reg; asm volatile("s_waitcnt lgkmcnt(0)" ::: "memory");
;   float rli[16];
; #pragma unroll
;   for (int r = 0; r < 16; ++r) rli[r] = __builtin_amdgcn_rcpf(li_l[crow(r, hi)]);
;   int le = (int)(threadIdx.x & 63u); asm volatile("" : "+v"(le));
;   const int r32e = le & 31, hie = le >> 5;
;   bf16* Ow = Ob + (long)(wid * QBLK) * LDO;
; #pragma unroll
;   for (int r = 0; r < 16; ++r) { int orow = crow(r, hie);
;     for (int d0 = 0; d0 < 4; ++d0) Ow[(long)orow * LDO + d0 * 32 + r32e] = __float2bfloat16(o[d0][r] * rli[r]); }
; __global__ void __launch_bounds__(NTHR, 2) fwd_megakernel(KArgs a) {
;     ...
;         for (int i = 0; i < upb; ++i) {
;             const int unit = vcu * upb + i; if (unit >= 512) break;
;             const int grp = unit >> 7, rem = unit & 127, gq = rem >> 5, qb = rem & 31, b = grp >> 1, kvh = grp & 1, h = kvh * 4 + gq;
;             const size_t qoff = ((size_t)(b * SEQ + qb * 256)) * DM + h * 128, koff = (size_t)b * SKV * 256 + kvh * 128;
;             att::attn_dense_body<att::bf16>(Q + qoff, Kb + koff, Vb + koff, O + qoff, SKV, (char*)lds_raw, mC, a.g_q, (const float*)(ws + WS_ROPE), (const float*)(ws + WS_ROPE) + 4096, qb * 256);
;             __syncthreads();
;         }
	v_mfma_f32_16x16x32_bf16 v[50:53], v[202:205], v[130:133], v[50:53]
	v_mfma_f32_16x16x32_bf16 v[54:57], v[202:205], v[134:137], v[54:57]
	s_waitcnt lgkmcnt(4)
	v_mfma_f32_16x16x32_bf16 v[58:61], v[206:209], v[130:133], v[58:61]
	v_mfma_f32_16x16x32_bf16 v[62:65], v[206:209], v[134:137], v[62:65]
	s_waitcnt lgkmcnt(2)
	v_mfma_f32_16x16x32_bf16 v[66:69], v[210:213], v[130:133], v[66:69]
	v_mfma_f32_16x16x32_bf16 v[70:73], v[210:213], v[134:137], v[70:73]
	s_waitcnt lgkmcnt(0)
	v_mfma_f32_16x16x32_bf16 v[74:77], v[214:217], v[130:133], v[74:77]
	v_mfma_f32_16x16x32_bf16 v[78:81], v[214:217], v[134:137], v[78:81]
	s_setprio 0
	ds_swizzle_b32 v6, v250 offset:swizzle(SWAP,16)
	s_waitcnt lgkmcnt(0)
	v_add_f32_e32 v250, v250, v6
	v_mov_b32_e32 v6, v250
	s_nop 1
	v_permlane32_swap_b32_e32 v250, v6
	v_add_f32_e32 v250, v250, v6
	v_rcp_f32_e32 v250, v250
	ds_swizzle_b32 v6, v251 offset:swizzle(SWAP,16)
	s_waitcnt lgkmcnt(0)
	v_add_f32_e32 v251, v251, v6
	v_mov_b32_e32 v6, v251
	s_nop 1
	v_permlane32_swap_b32_e32 v251, v6
	v_add_f32_e32 v251, v251, v6
	v_rcp_f32_e32 v251, v251
	s_add_u32 s12, s71, s48
	s_addc_u32 s13, s72, s49
	v_add_u32_e32 v201, s52, v16
	v_lshlrev_b32_e32 v201, 11, v201
	v_lshl_or_b32 v7, v17, 3, v201
	v_add_u32_e32 v200, 0x8000, v7
	v_mul_f32_e32 v18, v18, v250
	v_mul_f32_e32 v19, v19, v250
	v_mul_f32_e32 v20, v20, v250
	v_mul_f32_e32 v21, v21, v250
	v_cvt_pk_bf16_f32 v18, v18, v19
	v_cvt_pk_bf16_f32 v19, v20, v21
	global_store_dwordx2 v7, v[18:19], s[12:13] offset:0
	v_mul_f32_e32 v22, v22, v251
	v_mul_f32_e32 v23, v23, v251
	v_mul_f32_e32 v24, v24, v251
	v_mul_f32_e32 v25, v25, v251
	v_cvt_pk_bf16_f32 v22, v22, v23
	v_cvt_pk_bf16_f32 v23, v24, v25
	global_store_dwordx2 v200, v[22:23], s[12:13] offset:0
	v_mul_f32_e32 v26, v26, v250
	v_mul_f32_e32 v27, v27, v250
	v_mul_f32_e32 v28, v28, v250
	v_mul_f32_e32 v29, v29, v250
	v_cvt_pk_bf16_f32 v26, v26, v27
	v_cvt_pk_bf16_f32 v27, v28, v29
	global_store_dwordx2 v7, v[26:27], s[12:13] offset:32
	v_mul_f32_e32 v30, v30, v251
	v_mul_f32_e32 v31, v31, v251
	v_mul_f32_e32 v32, v32, v251
	v_mul_f32_e32 v33, v33, v251
	v_cvt_pk_bf16_f32 v30, v30, v31
	v_cvt_pk_bf16_f32 v31, v32, v33
	global_store_dwordx2 v200, v[30:31], s[12:13] offset:32
	v_mul_f32_e32 v34, v34, v250
	v_mul_f32_e32 v35, v35, v250
	v_mul_f32_e32 v36, v36, v250
	v_mul_f32_e32 v37, v37, v250
	v_cvt_pk_bf16_f32 v34, v34, v35
	v_cvt_pk_bf16_f32 v35, v36, v37
	global_store_dwordx2 v7, v[34:35], s[12:13] offset:64
	v_mul_f32_e32 v38, v38, v251
	v_mul_f32_e32 v39, v39, v251
	v_mul_f32_e32 v40, v40, v251
	v_mul_f32_e32 v41, v41, v251
	v_cvt_pk_bf16_f32 v38, v38, v39
	v_cvt_pk_bf16_f32 v39, v40, v41
	global_store_dwordx2 v200, v[38:39], s[12:13] offset:64
	v_mul_f32_e32 v42, v42, v250
	v_mul_f32_e32 v43, v43, v250
	v_mul_f32_e32 v44, v44, v250
	v_mul_f32_e32 v45, v45, v250
	v_cvt_pk_bf16_f32 v42, v42, v43
	v_cvt_pk_bf16_f32 v43, v44, v45
	global_store_dwordx2 v7, v[42:43], s[12:13] offset:96
	v_mul_f32_e32 v46, v46, v251
	v_mul_f32_e32 v47, v47, v251
	v_mul_f32_e32 v48, v48, v251
	v_mul_f32_e32 v49, v49, v251
	v_cvt_pk_bf16_f32 v46, v46, v47
	v_cvt_pk_bf16_f32 v47, v48, v49
	global_store_dwordx2 v200, v[46:47], s[12:13] offset:96
	v_mul_f32_e32 v50, v50, v250
	v_mul_f32_e32 v51, v51, v250
	v_mul_f32_e32 v52, v52, v250
	v_mul_f32_e32 v53, v53, v250
	v_cvt_pk_bf16_f32 v50, v50, v51
	v_cvt_pk_bf16_f32 v51, v52, v53
	global_store_dwordx2 v7, v[50:51], s[12:13] offset:128
	v_mul_f32_e32 v54, v54, v251
	v_mul_f32_e32 v55, v55, v251
	v_mul_f32_e32 v56, v56, v251
	v_mul_f32_e32 v57, v57, v251
	v_cvt_pk_bf16_f32 v54, v54, v55
	v_cvt_pk_bf16_f32 v55, v56, v57
	global_store_dwordx2 v200, v[54:55], s[12:13] offset:128
	v_mul_f32_e32 v58, v58, v250
	v_mul_f32_e32 v59, v59, v250
	v_mul_f32_e32 v60, v60, v250
	v_mul_f32_e32 v61, v61, v250
	v_cvt_pk_bf16_f32 v58, v58, v59
	v_cvt_pk_bf16_f32 v59, v60, v61
	global_store_dwordx2 v7, v[58:59], s[12:13] offset:160
	v_mul_f32_e32 v62, v62, v251
	v_mul_f32_e32 v63, v63, v251
	v_mul_f32_e32 v64, v64, v251
	v_mul_f32_e32 v65, v65, v251
	v_cvt_pk_bf16_f32 v62, v62, v63
	v_cvt_pk_bf16_f32 v63, v64, v65
	global_store_dwordx2 v200, v[62:63], s[12:13] offset:160
	v_mul_f32_e32 v66, v66, v250
	v_mul_f32_e32 v67, v67, v250
	v_mul_f32_e32 v68, v68, v250
	v_mul_f32_e32 v69, v69, v250
	v_cvt_pk_bf16_f32 v66, v66, v67
	v_cvt_pk_bf16_f32 v67, v68, v69
	global_store_dwordx2 v7, v[66:67], s[12:13] offset:192
	v_mul_f32_e32 v70, v70, v251
	v_mul_f32_e32 v71, v71, v251
	v_mul_f32_e32 v72, v72, v251
	v_mul_f32_e32 v73, v73, v251
	v_cvt_pk_bf16_f32 v70, v70, v71
	v_cvt_pk_bf16_f32 v71, v72, v73
	global_store_dwordx2 v200, v[70:71], s[12:13] offset:192
	v_mul_f32_e32 v74, v74, v250
	v_mul_f32_e32 v75, v75, v250
	v_mul_f32_e32 v76, v76, v250
	v_mul_f32_e32 v77, v77, v250
	v_cvt_pk_bf16_f32 v74, v74, v75
	v_cvt_pk_bf16_f32 v75, v76, v77
	global_store_dwordx2 v7, v[74:75], s[12:13] offset:224
	v_mul_f32_e32 v78, v78, v251
	v_mul_f32_e32 v79, v79, v251
	v_mul_f32_e32 v80, v80, v251
	v_mul_f32_e32 v81, v81, v251
	v_cvt_pk_bf16_f32 v78, v78, v79
	v_cvt_pk_bf16_f32 v79, v80, v81
	global_store_dwordx2 v200, v[78:79], s[12:13] offset:224
	s_add_i32 s74, s74, 1
	s_add_i32 s94, s94, 1
	s_cmp_eq_u32 s74, s66
	s_cselect_b64 s[0:1], -1, 0
	s_barrier
	s_branch .LBB0_818
